# GEMM phases: first K-iteration of each tile peeled with SrcC=0 on first-touch MFMAs; accumulator re-zeroing removed (on v24)
# speedup vs baseline: 1.0046x; 1.0001x over previous
; #define PG8_STAGE(bufoff, gbase, voff) do { _Pragma("unroll") for (int _i = 0; _i < 2; ++_i) \
;         __builtin_amdgcn_global_load_lds((const unsigned*)((const char*)(gbase) + (voff)[_i]), (LAS unsigned*)(lds + (bufoff) + ldsw + _i * 8192), 16, 0, 0); } while (0)
; #define PG8_LDA(dst, b, h) do { _Pragma("unroll") for (int m = 0; m < 4; ++m) _Pragma("unroll") for (int k = 0; k < 2; ++k) dst[m][k] = *(const LAS bf16x8*)(lds + PG8_SA(b, h) + aoff + m * 2048 + k * 1024); } while (0)
; #define PG8_LDB(dst, b, h) do { _Pragma("unroll") for (int n = 0; n < 2; ++n) _Pragma("unroll") for (int k = 0; k < 2; ++k) dst[n][k] = *(const LAS bf16x8*)(lds + PG8_SB(b, h) + boff + n * 2048 + k * 1024); } while (0)
; #define PG8_WAIT_V(n) asm volatile("s_waitcnt vmcnt(" #n ")" ::: "memory")
; #define PG8_WAIT_L(n) asm volatile("s_waitcnt lgkmcnt(" #n ")" ::: "memory")
; template <class Epi>
; __device__ __forceinline__ void gemm_phase(LAS unsigned char* lds, const Gemm g, const StaticOrder& S, const Epi& E) {
;     ...
;         const bool has_next = S.next(ui + 1, nxt);
;         const char* nA = has_next ? (const char*)g.A + (size_t)nxt.pm * tsA : cA; const char* nB = has_next ? (const char*)g.Bt + (size_t)nxt.pn * tsB : cB;
;         for (int t = 0; t < nt; t += 2) {
;             const bool last = (t == nt - 2);
;             const char* a1 = cA + (size_t)(t + 1) * kstep;
;             const char* a2 = last ? nA : cA + (size_t)(t + 2) * kstep; const char* b2 = last ? nB : cB + (size_t)(t + 2) * kstep;
;             const char* a3 = a2 + kstep; const char* b3 = b2 + kstep;
;             PG8_LDB(B0, 0, 0); PG8_LDB(B1, 0, 1); PG8_SCHED; PG8_LDA(At, 0, 0); PG8_STAGE(PG8_SA(1, 1), a1 + hsA, voffA);
;             PG8_WAIT_V(8); PG8_WAIT_L(0); PG8_BAR; PG8_MMA(0, 0, At, B0); PG8_MMA(0, 1, At, B1); PG8_BAR; PG8_SCHED;
;             PG8_LDA(At, 0, 1); PG8_STAGE(PG8_SB(0, 0), b2, voffB); PG8_STAGE(PG8_SB(0, 1), b2 + hsB, voffB); PG8_STAGE(PG8_SA(0, 0), a2, voffA);
;             PG8_WAIT_V(8); PG8_WAIT_L(0); PG8_BAR; PG8_MMA(1, 0, At, B0); PG8_MMA(1, 1, At, B1); PG8_BAR; PG8_SCHED;
;     ...
;         for (int a = 0; a < 2; ++a)
; #pragma unroll
;             for (int b = 0; b < 2; ++b)
; #pragma unroll
;                 for (int m = 0; m < 4; ++m)
; #pragma unroll
;                     for (int n = 0; n < 2; ++n) acc[a][b][m][n] = (f32x4){0.f, 0.f, 0.f, 0.f};
.LBB0_222:
	s_ashr_i32 s17, s16, 31
	s_lshl_b64 s[18:19], s[16:17], 19
	s_add_u32 s18, s46, s18
	s_addc_u32 s19, s47, s19
	s_and_b64 s[20:21], s[0:1], exec
	s_cselect_b32 s17, s19, s23
	s_cselect_b32 s80, s18, s22
	s_ashr_i32 s15, s14, 31
	s_lshl_b64 s[20:21], s[14:15], 19
	s_add_u32 s20, s34, s20
	s_addc_u32 s21, s35, s21
	s_and_b64 s[28:29], s[0:1], exec
	s_cselect_b32 s15, s21, s25
	s_cselect_b32 s81, s20, s24
	s_add_u32 s22, s22, 0x40080
	s_addc_u32 s23, s23, 0
	s_add_u32 s83, s24, 0x100
	s_addc_u32 s84, s25, 0
	s_mov_b32 s85, -2
	ds_read_b128 v[146:149], v152
	ds_read_b128 v[158:161], v152 offset:1024
	ds_read_b128 v[166:169], v152 offset:2048
	ds_read_b128 v[170:173], v152 offset:3072
	ds_read_b128 v[174:177], v153
	ds_read_b128 v[178:181], v153 offset:1024
	ds_read_b128 v[182:185], v153 offset:2048
	ds_read_b128 v[186:189], v153 offset:3072
	s_add_u32 s24, s22, 0xfffc0080
	s_addc_u32 s25, s23, -1
	s_cmp_eq_u32 s85, 12
	s_cselect_b32 s29, s17, s25
	s_cselect_b32 s28, s80, s24
	s_cselect_b32 s25, s15, s84
	s_cselect_b32 s24, s81, s83
	v_lshl_add_u64 v[222:223], s[22:23], 0, v[138:139]
	s_add_i32 m0, s59, 0xc000
	ds_read_b128 v[190:193], v154
	ds_read_b128 v[194:197], v154 offset:1024
	ds_read_b128 v[198:201], v154 offset:2048
	ds_read_b128 v[202:205], v154 offset:3072
	ds_read_b128 v[206:209], v154 offset:4096
	ds_read_b128 v[210:213], v154 offset:5120
	ds_read_b128 v[214:217], v154 offset:6144
	ds_read_b128 v[218:221], v154 offset:7168
	global_load_lds_dwordx4 v[222:223], off
	v_lshl_add_u64 v[222:223], s[22:23], 0, v[140:141]
	s_add_i32 m0, s59, 0xe000
	s_nop 0
	global_load_lds_dwordx4 v[222:223], off
	s_waitcnt vmcnt(8)
	s_waitcnt lgkmcnt(0)
	s_barrier
	s_setprio 1
	s_waitcnt lgkmcnt(0)
	v_mfma_f32_16x16x32_bf16 v[124:127], v[146:149], v[190:193], 0
	v_mfma_f32_16x16x32_bf16 v[120:123], v[166:169], v[190:193], 0
	v_mfma_f32_16x16x32_bf16 v[108:111], v[146:149], v[198:201], 0
	v_mfma_f32_16x16x32_bf16 v[104:107], v[166:169], v[198:201], 0
	v_mfma_f32_16x16x32_bf16 v[92:95], v[146:149], v[206:209], 0
	v_mfma_f32_16x16x32_bf16 v[88:91], v[166:169], v[206:209], 0
	v_mfma_f32_16x16x32_bf16 v[76:79], v[146:149], v[214:217], 0
	v_mfma_f32_16x16x32_bf16 v[72:75], v[166:169], v[214:217], 0
	v_mfma_f32_16x16x32_bf16 v[124:127], v[158:161], v[194:197], v[124:127]
	v_mfma_f32_16x16x32_bf16 v[120:123], v[170:173], v[194:197], v[120:123]
	v_mfma_f32_16x16x32_bf16 v[108:111], v[158:161], v[202:205], v[108:111]
	v_mfma_f32_16x16x32_bf16 v[104:107], v[170:173], v[202:205], v[104:107]
	v_mfma_f32_16x16x32_bf16 v[92:95], v[158:161], v[210:213], v[92:95]
	v_mfma_f32_16x16x32_bf16 v[88:91], v[170:173], v[210:213], v[88:91]
	v_mfma_f32_16x16x32_bf16 v[76:79], v[158:161], v[218:221], v[76:79]
	v_mfma_f32_16x16x32_bf16 v[72:75], v[170:173], v[218:221], v[72:75]
	s_setprio 0
	s_setprio 1
	v_mfma_f32_16x16x32_bf16 v[116:119], v[174:177], v[190:193], 0
	v_mfma_f32_16x16x32_bf16 v[112:115], v[182:185], v[190:193], 0
	v_mfma_f32_16x16x32_bf16 v[100:103], v[174:177], v[198:201], 0
	v_mfma_f32_16x16x32_bf16 v[96:99], v[182:185], v[198:201], 0
	v_mfma_f32_16x16x32_bf16 v[84:87], v[174:177], v[206:209], 0
	v_mfma_f32_16x16x32_bf16 v[80:83], v[182:185], v[206:209], 0
	v_mfma_f32_16x16x32_bf16 v[68:71], v[174:177], v[214:217], 0
	v_mfma_f32_16x16x32_bf16 v[64:67], v[182:185], v[214:217], 0
	v_mfma_f32_16x16x32_bf16 v[116:119], v[178:181], v[194:197], v[116:119]
	v_mfma_f32_16x16x32_bf16 v[112:115], v[186:189], v[194:197], v[112:115]
	v_mfma_f32_16x16x32_bf16 v[100:103], v[178:181], v[202:205], v[100:103]
	v_mfma_f32_16x16x32_bf16 v[96:99], v[186:189], v[202:205], v[96:99]
	v_mfma_f32_16x16x32_bf16 v[84:87], v[178:181], v[210:213], v[84:87]
	v_mfma_f32_16x16x32_bf16 v[80:83], v[186:189], v[210:213], v[80:83]
	v_mfma_f32_16x16x32_bf16 v[68:71], v[178:181], v[218:221], v[68:71]
	v_mfma_f32_16x16x32_bf16 v[64:67], v[186:189], v[218:221], v[64:67]
	s_setprio 0
	s_barrier
	s_add_i32 s33, s76, s56
	v_lshl_add_u64 v[222:223], s[24:25], 0, v[134:135]
	s_mov_b32 m0, s33
	ds_read_b128 v[190:193], v154 offset:16384
	ds_read_b128 v[194:197], v154 offset:17408
	ds_read_b128 v[198:201], v154 offset:18432
	ds_read_b128 v[202:205], v154 offset:19456
	ds_read_b128 v[206:209], v154 offset:20480
	ds_read_b128 v[210:213], v154 offset:21504
	ds_read_b128 v[214:217], v154 offset:22528
	ds_read_b128 v[218:221], v154 offset:23552
	global_load_lds_dwordx4 v[222:223], off
	s_add_i32 m0, s33, 0x2000
	s_add_u32 s86, s24, 0x40000
	v_lshl_add_u64 v[224:225], s[24:25], 0, v[130:131]
	s_addc_u32 s87, s25, 0
	s_add_i32 s33, s77, s56
	global_load_lds_dwordx4 v[224:225], off
	v_lshl_add_u64 v[226:227], s[86:87], 0, v[134:135]
	s_mov_b32 m0, s33
	v_lshl_add_u64 v[228:229], s[28:29], 0, v[132:133]
	global_load_lds_dwordx4 v[226:227], off
	v_lshl_add_u64 v[226:227], s[86:87], 0, v[130:131]
	s_add_i32 m0, s33, 0x2000
	s_nop 0
	global_load_lds_dwordx4 v[226:227], off
	v_lshl_add_u64 v[226:227], s[28:29], 0, v[136:137]
	s_mov_b32 m0, s59
	s_nop 0
	global_load_lds_dwordx4 v[226:227], off
	s_mov_b32 m0, s60
	s_nop 0
	global_load_lds_dwordx4 v[228:229], off
	s_waitcnt vmcnt(8)
	s_waitcnt lgkmcnt(0)
	s_barrier
; #define PG8_STAGE(bufoff, gbase, voff) do { _Pragma("unroll") for (int _i = 0; _i < 2; ++_i) \
;         __builtin_amdgcn_global_load_lds((const unsigned*)((const char*)(gbase) + (voff)[_i]), (LAS unsigned*)(lds + (bufoff) + ldsw + _i * 8192), 16, 0, 0); } while (0)
; #define PG8_LDA(dst, b, h) do { _Pragma("unroll") for (int m = 0; m < 4; ++m) _Pragma("unroll") for (int k = 0; k < 2; ++k) dst[m][k] = *(const LAS bf16x8*)(lds + PG8_SA(b, h) + aoff + m * 2048 + k * 1024); } while (0)
; #define PG8_LDB(dst, b, h) do { _Pragma("unroll") for (int n = 0; n < 2; ++n) _Pragma("unroll") for (int k = 0; k < 2; ++k) dst[n][k] = *(const LAS bf16x8*)(lds + PG8_SB(b, h) + boff + n * 2048 + k * 1024); } while (0)
; #define PG8_MMA(ai, bj, At, Bt) do { __builtin_amdgcn_s_setprio(1); _Pragma("unroll") for (int m = 0; m < 4; ++m) _Pragma("unroll") for (int n = 0; n < 2; ++n) _Pragma("unroll") for (int k = 0; k < 2; ++k) \
;         acc[ai][bj][m][n] = __builtin_amdgcn_mfma_f32_16x16x32_bf16(Bt[n][k], At[m][k], acc[ai][bj][m][n], 0, 0, 0); __builtin_amdgcn_s_setprio(0); } while (0)
; #define PG8_WAIT_V(n) asm volatile("s_waitcnt vmcnt(" #n ")" ::: "memory")
; #define PG8_WAIT_L(n) asm volatile("s_waitcnt lgkmcnt(" #n ")" ::: "memory")
; #define PG8_BAR __builtin_amdgcn_s_barrier()
; #define PG8_SCHED __builtin_amdgcn_sched_barrier(0)
; template <class Epi>
; __device__ __forceinline__ void gemm_phase(LAS unsigned char* lds, const Gemm g, const StaticOrder& S, const Epi& E) {
;     ...
;             PG8_WAIT_V(8); PG8_WAIT_L(0); PG8_BAR; PG8_MMA(1, 0, At, B0); PG8_MMA(1, 1, At, B1); PG8_BAR; PG8_SCHED;
;             PG8_LDB(B0, 1, 0); PG8_LDB(B1, 1, 1); PG8_SCHED; PG8_LDA(At, 1, 0); PG8_STAGE(PG8_SA(0, 1), a2 + hsA, voffA);
;             PG8_WAIT_V(8); PG8_WAIT_L(0); PG8_BAR; PG8_MMA(0, 0, At, B0); PG8_MMA(0, 1, At, B1); PG8_BAR; PG8_SCHED;
	s_setprio 1
	s_waitcnt lgkmcnt(0)
	v_mfma_f32_16x16x32_bf16 v[60:63], v[146:149], v[190:193], 0
	v_mfma_f32_16x16x32_bf16 v[56:59], v[166:169], v[190:193], 0
	v_mfma_f32_16x16x32_bf16 v[44:47], v[146:149], v[198:201], 0
	v_mfma_f32_16x16x32_bf16 v[40:43], v[166:169], v[198:201], 0
	v_mfma_f32_16x16x32_bf16 v[28:31], v[146:149], v[206:209], 0
	v_mfma_f32_16x16x32_bf16 v[24:27], v[166:169], v[206:209], 0
	v_mfma_f32_16x16x32_bf16 v[12:15], v[146:149], v[214:217], 0
	v_mfma_f32_16x16x32_bf16 v[8:11], v[166:169], v[214:217], 0
	v_mfma_f32_16x16x32_bf16 v[60:63], v[158:161], v[194:197], v[60:63]
	v_mfma_f32_16x16x32_bf16 v[56:59], v[170:173], v[194:197], v[56:59]
	v_mfma_f32_16x16x32_bf16 v[44:47], v[158:161], v[202:205], v[44:47]
	v_mfma_f32_16x16x32_bf16 v[40:43], v[170:173], v[202:205], v[40:43]
	v_mfma_f32_16x16x32_bf16 v[28:31], v[158:161], v[210:213], v[28:31]
	v_mfma_f32_16x16x32_bf16 v[24:27], v[170:173], v[210:213], v[24:27]
	v_mfma_f32_16x16x32_bf16 v[12:15], v[158:161], v[218:221], v[12:15]
	v_mfma_f32_16x16x32_bf16 v[8:11], v[170:173], v[218:221], v[8:11]
	s_setprio 0
	s_setprio 1
	v_mfma_f32_16x16x32_bf16 v[52:55], v[174:177], v[190:193], 0
	v_mfma_f32_16x16x32_bf16 v[48:51], v[182:185], v[190:193], 0
	v_mfma_f32_16x16x32_bf16 v[36:39], v[174:177], v[198:201], 0
	v_mfma_f32_16x16x32_bf16 v[32:35], v[182:185], v[198:201], 0
	v_mfma_f32_16x16x32_bf16 v[20:23], v[174:177], v[206:209], 0
	v_mfma_f32_16x16x32_bf16 v[16:19], v[182:185], v[206:209], 0
	v_mfma_f32_16x16x32_bf16 v[4:7], v[174:177], v[214:217], 0
	v_mfma_f32_16x16x32_bf16 v[0:3], v[182:185], v[214:217], 0
	v_mfma_f32_16x16x32_bf16 v[52:55], v[178:181], v[194:197], v[52:55]
	v_mfma_f32_16x16x32_bf16 v[48:51], v[186:189], v[194:197], v[48:51]
	v_mfma_f32_16x16x32_bf16 v[36:39], v[178:181], v[202:205], v[36:39]
	v_mfma_f32_16x16x32_bf16 v[32:35], v[186:189], v[202:205], v[32:35]
	v_mfma_f32_16x16x32_bf16 v[20:23], v[178:181], v[210:213], v[20:23]
	v_mfma_f32_16x16x32_bf16 v[16:19], v[186:189], v[210:213], v[16:19]
	v_mfma_f32_16x16x32_bf16 v[4:7], v[178:181], v[218:221], v[4:7]
	v_mfma_f32_16x16x32_bf16 v[0:3], v[186:189], v[218:221], v[0:3]
	s_setprio 0
	s_barrier
	s_add_i32 s33, 0, 0x18000
	v_add_u32_e32 v165, s33, v150
	s_add_i32 s86, 0, 0x1c000
	ds_read_b128 v[146:149], v165
	ds_read_b128 v[158:161], v165 offset:1024
	ds_read_b128 v[166:169], v165 offset:2048
	ds_read_b128 v[170:173], v165 offset:3072
	v_add_u32_e32 v165, s86, v150
	ds_read_b128 v[174:177], v165
	ds_read_b128 v[178:181], v165 offset:1024
	ds_read_b128 v[182:185], v165 offset:2048
	ds_read_b128 v[186:189], v165 offset:3072
	s_add_u32 s28, s28, 0x40000
	s_addc_u32 s29, s29, 0
	s_mov_b32 m0, s61
	v_lshl_add_u64 v[230:231], s[28:29], 0, v[136:137]
	ds_read_b128 v[190:193], v154 offset:32768
	ds_read_b128 v[194:197], v154 offset:33792
	ds_read_b128 v[198:201], v154 offset:34816
	ds_read_b128 v[202:205], v154 offset:35840
	ds_read_b128 v[206:209], v154 offset:36864
	ds_read_b128 v[210:213], v154 offset:37888
	ds_read_b128 v[214:217], v154 offset:38912
	ds_read_b128 v[218:221], v154 offset:39936
	global_load_lds_dwordx4 v[230:231], off
	v_lshl_add_u64 v[230:231], s[28:29], 0, v[132:133]
	s_mov_b32 m0, s62
	s_nop 0
	global_load_lds_dwordx4 v[230:231], off
	s_waitcnt vmcnt(8)
	s_waitcnt lgkmcnt(0)
	s_barrier
	s_setprio 1
	s_waitcnt lgkmcnt(0)
	v_mfma_f32_16x16x32_bf16 v[124:127], v[146:149], v[190:193], v[124:127]
	v_mfma_f32_16x16x32_bf16 v[120:123], v[166:169], v[190:193], v[120:123]
	v_mfma_f32_16x16x32_bf16 v[108:111], v[146:149], v[198:201], v[108:111]
	v_mfma_f32_16x16x32_bf16 v[104:107], v[166:169], v[198:201], v[104:107]
	v_mfma_f32_16x16x32_bf16 v[92:95], v[146:149], v[206:209], v[92:95]
	v_mfma_f32_16x16x32_bf16 v[88:91], v[166:169], v[206:209], v[88:91]
	v_mfma_f32_16x16x32_bf16 v[76:79], v[146:149], v[214:217], v[76:79]
	v_mfma_f32_16x16x32_bf16 v[72:75], v[166:169], v[214:217], v[72:75]
	v_mfma_f32_16x16x32_bf16 v[124:127], v[158:161], v[194:197], v[124:127]
	v_mfma_f32_16x16x32_bf16 v[120:123], v[170:173], v[194:197], v[120:123]
	v_mfma_f32_16x16x32_bf16 v[108:111], v[158:161], v[202:205], v[108:111]
	v_mfma_f32_16x16x32_bf16 v[104:107], v[170:173], v[202:205], v[104:107]
	v_mfma_f32_16x16x32_bf16 v[92:95], v[158:161], v[210:213], v[92:95]
	v_mfma_f32_16x16x32_bf16 v[88:91], v[170:173], v[210:213], v[88:91]
	v_mfma_f32_16x16x32_bf16 v[76:79], v[158:161], v[218:221], v[76:79]
	v_mfma_f32_16x16x32_bf16 v[72:75], v[170:173], v[218:221], v[72:75]
	s_setprio 0
	s_setprio 1
	v_mfma_f32_16x16x32_bf16 v[116:119], v[174:177], v[190:193], v[116:119]
	v_mfma_f32_16x16x32_bf16 v[112:115], v[182:185], v[190:193], v[112:115]
	v_mfma_f32_16x16x32_bf16 v[100:103], v[174:177], v[198:201], v[100:103]
	v_mfma_f32_16x16x32_bf16 v[96:99], v[182:185], v[198:201], v[96:99]
	v_mfma_f32_16x16x32_bf16 v[84:87], v[174:177], v[206:209], v[84:87]
	v_mfma_f32_16x16x32_bf16 v[80:83], v[182:185], v[206:209], v[80:83]
	v_mfma_f32_16x16x32_bf16 v[68:71], v[174:177], v[214:217], v[68:71]
	v_mfma_f32_16x16x32_bf16 v[64:67], v[182:185], v[214:217], v[64:67]
	v_mfma_f32_16x16x32_bf16 v[116:119], v[178:181], v[194:197], v[116:119]
	v_mfma_f32_16x16x32_bf16 v[112:115], v[186:189], v[194:197], v[112:115]
	v_mfma_f32_16x16x32_bf16 v[100:103], v[178:181], v[202:205], v[100:103]
	v_mfma_f32_16x16x32_bf16 v[96:99], v[186:189], v[202:205], v[96:99]
	v_mfma_f32_16x16x32_bf16 v[84:87], v[178:181], v[210:213], v[84:87]
	v_mfma_f32_16x16x32_bf16 v[80:83], v[186:189], v[210:213], v[80:83]
	v_mfma_f32_16x16x32_bf16 v[68:71], v[178:181], v[218:221], v[68:71]
	v_mfma_f32_16x16x32_bf16 v[64:67], v[186:189], v[218:221], v[64:67]
	s_setprio 0
	s_barrier
; #define PG8_STAGE(bufoff, gbase, voff) do { _Pragma("unroll") for (int _i = 0; _i < 2; ++_i) \
;         __builtin_amdgcn_global_load_lds((const unsigned*)((const char*)(gbase) + (voff)[_i]), (LAS unsigned*)(lds + (bufoff) + ldsw + _i * 8192), 16, 0, 0); } while (0)
; #define PG8_LDA(dst, b, h) do { _Pragma("unroll") for (int m = 0; m < 4; ++m) _Pragma("unroll") for (int k = 0; k < 2; ++k) dst[m][k] = *(const LAS bf16x8*)(lds + PG8_SA(b, h) + aoff + m * 2048 + k * 1024); } while (0)
; #define PG8_MMA(ai, bj, At, Bt) do { __builtin_amdgcn_s_setprio(1); _Pragma("unroll") for (int m = 0; m < 4; ++m) _Pragma("unroll") for (int n = 0; n < 2; ++n) _Pragma("unroll") for (int k = 0; k < 2; ++k) \
;         acc[ai][bj][m][n] = __builtin_amdgcn_mfma_f32_16x16x32_bf16(Bt[n][k], At[m][k], acc[ai][bj][m][n], 0, 0, 0); __builtin_amdgcn_s_setprio(0); } while (0)
; #define PG8_WAIT_V(n) asm volatile("s_waitcnt vmcnt(" #n ")" ::: "memory")
; #define PG8_WAIT_L(n) asm volatile("s_waitcnt lgkmcnt(" #n ")" ::: "memory")
; #define PG8_BAR __builtin_amdgcn_s_barrier()
; #define PG8_SCHED __builtin_amdgcn_sched_barrier(0)
; template <class Epi>
; __device__ __forceinline__ void gemm_phase(LAS unsigned char* lds, const Gemm g, const StaticOrder& S, const Epi& E) {
;     ...
;             PG8_LDA(At, 1, 1); PG8_STAGE(PG8_SB(1, 0), b3, voffB); PG8_STAGE(PG8_SB(1, 1), b3 + hsB, voffB); PG8_STAGE(PG8_SA(1, 0), a3, voffA);
;             PG8_WAIT_V(8); PG8_WAIT_L(0); PG8_BAR; PG8_MMA(1, 0, At, B0); PG8_MMA(1, 1, At, B1); PG8_BAR; PG8_SCHED;
;         }
	s_add_i32 s28, s33, s56
	v_lshl_add_u64 v[222:223], v[222:223], 0, s[8:9]
	s_mov_b32 m0, s28
	ds_read_b128 v[190:193], v154 offset:49152
	ds_read_b128 v[194:197], v154 offset:50176
	ds_read_b128 v[198:201], v154 offset:51200
	ds_read_b128 v[202:205], v154 offset:52224
	ds_read_b128 v[206:209], v154 offset:53248
	ds_read_b128 v[210:213], v154 offset:54272
	ds_read_b128 v[214:217], v154 offset:55296
	ds_read_b128 v[218:221], v154 offset:56320
	global_load_lds_dwordx4 v[222:223], off
	s_add_i32 m0, s28, 0x2000
	s_add_u32 s24, s24, 0x40080
	v_lshl_add_u64 v[222:223], v[224:225], 0, s[8:9]
	s_addc_u32 s25, s25, 0
	s_add_i32 s28, s86, s56
	global_load_lds_dwordx4 v[222:223], off
	v_lshl_add_u64 v[222:223], s[24:25], 0, v[134:135]
	s_mov_b32 m0, s28
	s_nop 0
	global_load_lds_dwordx4 v[222:223], off
	v_lshl_add_u64 v[222:223], s[24:25], 0, v[130:131]
	s_add_i32 m0, s28, 0x2000
	s_nop 0
	global_load_lds_dwordx4 v[222:223], off
	v_lshl_add_u64 v[222:223], v[226:227], 0, s[8:9]
	s_mov_b32 m0, s64
	s_nop 0
	global_load_lds_dwordx4 v[222:223], off
	v_lshl_add_u64 v[222:223], v[228:229], 0, s[8:9]
	s_mov_b32 m0, s65
	s_nop 0
	global_load_lds_dwordx4 v[222:223], off
	s_waitcnt vmcnt(8)
	s_waitcnt lgkmcnt(0)
	s_barrier
	s_setprio 1
	s_waitcnt lgkmcnt(0)
	v_mfma_f32_16x16x32_bf16 v[60:63], v[146:149], v[190:193], v[60:63]
	v_mfma_f32_16x16x32_bf16 v[56:59], v[166:169], v[190:193], v[56:59]
	v_mfma_f32_16x16x32_bf16 v[44:47], v[146:149], v[198:201], v[44:47]
	v_mfma_f32_16x16x32_bf16 v[40:43], v[166:169], v[198:201], v[40:43]
	v_mfma_f32_16x16x32_bf16 v[28:31], v[146:149], v[206:209], v[28:31]
	v_mfma_f32_16x16x32_bf16 v[24:27], v[166:169], v[206:209], v[24:27]
	v_mfma_f32_16x16x32_bf16 v[12:15], v[146:149], v[214:217], v[12:15]
	v_mfma_f32_16x16x32_bf16 v[8:11], v[166:169], v[214:217], v[8:11]
	v_mfma_f32_16x16x32_bf16 v[60:63], v[158:161], v[194:197], v[60:63]
	v_mfma_f32_16x16x32_bf16 v[56:59], v[170:173], v[194:197], v[56:59]
	v_mfma_f32_16x16x32_bf16 v[44:47], v[158:161], v[202:205], v[44:47]
	v_mfma_f32_16x16x32_bf16 v[40:43], v[170:173], v[202:205], v[40:43]
	v_mfma_f32_16x16x32_bf16 v[28:31], v[158:161], v[210:213], v[28:31]
	v_mfma_f32_16x16x32_bf16 v[24:27], v[170:173], v[210:213], v[24:27]
	v_mfma_f32_16x16x32_bf16 v[12:15], v[158:161], v[218:221], v[12:15]
	v_mfma_f32_16x16x32_bf16 v[8:11], v[170:173], v[218:221], v[8:11]
	s_setprio 0
	s_setprio 1
	v_mfma_f32_16x16x32_bf16 v[52:55], v[174:177], v[190:193], v[52:55]
	v_mfma_f32_16x16x32_bf16 v[48:51], v[182:185], v[190:193], v[48:51]
	v_mfma_f32_16x16x32_bf16 v[36:39], v[174:177], v[198:201], v[36:39]
	v_mfma_f32_16x16x32_bf16 v[32:35], v[182:185], v[198:201], v[32:35]
	v_mfma_f32_16x16x32_bf16 v[20:23], v[174:177], v[206:209], v[20:23]
	v_mfma_f32_16x16x32_bf16 v[16:19], v[182:185], v[206:209], v[16:19]
	v_mfma_f32_16x16x32_bf16 v[4:7], v[174:177], v[214:217], v[4:7]
	v_mfma_f32_16x16x32_bf16 v[0:3], v[182:185], v[214:217], v[0:3]
	v_mfma_f32_16x16x32_bf16 v[52:55], v[178:181], v[194:197], v[52:55]
	v_mfma_f32_16x16x32_bf16 v[48:51], v[186:189], v[194:197], v[48:51]
	v_mfma_f32_16x16x32_bf16 v[36:39], v[178:181], v[202:205], v[36:39]
	v_mfma_f32_16x16x32_bf16 v[32:35], v[186:189], v[202:205], v[32:35]
	v_mfma_f32_16x16x32_bf16 v[20:23], v[178:181], v[210:213], v[20:23]
	v_mfma_f32_16x16x32_bf16 v[16:19], v[186:189], v[210:213], v[16:19]
	v_mfma_f32_16x16x32_bf16 v[4:7], v[178:181], v[218:221], v[4:7]
	v_mfma_f32_16x16x32_bf16 v[0:3], v[186:189], v[218:221], v[0:3]
	s_setprio 0
	s_barrier
	s_add_i32 s85, s85, 2
	s_add_u32 s22, s22, 0x100
	s_addc_u32 s23, s23, 0
	s_add_u32 s83, s83, 0x100
	s_addc_u32 s84, s84, 0
	s_cmp_gt_u32 s85, 13
	s_cbranch_scc0 .LBB0_223
	s_branch .Lpeel_exit0

; #define PG8_BAR __builtin_amdgcn_s_barrier()
; template <class Epi>
; __device__ __forceinline__ void gemm_phase(LAS unsigned char* lds, const Gemm g, const StaticOrder& S, const Epi& E) {
;     ...
;         if (wr == 0) PG8_BAR;
;         E(acc, cur, wr, wc, fr, fq);
;         if (!has_next) break;
.Lpeel_exit0:
	s_and_b64 vcc, exec, s[10:11]
	s_cbranch_vccz .LBB0_226
	s_barrier

; #define PG8_STAGE(bufoff, gbase, voff) do { _Pragma("unroll") for (int _i = 0; _i < 2; ++_i) \
;         __builtin_amdgcn_global_load_lds((const unsigned*)((const char*)(gbase) + (voff)[_i]), (LAS unsigned*)(lds + (bufoff) + ldsw + _i * 8192), 16, 0, 0); } while (0)
; #define PG8_LDA(dst, b, h) do { _Pragma("unroll") for (int m = 0; m < 4; ++m) _Pragma("unroll") for (int k = 0; k < 2; ++k) dst[m][k] = *(const LAS bf16x8*)(lds + PG8_SA(b, h) + aoff + m * 2048 + k * 1024); } while (0)
; #define PG8_LDB(dst, b, h) do { _Pragma("unroll") for (int n = 0; n < 2; ++n) _Pragma("unroll") for (int k = 0; k < 2; ++k) dst[n][k] = *(const LAS bf16x8*)(lds + PG8_SB(b, h) + boff + n * 2048 + k * 1024); } while (0)
; #define PG8_WAIT_V(n) asm volatile("s_waitcnt vmcnt(" #n ")" ::: "memory")
; #define PG8_WAIT_L(n) asm volatile("s_waitcnt lgkmcnt(" #n ")" ::: "memory")
; template <class Epi>
; __device__ __forceinline__ void gemm_phase(LAS unsigned char* lds, const Gemm g, const StaticOrder& S, const Epi& E) {
;     ...
;         const bool has_next = S.next(ui + 1, nxt);
;         const char* nA = has_next ? (const char*)g.A + (size_t)nxt.pm * tsA : cA; const char* nB = has_next ? (const char*)g.Bt + (size_t)nxt.pn * tsB : cB;
;         for (int t = 0; t < nt; t += 2) {
;             const bool last = (t == nt - 2);
;             const char* a1 = cA + (size_t)(t + 1) * kstep;
;             const char* a2 = last ? nA : cA + (size_t)(t + 2) * kstep; const char* b2 = last ? nB : cB + (size_t)(t + 2) * kstep;
;             const char* a3 = a2 + kstep; const char* b3 = b2 + kstep;
;             PG8_LDB(B0, 0, 0); PG8_LDB(B1, 0, 1); PG8_SCHED; PG8_LDA(At, 0, 0); PG8_STAGE(PG8_SA(1, 1), a1 + hsA, voffA);
;             PG8_WAIT_V(8); PG8_WAIT_L(0); PG8_BAR; PG8_MMA(0, 0, At, B0); PG8_MMA(0, 1, At, B1); PG8_BAR; PG8_SCHED;
;             PG8_LDA(At, 0, 1); PG8_STAGE(PG8_SB(0, 0), b2, voffB); PG8_STAGE(PG8_SB(0, 1), b2 + hsB, voffB); PG8_STAGE(PG8_SA(0, 0), a2, voffA);
;             PG8_WAIT_V(8); PG8_WAIT_L(0); PG8_BAR; PG8_MMA(1, 0, At, B0); PG8_MMA(1, 1, At, B1); PG8_BAR; PG8_SCHED;
;     ...
;         for (int a = 0; a < 2; ++a)
; #pragma unroll
;             for (int b = 0; b < 2; ++b)
; #pragma unroll
;                 for (int m = 0; m < 4; ++m)
; #pragma unroll
;                     for (int n = 0; n < 2; ++n) acc[a][b][m][n] = (f32x4){0.f, 0.f, 0.f, 0.f};
.LBB0_304:
	s_add_u32 s86, s28, 0x100
	s_addc_u32 s87, s29, 0
	s_mov_b32 s88, -2
	s_waitcnt lgkmcnt(0)
	ds_read_b128 v[146:149], v167
	ds_read_b128 v[150:153], v167 offset:1024
	ds_read_b128 v[158:161], v167 offset:2048
	ds_read_b128 v[172:175], v167 offset:3072
	ds_read_b128 v[176:179], v168
	ds_read_b128 v[180:183], v168 offset:1024
	ds_read_b128 v[184:187], v168 offset:2048
	ds_read_b128 v[188:191], v168 offset:3072
	s_add_u32 s8, s24, 0x100
	s_addc_u32 s9, s25, 0
	s_cmp_eq_u32 s88, 40
	s_cselect_b32 s57, s21, s9
	s_cselect_b32 s56, s20, s8
	s_cselect_b32 s29, s23, s87
	s_cselect_b32 s28, s22, s86
	v_lshl_add_u64 v[154:155], s[24:25], 0, v[138:139]
	s_add_i32 m0, s61, 0xc000
	ds_read_b128 v[192:195], v169
	ds_read_b128 v[196:199], v169 offset:1024
	ds_read_b128 v[200:203], v169 offset:2048
	ds_read_b128 v[204:207], v169 offset:3072
	ds_read_b128 v[208:211], v169 offset:4096
	ds_read_b128 v[212:215], v169 offset:5120
	ds_read_b128 v[216:219], v169 offset:6144
	ds_read_b128 v[220:223], v169 offset:7168
	global_load_lds_dwordx4 v[154:155], off
	v_lshl_add_u64 v[154:155], s[24:25], 0, v[140:141]
	s_add_i32 m0, s61, 0xe000
	s_nop 0
	global_load_lds_dwordx4 v[154:155], off
	s_waitcnt vmcnt(8)
	s_waitcnt lgkmcnt(0)
	s_barrier
	s_setprio 1
	s_waitcnt lgkmcnt(0)
	v_mfma_f32_16x16x32_bf16 v[124:127], v[146:149], v[192:195], 0
	v_mfma_f32_16x16x32_bf16 v[120:123], v[158:161], v[192:195], 0
	v_mfma_f32_16x16x32_bf16 v[108:111], v[146:149], v[200:203], 0
	v_mfma_f32_16x16x32_bf16 v[104:107], v[158:161], v[200:203], 0
	v_mfma_f32_16x16x32_bf16 v[92:95], v[146:149], v[208:211], 0
	v_mfma_f32_16x16x32_bf16 v[88:91], v[158:161], v[208:211], 0
	v_mfma_f32_16x16x32_bf16 v[76:79], v[146:149], v[216:219], 0
	v_mfma_f32_16x16x32_bf16 v[72:75], v[158:161], v[216:219], 0
	v_mfma_f32_16x16x32_bf16 v[124:127], v[150:153], v[196:199], v[124:127]
	v_mfma_f32_16x16x32_bf16 v[120:123], v[172:175], v[196:199], v[120:123]
	v_mfma_f32_16x16x32_bf16 v[108:111], v[150:153], v[204:207], v[108:111]
	v_mfma_f32_16x16x32_bf16 v[104:107], v[172:175], v[204:207], v[104:107]
	v_mfma_f32_16x16x32_bf16 v[92:95], v[150:153], v[212:215], v[92:95]
	v_mfma_f32_16x16x32_bf16 v[88:91], v[172:175], v[212:215], v[88:91]
	v_mfma_f32_16x16x32_bf16 v[76:79], v[150:153], v[220:223], v[76:79]
	v_mfma_f32_16x16x32_bf16 v[72:75], v[172:175], v[220:223], v[72:75]
	s_setprio 0
	s_setprio 1
	v_mfma_f32_16x16x32_bf16 v[116:119], v[176:179], v[192:195], 0
	v_mfma_f32_16x16x32_bf16 v[112:115], v[184:187], v[192:195], 0
	v_mfma_f32_16x16x32_bf16 v[100:103], v[176:179], v[200:203], 0
	v_mfma_f32_16x16x32_bf16 v[96:99], v[184:187], v[200:203], 0
	v_mfma_f32_16x16x32_bf16 v[84:87], v[176:179], v[208:211], 0
	v_mfma_f32_16x16x32_bf16 v[80:83], v[184:187], v[208:211], 0
	v_mfma_f32_16x16x32_bf16 v[68:71], v[176:179], v[216:219], 0
	v_mfma_f32_16x16x32_bf16 v[64:67], v[184:187], v[216:219], 0
	v_mfma_f32_16x16x32_bf16 v[116:119], v[180:183], v[196:199], v[116:119]
	v_mfma_f32_16x16x32_bf16 v[112:115], v[188:191], v[196:199], v[112:115]
	v_mfma_f32_16x16x32_bf16 v[100:103], v[180:183], v[204:207], v[100:103]
	v_mfma_f32_16x16x32_bf16 v[96:99], v[188:191], v[204:207], v[96:99]
	v_mfma_f32_16x16x32_bf16 v[84:87], v[180:183], v[212:215], v[84:87]
	v_mfma_f32_16x16x32_bf16 v[80:83], v[188:191], v[212:215], v[80:83]
	v_mfma_f32_16x16x32_bf16 v[68:71], v[180:183], v[220:223], v[68:71]
	v_mfma_f32_16x16x32_bf16 v[64:67], v[188:191], v[220:223], v[64:67]
	s_setprio 0
	s_barrier
	s_add_i32 s24, s79, s60
	v_lshl_add_u64 v[154:155], s[28:29], 0, v[132:133]
	s_mov_b32 m0, s24
	ds_read_b128 v[192:195], v169 offset:16384
	ds_read_b128 v[196:199], v169 offset:17408
	ds_read_b128 v[200:203], v169 offset:18432
	ds_read_b128 v[204:207], v169 offset:19456
	ds_read_b128 v[208:211], v169 offset:20480
	ds_read_b128 v[212:215], v169 offset:21504
	ds_read_b128 v[216:219], v169 offset:22528
	ds_read_b128 v[220:223], v169 offset:23552
	global_load_lds_dwordx4 v[154:155], off
	s_add_i32 m0, s24, 0x2000
	s_add_u32 s24, s28, 0xb0000
	v_lshl_add_u64 v[224:225], s[28:29], 0, v[136:137]
	s_addc_u32 s25, s29, 0
	s_add_i32 s33, s80, s60
	global_load_lds_dwordx4 v[224:225], off
	v_lshl_add_u64 v[226:227], s[24:25], 0, v[132:133]
	s_mov_b32 m0, s33
	v_lshl_add_u64 v[228:229], s[56:57], 0, v[134:135]
	global_load_lds_dwordx4 v[226:227], off
	v_lshl_add_u64 v[226:227], s[24:25], 0, v[136:137]
	s_add_i32 m0, s33, 0x2000
	s_nop 0
	global_load_lds_dwordx4 v[226:227], off
	v_lshl_add_u64 v[226:227], s[56:57], 0, v[130:131]
	s_mov_b32 m0, s61
	s_nop 0
	global_load_lds_dwordx4 v[226:227], off
	s_mov_b32 m0, s62
	s_nop 0
	global_load_lds_dwordx4 v[228:229], off
	s_waitcnt vmcnt(8)
	s_waitcnt lgkmcnt(0)
	s_barrier
; #define PG8_STAGE(bufoff, gbase, voff) do { _Pragma("unroll") for (int _i = 0; _i < 2; ++_i) \
;         __builtin_amdgcn_global_load_lds((const unsigned*)((const char*)(gbase) + (voff)[_i]), (LAS unsigned*)(lds + (bufoff) + ldsw + _i * 8192), 16, 0, 0); } while (0)
; #define PG8_LDA(dst, b, h) do { _Pragma("unroll") for (int m = 0; m < 4; ++m) _Pragma("unroll") for (int k = 0; k < 2; ++k) dst[m][k] = *(const LAS bf16x8*)(lds + PG8_SA(b, h) + aoff + m * 2048 + k * 1024); } while (0)
; #define PG8_LDB(dst, b, h) do { _Pragma("unroll") for (int n = 0; n < 2; ++n) _Pragma("unroll") for (int k = 0; k < 2; ++k) dst[n][k] = *(const LAS bf16x8*)(lds + PG8_SB(b, h) + boff + n * 2048 + k * 1024); } while (0)
; #define PG8_MMA(ai, bj, At, Bt) do { __builtin_amdgcn_s_setprio(1); _Pragma("unroll") for (int m = 0; m < 4; ++m) _Pragma("unroll") for (int n = 0; n < 2; ++n) _Pragma("unroll") for (int k = 0; k < 2; ++k) \
;         acc[ai][bj][m][n] = __builtin_amdgcn_mfma_f32_16x16x32_bf16(Bt[n][k], At[m][k], acc[ai][bj][m][n], 0, 0, 0); __builtin_amdgcn_s_setprio(0); } while (0)
; #define PG8_WAIT_V(n) asm volatile("s_waitcnt vmcnt(" #n ")" ::: "memory")
; #define PG8_WAIT_L(n) asm volatile("s_waitcnt lgkmcnt(" #n ")" ::: "memory")
; #define PG8_BAR __builtin_amdgcn_s_barrier()
; #define PG8_SCHED __builtin_amdgcn_sched_barrier(0)
; template <class Epi>
; __device__ __forceinline__ void gemm_phase(LAS unsigned char* lds, const Gemm g, const StaticOrder& S, const Epi& E) {
;     ...
;             PG8_WAIT_V(8); PG8_WAIT_L(0); PG8_BAR; PG8_MMA(1, 0, At, B0); PG8_MMA(1, 1, At, B1); PG8_BAR; PG8_SCHED;
;             PG8_LDB(B0, 1, 0); PG8_LDB(B1, 1, 1); PG8_SCHED; PG8_LDA(At, 1, 0); PG8_STAGE(PG8_SA(0, 1), a2 + hsA, voffA);
;             PG8_WAIT_V(8); PG8_WAIT_L(0); PG8_BAR; PG8_MMA(0, 0, At, B0); PG8_MMA(0, 1, At, B1); PG8_BAR; PG8_SCHED;
	s_setprio 1
	s_waitcnt lgkmcnt(0)
	v_mfma_f32_16x16x32_bf16 v[60:63], v[146:149], v[192:195], 0
	v_mfma_f32_16x16x32_bf16 v[56:59], v[158:161], v[192:195], 0
	v_mfma_f32_16x16x32_bf16 v[44:47], v[146:149], v[200:203], 0
	v_mfma_f32_16x16x32_bf16 v[40:43], v[158:161], v[200:203], 0
	v_mfma_f32_16x16x32_bf16 v[28:31], v[146:149], v[208:211], 0
	v_mfma_f32_16x16x32_bf16 v[24:27], v[158:161], v[208:211], 0
	v_mfma_f32_16x16x32_bf16 v[12:15], v[146:149], v[216:219], 0
	v_mfma_f32_16x16x32_bf16 v[8:11], v[158:161], v[216:219], 0
	v_mfma_f32_16x16x32_bf16 v[60:63], v[150:153], v[196:199], v[60:63]
	v_mfma_f32_16x16x32_bf16 v[56:59], v[172:175], v[196:199], v[56:59]
	v_mfma_f32_16x16x32_bf16 v[44:47], v[150:153], v[204:207], v[44:47]
	v_mfma_f32_16x16x32_bf16 v[40:43], v[172:175], v[204:207], v[40:43]
	v_mfma_f32_16x16x32_bf16 v[28:31], v[150:153], v[212:215], v[28:31]
	v_mfma_f32_16x16x32_bf16 v[24:27], v[172:175], v[212:215], v[24:27]
	v_mfma_f32_16x16x32_bf16 v[12:15], v[150:153], v[220:223], v[12:15]
	v_mfma_f32_16x16x32_bf16 v[8:11], v[172:175], v[220:223], v[8:11]
	s_setprio 0
	s_setprio 1
	v_mfma_f32_16x16x32_bf16 v[52:55], v[176:179], v[192:195], 0
	v_mfma_f32_16x16x32_bf16 v[48:51], v[184:187], v[192:195], 0
	v_mfma_f32_16x16x32_bf16 v[36:39], v[176:179], v[200:203], 0
	v_mfma_f32_16x16x32_bf16 v[32:35], v[184:187], v[200:203], 0
	v_mfma_f32_16x16x32_bf16 v[20:23], v[176:179], v[208:211], 0
	v_mfma_f32_16x16x32_bf16 v[16:19], v[184:187], v[208:211], 0
	v_mfma_f32_16x16x32_bf16 v[4:7], v[176:179], v[216:219], 0
	v_mfma_f32_16x16x32_bf16 v[0:3], v[184:187], v[216:219], 0
	v_mfma_f32_16x16x32_bf16 v[52:55], v[180:183], v[196:199], v[52:55]
	v_mfma_f32_16x16x32_bf16 v[48:51], v[188:191], v[196:199], v[48:51]
	v_mfma_f32_16x16x32_bf16 v[36:39], v[180:183], v[204:207], v[36:39]
	v_mfma_f32_16x16x32_bf16 v[32:35], v[188:191], v[204:207], v[32:35]
	v_mfma_f32_16x16x32_bf16 v[20:23], v[180:183], v[212:215], v[20:23]
	v_mfma_f32_16x16x32_bf16 v[16:19], v[188:191], v[212:215], v[16:19]
	v_mfma_f32_16x16x32_bf16 v[4:7], v[180:183], v[220:223], v[4:7]
	v_mfma_f32_16x16x32_bf16 v[0:3], v[188:191], v[220:223], v[0:3]
	s_setprio 0
	s_barrier
	s_add_i32 s33, 0, 0x18000
	v_add_u32_e32 v171, s33, v165
	s_add_i32 s89, 0, 0x1c000
	ds_read_b128 v[146:149], v171
	ds_read_b128 v[150:153], v171 offset:1024
	ds_read_b128 v[158:161], v171 offset:2048
	ds_read_b128 v[172:175], v171 offset:3072
	v_add_u32_e32 v171, s89, v165
	ds_read_b128 v[176:179], v171
	ds_read_b128 v[180:183], v171 offset:1024
	ds_read_b128 v[184:187], v171 offset:2048
	ds_read_b128 v[188:191], v171 offset:3072
	s_add_u32 s24, s56, 0xb0000
	s_addc_u32 s25, s57, 0
	s_mov_b32 m0, s63
	v_lshl_add_u64 v[230:231], s[24:25], 0, v[130:131]
	ds_read_b128 v[192:195], v169 offset:32768
	ds_read_b128 v[196:199], v169 offset:33792
	ds_read_b128 v[200:203], v169 offset:34816
	ds_read_b128 v[204:207], v169 offset:35840
	ds_read_b128 v[208:211], v169 offset:36864
	ds_read_b128 v[212:215], v169 offset:37888
	ds_read_b128 v[216:219], v169 offset:38912
	ds_read_b128 v[220:223], v169 offset:39936
	global_load_lds_dwordx4 v[230:231], off
	v_lshl_add_u64 v[230:231], s[24:25], 0, v[134:135]
	s_mov_b32 m0, s64
	s_nop 0
	global_load_lds_dwordx4 v[230:231], off
	s_waitcnt vmcnt(8)
	s_waitcnt lgkmcnt(0)
	s_barrier
	s_setprio 1
	s_waitcnt lgkmcnt(0)
	v_mfma_f32_16x16x32_bf16 v[124:127], v[146:149], v[192:195], v[124:127]
	v_mfma_f32_16x16x32_bf16 v[120:123], v[158:161], v[192:195], v[120:123]
	v_mfma_f32_16x16x32_bf16 v[108:111], v[146:149], v[200:203], v[108:111]
	v_mfma_f32_16x16x32_bf16 v[104:107], v[158:161], v[200:203], v[104:107]
	v_mfma_f32_16x16x32_bf16 v[92:95], v[146:149], v[208:211], v[92:95]
	v_mfma_f32_16x16x32_bf16 v[88:91], v[158:161], v[208:211], v[88:91]
	v_mfma_f32_16x16x32_bf16 v[76:79], v[146:149], v[216:219], v[76:79]
	v_mfma_f32_16x16x32_bf16 v[72:75], v[158:161], v[216:219], v[72:75]
	v_mfma_f32_16x16x32_bf16 v[124:127], v[150:153], v[196:199], v[124:127]
	v_mfma_f32_16x16x32_bf16 v[120:123], v[172:175], v[196:199], v[120:123]
	v_mfma_f32_16x16x32_bf16 v[108:111], v[150:153], v[204:207], v[108:111]
	v_mfma_f32_16x16x32_bf16 v[104:107], v[172:175], v[204:207], v[104:107]
	v_mfma_f32_16x16x32_bf16 v[92:95], v[150:153], v[212:215], v[92:95]
	v_mfma_f32_16x16x32_bf16 v[88:91], v[172:175], v[212:215], v[88:91]
	v_mfma_f32_16x16x32_bf16 v[76:79], v[150:153], v[220:223], v[76:79]
	v_mfma_f32_16x16x32_bf16 v[72:75], v[172:175], v[220:223], v[72:75]
	s_setprio 0
	s_setprio 1
	v_mfma_f32_16x16x32_bf16 v[116:119], v[176:179], v[192:195], v[116:119]
	v_mfma_f32_16x16x32_bf16 v[112:115], v[184:187], v[192:195], v[112:115]
	v_mfma_f32_16x16x32_bf16 v[100:103], v[176:179], v[200:203], v[100:103]
	v_mfma_f32_16x16x32_bf16 v[96:99], v[184:187], v[200:203], v[96:99]
	v_mfma_f32_16x16x32_bf16 v[84:87], v[176:179], v[208:211], v[84:87]
	v_mfma_f32_16x16x32_bf16 v[80:83], v[184:187], v[208:211], v[80:83]
	v_mfma_f32_16x16x32_bf16 v[68:71], v[176:179], v[216:219], v[68:71]
	v_mfma_f32_16x16x32_bf16 v[64:67], v[184:187], v[216:219], v[64:67]
	v_mfma_f32_16x16x32_bf16 v[116:119], v[180:183], v[196:199], v[116:119]
	v_mfma_f32_16x16x32_bf16 v[112:115], v[188:191], v[196:199], v[112:115]
	v_mfma_f32_16x16x32_bf16 v[100:103], v[180:183], v[204:207], v[100:103]
	v_mfma_f32_16x16x32_bf16 v[96:99], v[188:191], v[204:207], v[96:99]
	v_mfma_f32_16x16x32_bf16 v[84:87], v[180:183], v[212:215], v[84:87]
	v_mfma_f32_16x16x32_bf16 v[80:83], v[188:191], v[212:215], v[80:83]
	v_mfma_f32_16x16x32_bf16 v[68:71], v[180:183], v[220:223], v[68:71]
	v_mfma_f32_16x16x32_bf16 v[64:67], v[188:191], v[220:223], v[64:67]
	s_setprio 0
	s_barrier
; #define PG8_STAGE(bufoff, gbase, voff) do { _Pragma("unroll") for (int _i = 0; _i < 2; ++_i) \
;         __builtin_amdgcn_global_load_lds((const unsigned*)((const char*)(gbase) + (voff)[_i]), (LAS unsigned*)(lds + (bufoff) + ldsw + _i * 8192), 16, 0, 0); } while (0)
; #define PG8_LDA(dst, b, h) do { _Pragma("unroll") for (int m = 0; m < 4; ++m) _Pragma("unroll") for (int k = 0; k < 2; ++k) dst[m][k] = *(const LAS bf16x8*)(lds + PG8_SA(b, h) + aoff + m * 2048 + k * 1024); } while (0)
; #define PG8_MMA(ai, bj, At, Bt) do { __builtin_amdgcn_s_setprio(1); _Pragma("unroll") for (int m = 0; m < 4; ++m) _Pragma("unroll") for (int n = 0; n < 2; ++n) _Pragma("unroll") for (int k = 0; k < 2; ++k) \
;         acc[ai][bj][m][n] = __builtin_amdgcn_mfma_f32_16x16x32_bf16(Bt[n][k], At[m][k], acc[ai][bj][m][n], 0, 0, 0); __builtin_amdgcn_s_setprio(0); } while (0)
; #define PG8_WAIT_V(n) asm volatile("s_waitcnt vmcnt(" #n ")" ::: "memory")
; #define PG8_WAIT_L(n) asm volatile("s_waitcnt lgkmcnt(" #n ")" ::: "memory")
; #define PG8_BAR __builtin_amdgcn_s_barrier()
; #define PG8_SCHED __builtin_amdgcn_sched_barrier(0)
; template <class Epi>
; __device__ __forceinline__ void gemm_phase(LAS unsigned char* lds, const Gemm g, const StaticOrder& S, const Epi& E) {
;     ...
;             PG8_LDA(At, 1, 1); PG8_STAGE(PG8_SB(1, 0), b3, voffB); PG8_STAGE(PG8_SB(1, 1), b3 + hsB, voffB); PG8_STAGE(PG8_SA(1, 0), a3, voffA);
;             PG8_WAIT_V(8); PG8_WAIT_L(0); PG8_BAR; PG8_MMA(1, 0, At, B0); PG8_MMA(1, 1, At, B1); PG8_BAR; PG8_SCHED;
;         }
	s_add_i32 s24, s33, s60
	v_lshl_add_u64 v[154:155], v[154:155], 0, s[14:15]
	s_mov_b32 m0, s24
	ds_read_b128 v[192:195], v169 offset:49152
	ds_read_b128 v[196:199], v169 offset:50176
	ds_read_b128 v[200:203], v169 offset:51200
	ds_read_b128 v[204:207], v169 offset:52224
	ds_read_b128 v[208:211], v169 offset:53248
	ds_read_b128 v[212:215], v169 offset:54272
	ds_read_b128 v[216:219], v169 offset:55296
	ds_read_b128 v[220:223], v169 offset:56320
	global_load_lds_dwordx4 v[154:155], off
	s_add_i32 m0, s24, 0x2000
	s_add_u32 s24, s28, 0xb0080
	v_lshl_add_u64 v[154:155], v[224:225], 0, s[14:15]
	s_addc_u32 s25, s29, 0
	s_add_i32 s28, s89, s60
	global_load_lds_dwordx4 v[154:155], off
	v_lshl_add_u64 v[154:155], s[24:25], 0, v[132:133]
	s_mov_b32 m0, s28
	s_nop 0
	global_load_lds_dwordx4 v[154:155], off
	v_lshl_add_u64 v[154:155], s[24:25], 0, v[136:137]
	s_add_i32 m0, s28, 0x2000
	s_nop 0
	global_load_lds_dwordx4 v[154:155], off
	v_lshl_add_u64 v[154:155], v[226:227], 0, s[14:15]
	s_mov_b32 m0, s66
	s_nop 0
	global_load_lds_dwordx4 v[154:155], off
	v_lshl_add_u64 v[154:155], v[228:229], 0, s[14:15]
	s_mov_b32 m0, s67
	s_nop 0
	global_load_lds_dwordx4 v[154:155], off
	s_waitcnt vmcnt(8)
	s_waitcnt lgkmcnt(0)
	s_barrier
	s_setprio 1
	s_waitcnt lgkmcnt(0)
	v_mfma_f32_16x16x32_bf16 v[60:63], v[146:149], v[192:195], v[60:63]
	v_mfma_f32_16x16x32_bf16 v[56:59], v[158:161], v[192:195], v[56:59]
	v_mfma_f32_16x16x32_bf16 v[44:47], v[146:149], v[200:203], v[44:47]
	v_mfma_f32_16x16x32_bf16 v[40:43], v[158:161], v[200:203], v[40:43]
	v_mfma_f32_16x16x32_bf16 v[28:31], v[146:149], v[208:211], v[28:31]
	v_mfma_f32_16x16x32_bf16 v[24:27], v[158:161], v[208:211], v[24:27]
	v_mfma_f32_16x16x32_bf16 v[12:15], v[146:149], v[216:219], v[12:15]
	v_mfma_f32_16x16x32_bf16 v[8:11], v[158:161], v[216:219], v[8:11]
	v_mfma_f32_16x16x32_bf16 v[60:63], v[150:153], v[196:199], v[60:63]
	v_mfma_f32_16x16x32_bf16 v[56:59], v[172:175], v[196:199], v[56:59]
	v_mfma_f32_16x16x32_bf16 v[44:47], v[150:153], v[204:207], v[44:47]
	v_mfma_f32_16x16x32_bf16 v[40:43], v[172:175], v[204:207], v[40:43]
	v_mfma_f32_16x16x32_bf16 v[28:31], v[150:153], v[212:215], v[28:31]
	v_mfma_f32_16x16x32_bf16 v[24:27], v[172:175], v[212:215], v[24:27]
	v_mfma_f32_16x16x32_bf16 v[12:15], v[150:153], v[220:223], v[12:15]
	v_mfma_f32_16x16x32_bf16 v[8:11], v[172:175], v[220:223], v[8:11]
	s_setprio 0
	s_setprio 1
	v_mfma_f32_16x16x32_bf16 v[52:55], v[176:179], v[192:195], v[52:55]
	v_mfma_f32_16x16x32_bf16 v[48:51], v[184:187], v[192:195], v[48:51]
	v_mfma_f32_16x16x32_bf16 v[36:39], v[176:179], v[200:203], v[36:39]
	v_mfma_f32_16x16x32_bf16 v[32:35], v[184:187], v[200:203], v[32:35]
	v_mfma_f32_16x16x32_bf16 v[20:23], v[176:179], v[208:211], v[20:23]
	v_mfma_f32_16x16x32_bf16 v[16:19], v[184:187], v[208:211], v[16:19]
	v_mfma_f32_16x16x32_bf16 v[4:7], v[176:179], v[216:219], v[4:7]
	v_mfma_f32_16x16x32_bf16 v[0:3], v[184:187], v[216:219], v[0:3]
	v_mfma_f32_16x16x32_bf16 v[52:55], v[180:183], v[196:199], v[52:55]
	v_mfma_f32_16x16x32_bf16 v[48:51], v[188:191], v[196:199], v[48:51]
	v_mfma_f32_16x16x32_bf16 v[36:39], v[180:183], v[204:207], v[36:39]
	v_mfma_f32_16x16x32_bf16 v[32:35], v[188:191], v[204:207], v[32:35]
	v_mfma_f32_16x16x32_bf16 v[20:23], v[180:183], v[212:215], v[20:23]
	v_mfma_f32_16x16x32_bf16 v[16:19], v[188:191], v[212:215], v[16:19]
	v_mfma_f32_16x16x32_bf16 v[4:7], v[180:183], v[220:223], v[4:7]
	v_mfma_f32_16x16x32_bf16 v[0:3], v[188:191], v[220:223], v[0:3]
	s_setprio 0
	s_barrier
	s_add_i32 s88, s88, 2
	s_add_u32 s86, s86, 0x100
	s_addc_u32 s87, s87, 0
	s_cmp_gt_u32 s88, 41
	s_mov_b64 s[24:25], s[8:9]
	s_cbranch_scc0 .LBB0_305
	s_branch .Lpeel_exit1

; #define PG8_BAR __builtin_amdgcn_s_barrier()
; template <class Epi>
; __device__ __forceinline__ void gemm_phase(LAS unsigned char* lds, const Gemm g, const StaticOrder& S, const Epi& E) {
;     ...
;         if (wr == 0) PG8_BAR;
;         E(acc, cur, wr, wc, fr, fq);
;         if (!has_next) break;
.Lpeel_exit1:
	s_and_b64 vcc, exec, s[16:17]
	s_cbranch_vccz .LBB0_308
	s_barrier

; #define PG8_STAGE(bufoff, gbase, voff) do { _Pragma("unroll") for (int _i = 0; _i < 2; ++_i) \
;         __builtin_amdgcn_global_load_lds((const unsigned*)((const char*)(gbase) + (voff)[_i]), (LAS unsigned*)(lds + (bufoff) + ldsw + _i * 8192), 16, 0, 0); } while (0)
; #define PG8_LDA(dst, b, h) do { _Pragma("unroll") for (int m = 0; m < 4; ++m) _Pragma("unroll") for (int k = 0; k < 2; ++k) dst[m][k] = *(const LAS bf16x8*)(lds + PG8_SA(b, h) + aoff + m * 2048 + k * 1024); } while (0)
; #define PG8_LDB(dst, b, h) do { _Pragma("unroll") for (int n = 0; n < 2; ++n) _Pragma("unroll") for (int k = 0; k < 2; ++k) dst[n][k] = *(const LAS bf16x8*)(lds + PG8_SB(b, h) + boff + n * 2048 + k * 1024); } while (0)
; #define PG8_WAIT_V(n) asm volatile("s_waitcnt vmcnt(" #n ")" ::: "memory")
; #define PG8_WAIT_L(n) asm volatile("s_waitcnt lgkmcnt(" #n ")" ::: "memory")
; template <class Epi>
; __device__ __forceinline__ void gemm_phase(LAS unsigned char* lds, const Gemm g, const StaticOrder& S, const Epi& E) {
;     ...
;         const bool has_next = S.next(ui + 1, nxt);
;         const char* nA = has_next ? (const char*)g.A + (size_t)nxt.pm * tsA : cA; const char* nB = has_next ? (const char*)g.Bt + (size_t)nxt.pn * tsB : cB;
;         for (int t = 0; t < nt; t += 2) {
;             const bool last = (t == nt - 2);
;             const char* a1 = cA + (size_t)(t + 1) * kstep;
;             const char* a2 = last ? nA : cA + (size_t)(t + 2) * kstep; const char* b2 = last ? nB : cB + (size_t)(t + 2) * kstep;
;             const char* a3 = a2 + kstep; const char* b3 = b2 + kstep;
;             PG8_LDB(B0, 0, 0); PG8_LDB(B1, 0, 1); PG8_SCHED; PG8_LDA(At, 0, 0); PG8_STAGE(PG8_SA(1, 1), a1 + hsA, voffA);
;             PG8_WAIT_V(8); PG8_WAIT_L(0); PG8_BAR; PG8_MMA(0, 0, At, B0); PG8_MMA(0, 1, At, B1); PG8_BAR; PG8_SCHED;
;             PG8_LDA(At, 0, 1); PG8_STAGE(PG8_SB(0, 0), b2, voffB); PG8_STAGE(PG8_SB(0, 1), b2 + hsB, voffB); PG8_STAGE(PG8_SA(0, 0), a2, voffA);
;             PG8_WAIT_V(8); PG8_WAIT_L(0); PG8_BAR; PG8_MMA(1, 0, At, B0); PG8_MMA(1, 1, At, B1); PG8_BAR; PG8_SCHED;
;     ...
;         for (int a = 0; a < 2; ++a)
; #pragma unroll
;             for (int b = 0; b < 2; ++b)
; #pragma unroll
;                 for (int m = 0; m < 4; ++m)
; #pragma unroll
;                     for (int n = 0; n < 2; ++n) acc[a][b][m][n] = (f32x4){0.f, 0.f, 0.f, 0.f};
.LBB0_422:
	s_ashr_i32 s17, s16, 31
	s_lshl_b64 s[18:19], s[16:17], 19
	s_add_u32 s18, s46, s18
	s_addc_u32 s19, s47, s19
	s_and_b64 s[20:21], s[4:5], exec
	s_cselect_b32 s7, s19, s25
	s_cselect_b32 s17, s18, s24
	s_ashr_i32 s15, s14, 31
	s_lshl_b64 s[20:21], s[14:15], 19
	s_add_u32 s20, s60, s20
	s_addc_u32 s21, s61, s21
	s_and_b64 s[56:57], s[4:5], exec
	s_cselect_b32 s15, s21, s29
	s_cselect_b32 s23, s20, s28
	s_add_u32 s24, s24, 0x40080
	s_addc_u32 s25, s25, 0
	s_add_u32 s88, s28, 0x100
	s_addc_u32 s89, s29, 0
	s_mov_b32 s90, -2
	ds_read_b128 v[146:149], v160
	ds_read_b128 v[150:153], v160 offset:1024
	ds_read_b128 v[168:171], v160 offset:2048
	ds_read_b128 v[172:175], v160 offset:3072
	ds_read_b128 v[176:179], v161
	ds_read_b128 v[180:183], v161 offset:1024
	ds_read_b128 v[184:187], v161 offset:2048
	ds_read_b128 v[188:191], v161 offset:3072
	s_add_u32 s28, s24, 0xfffc0080
	s_addc_u32 s29, s25, -1
	s_cmp_eq_u32 s90, 12
	s_cselect_b32 s57, s7, s29
	s_cselect_b32 s56, s17, s28
	s_cselect_b32 s29, s15, s89
	s_cselect_b32 s28, s23, s88
	v_lshl_add_u64 v[154:155], s[24:25], 0, v[138:139]
	s_add_i32 m0, s63, 0xc000
	ds_read_b128 v[192:195], v165
	ds_read_b128 v[196:199], v165 offset:1024
	ds_read_b128 v[200:203], v165 offset:2048
	ds_read_b128 v[204:207], v165 offset:3072
	ds_read_b128 v[208:211], v165 offset:4096
	ds_read_b128 v[212:215], v165 offset:5120
	ds_read_b128 v[216:219], v165 offset:6144
	ds_read_b128 v[220:223], v165 offset:7168
	global_load_lds_dwordx4 v[154:155], off
	v_lshl_add_u64 v[154:155], s[24:25], 0, v[140:141]
	s_add_i32 m0, s63, 0xe000
	s_nop 0
	global_load_lds_dwordx4 v[154:155], off
	s_waitcnt vmcnt(8)
	s_waitcnt lgkmcnt(0)
	s_barrier
	s_setprio 1
	s_waitcnt lgkmcnt(0)
	v_mfma_f32_16x16x32_bf16 v[124:127], v[146:149], v[192:195], 0
	v_mfma_f32_16x16x32_bf16 v[120:123], v[168:171], v[192:195], 0
	v_mfma_f32_16x16x32_bf16 v[108:111], v[146:149], v[200:203], 0
	v_mfma_f32_16x16x32_bf16 v[104:107], v[168:171], v[200:203], 0
	v_mfma_f32_16x16x32_bf16 v[92:95], v[146:149], v[208:211], 0
	v_mfma_f32_16x16x32_bf16 v[88:91], v[168:171], v[208:211], 0
	v_mfma_f32_16x16x32_bf16 v[76:79], v[146:149], v[216:219], 0
	v_mfma_f32_16x16x32_bf16 v[72:75], v[168:171], v[216:219], 0
	v_mfma_f32_16x16x32_bf16 v[124:127], v[150:153], v[196:199], v[124:127]
	v_mfma_f32_16x16x32_bf16 v[120:123], v[172:175], v[196:199], v[120:123]
	v_mfma_f32_16x16x32_bf16 v[108:111], v[150:153], v[204:207], v[108:111]
	v_mfma_f32_16x16x32_bf16 v[104:107], v[172:175], v[204:207], v[104:107]
	v_mfma_f32_16x16x32_bf16 v[92:95], v[150:153], v[212:215], v[92:95]
	v_mfma_f32_16x16x32_bf16 v[88:91], v[172:175], v[212:215], v[88:91]
	v_mfma_f32_16x16x32_bf16 v[76:79], v[150:153], v[220:223], v[76:79]
	v_mfma_f32_16x16x32_bf16 v[72:75], v[172:175], v[220:223], v[72:75]
	s_setprio 0
	s_setprio 1
	v_mfma_f32_16x16x32_bf16 v[116:119], v[176:179], v[192:195], 0
	v_mfma_f32_16x16x32_bf16 v[112:115], v[184:187], v[192:195], 0
	v_mfma_f32_16x16x32_bf16 v[100:103], v[176:179], v[200:203], 0
	v_mfma_f32_16x16x32_bf16 v[96:99], v[184:187], v[200:203], 0
	v_mfma_f32_16x16x32_bf16 v[84:87], v[176:179], v[208:211], 0
	v_mfma_f32_16x16x32_bf16 v[80:83], v[184:187], v[208:211], 0
	v_mfma_f32_16x16x32_bf16 v[68:71], v[176:179], v[216:219], 0
	v_mfma_f32_16x16x32_bf16 v[64:67], v[184:187], v[216:219], 0
	v_mfma_f32_16x16x32_bf16 v[116:119], v[180:183], v[196:199], v[116:119]
	v_mfma_f32_16x16x32_bf16 v[112:115], v[188:191], v[196:199], v[112:115]
	v_mfma_f32_16x16x32_bf16 v[100:103], v[180:183], v[204:207], v[100:103]
	v_mfma_f32_16x16x32_bf16 v[96:99], v[188:191], v[204:207], v[96:99]
	v_mfma_f32_16x16x32_bf16 v[84:87], v[180:183], v[212:215], v[84:87]
	v_mfma_f32_16x16x32_bf16 v[80:83], v[188:191], v[212:215], v[80:83]
	v_mfma_f32_16x16x32_bf16 v[68:71], v[180:183], v[220:223], v[68:71]
	v_mfma_f32_16x16x32_bf16 v[64:67], v[188:191], v[220:223], v[64:67]
	s_setprio 0
	s_barrier
	s_add_i32 s33, s83, s62
	v_lshl_add_u64 v[154:155], s[28:29], 0, v[132:133]
	s_mov_b32 m0, s33
	ds_read_b128 v[192:195], v165 offset:16384
	ds_read_b128 v[196:199], v165 offset:17408
	ds_read_b128 v[200:203], v165 offset:18432
	ds_read_b128 v[204:207], v165 offset:19456
	ds_read_b128 v[208:211], v165 offset:20480
	ds_read_b128 v[212:215], v165 offset:21504
	ds_read_b128 v[216:219], v165 offset:22528
	ds_read_b128 v[220:223], v165 offset:23552
	global_load_lds_dwordx4 v[154:155], off
	s_add_i32 m0, s33, 0x2000
	s_add_u32 s92, s28, 0x40000
	v_lshl_add_u64 v[224:225], s[28:29], 0, v[136:137]
	s_addc_u32 s93, s29, 0
	s_add_i32 s33, s84, s62
	global_load_lds_dwordx4 v[224:225], off
	v_lshl_add_u64 v[226:227], s[92:93], 0, v[132:133]
	s_mov_b32 m0, s33
	v_lshl_add_u64 v[228:229], s[56:57], 0, v[134:135]
	global_load_lds_dwordx4 v[226:227], off
	v_lshl_add_u64 v[226:227], s[92:93], 0, v[136:137]
	s_add_i32 m0, s33, 0x2000
	s_nop 0
	global_load_lds_dwordx4 v[226:227], off
	v_lshl_add_u64 v[226:227], s[56:57], 0, v[130:131]
	s_mov_b32 m0, s63
	s_nop 0
	global_load_lds_dwordx4 v[226:227], off
	s_mov_b32 m0, s64
	s_nop 0
	global_load_lds_dwordx4 v[228:229], off
	s_waitcnt vmcnt(8)
	s_waitcnt lgkmcnt(0)
	s_barrier
; #define PG8_STAGE(bufoff, gbase, voff) do { _Pragma("unroll") for (int _i = 0; _i < 2; ++_i) \
;         __builtin_amdgcn_global_load_lds((const unsigned*)((const char*)(gbase) + (voff)[_i]), (LAS unsigned*)(lds + (bufoff) + ldsw + _i * 8192), 16, 0, 0); } while (0)
; #define PG8_LDA(dst, b, h) do { _Pragma("unroll") for (int m = 0; m < 4; ++m) _Pragma("unroll") for (int k = 0; k < 2; ++k) dst[m][k] = *(const LAS bf16x8*)(lds + PG8_SA(b, h) + aoff + m * 2048 + k * 1024); } while (0)
; #define PG8_LDB(dst, b, h) do { _Pragma("unroll") for (int n = 0; n < 2; ++n) _Pragma("unroll") for (int k = 0; k < 2; ++k) dst[n][k] = *(const LAS bf16x8*)(lds + PG8_SB(b, h) + boff + n * 2048 + k * 1024); } while (0)
; #define PG8_MMA(ai, bj, At, Bt) do { __builtin_amdgcn_s_setprio(1); _Pragma("unroll") for (int m = 0; m < 4; ++m) _Pragma("unroll") for (int n = 0; n < 2; ++n) _Pragma("unroll") for (int k = 0; k < 2; ++k) \
;         acc[ai][bj][m][n] = __builtin_amdgcn_mfma_f32_16x16x32_bf16(Bt[n][k], At[m][k], acc[ai][bj][m][n], 0, 0, 0); __builtin_amdgcn_s_setprio(0); } while (0)
; #define PG8_WAIT_V(n) asm volatile("s_waitcnt vmcnt(" #n ")" ::: "memory")
; #define PG8_WAIT_L(n) asm volatile("s_waitcnt lgkmcnt(" #n ")" ::: "memory")
; #define PG8_BAR __builtin_amdgcn_s_barrier()
; #define PG8_SCHED __builtin_amdgcn_sched_barrier(0)
; template <class Epi>
; __device__ __forceinline__ void gemm_phase(LAS unsigned char* lds, const Gemm g, const StaticOrder& S, const Epi& E) {
;     ...
;             PG8_WAIT_V(8); PG8_WAIT_L(0); PG8_BAR; PG8_MMA(1, 0, At, B0); PG8_MMA(1, 1, At, B1); PG8_BAR; PG8_SCHED;
;             PG8_LDB(B0, 1, 0); PG8_LDB(B1, 1, 1); PG8_SCHED; PG8_LDA(At, 1, 0); PG8_STAGE(PG8_SA(0, 1), a2 + hsA, voffA);
;             PG8_WAIT_V(8); PG8_WAIT_L(0); PG8_BAR; PG8_MMA(0, 0, At, B0); PG8_MMA(0, 1, At, B1); PG8_BAR; PG8_SCHED;
	s_setprio 1
	s_waitcnt lgkmcnt(0)
	v_mfma_f32_16x16x32_bf16 v[60:63], v[146:149], v[192:195], 0
	v_mfma_f32_16x16x32_bf16 v[56:59], v[168:171], v[192:195], 0
	v_mfma_f32_16x16x32_bf16 v[44:47], v[146:149], v[200:203], 0
	v_mfma_f32_16x16x32_bf16 v[40:43], v[168:171], v[200:203], 0
	v_mfma_f32_16x16x32_bf16 v[28:31], v[146:149], v[208:211], 0
	v_mfma_f32_16x16x32_bf16 v[24:27], v[168:171], v[208:211], 0
	v_mfma_f32_16x16x32_bf16 v[12:15], v[146:149], v[216:219], 0
	v_mfma_f32_16x16x32_bf16 v[8:11], v[168:171], v[216:219], 0
	v_mfma_f32_16x16x32_bf16 v[60:63], v[150:153], v[196:199], v[60:63]
	v_mfma_f32_16x16x32_bf16 v[56:59], v[172:175], v[196:199], v[56:59]
	v_mfma_f32_16x16x32_bf16 v[44:47], v[150:153], v[204:207], v[44:47]
	v_mfma_f32_16x16x32_bf16 v[40:43], v[172:175], v[204:207], v[40:43]
	v_mfma_f32_16x16x32_bf16 v[28:31], v[150:153], v[212:215], v[28:31]
	v_mfma_f32_16x16x32_bf16 v[24:27], v[172:175], v[212:215], v[24:27]
	v_mfma_f32_16x16x32_bf16 v[12:15], v[150:153], v[220:223], v[12:15]
	v_mfma_f32_16x16x32_bf16 v[8:11], v[172:175], v[220:223], v[8:11]
	s_setprio 0
	s_setprio 1
	v_mfma_f32_16x16x32_bf16 v[52:55], v[176:179], v[192:195], 0
	v_mfma_f32_16x16x32_bf16 v[48:51], v[184:187], v[192:195], 0
	v_mfma_f32_16x16x32_bf16 v[36:39], v[176:179], v[200:203], 0
	v_mfma_f32_16x16x32_bf16 v[32:35], v[184:187], v[200:203], 0
	v_mfma_f32_16x16x32_bf16 v[20:23], v[176:179], v[208:211], 0
	v_mfma_f32_16x16x32_bf16 v[16:19], v[184:187], v[208:211], 0
	v_mfma_f32_16x16x32_bf16 v[4:7], v[176:179], v[216:219], 0
	v_mfma_f32_16x16x32_bf16 v[0:3], v[184:187], v[216:219], 0
	v_mfma_f32_16x16x32_bf16 v[52:55], v[180:183], v[196:199], v[52:55]
	v_mfma_f32_16x16x32_bf16 v[48:51], v[188:191], v[196:199], v[48:51]
	v_mfma_f32_16x16x32_bf16 v[36:39], v[180:183], v[204:207], v[36:39]
	v_mfma_f32_16x16x32_bf16 v[32:35], v[188:191], v[204:207], v[32:35]
	v_mfma_f32_16x16x32_bf16 v[20:23], v[180:183], v[212:215], v[20:23]
	v_mfma_f32_16x16x32_bf16 v[16:19], v[188:191], v[212:215], v[16:19]
	v_mfma_f32_16x16x32_bf16 v[4:7], v[180:183], v[220:223], v[4:7]
	v_mfma_f32_16x16x32_bf16 v[0:3], v[188:191], v[220:223], v[0:3]
	s_setprio 0
	s_barrier
	s_add_i32 s33, 0, 0x18000
	s_add_i32 s91, 0, 0x1c000
	v_add_u32_e32 v172, s33, v158
	v_add_u32_e32 v188, s91, v158
	ds_read_b128 v[146:149], v172
	ds_read_b128 v[150:153], v172 offset:1024
	ds_read_b128 v[168:171], v172 offset:2048
	ds_read_b128 v[172:175], v172 offset:3072
	ds_read_b128 v[176:179], v188
	ds_read_b128 v[180:183], v188 offset:1024
	ds_read_b128 v[184:187], v188 offset:2048
	ds_read_b128 v[188:191], v188 offset:3072
	s_add_u32 s56, s56, 0x40000
	s_addc_u32 s57, s57, 0
	s_mov_b32 m0, s65
	v_lshl_add_u64 v[230:231], s[56:57], 0, v[130:131]
	ds_read_b128 v[192:195], v165 offset:32768
	ds_read_b128 v[196:199], v165 offset:33792
	ds_read_b128 v[200:203], v165 offset:34816
	ds_read_b128 v[204:207], v165 offset:35840
	ds_read_b128 v[208:211], v165 offset:36864
	ds_read_b128 v[212:215], v165 offset:37888
	ds_read_b128 v[216:219], v165 offset:38912
	ds_read_b128 v[220:223], v165 offset:39936
	global_load_lds_dwordx4 v[230:231], off
	v_lshl_add_u64 v[230:231], s[56:57], 0, v[134:135]
	s_mov_b32 m0, s66
	s_nop 0
	global_load_lds_dwordx4 v[230:231], off
	s_waitcnt vmcnt(8)
	s_waitcnt lgkmcnt(0)
	s_barrier
	s_setprio 1
	s_waitcnt lgkmcnt(0)
	v_mfma_f32_16x16x32_bf16 v[124:127], v[146:149], v[192:195], v[124:127]
	v_mfma_f32_16x16x32_bf16 v[120:123], v[168:171], v[192:195], v[120:123]
	v_mfma_f32_16x16x32_bf16 v[108:111], v[146:149], v[200:203], v[108:111]
	v_mfma_f32_16x16x32_bf16 v[104:107], v[168:171], v[200:203], v[104:107]
	v_mfma_f32_16x16x32_bf16 v[92:95], v[146:149], v[208:211], v[92:95]
	v_mfma_f32_16x16x32_bf16 v[88:91], v[168:171], v[208:211], v[88:91]
	v_mfma_f32_16x16x32_bf16 v[76:79], v[146:149], v[216:219], v[76:79]
	v_mfma_f32_16x16x32_bf16 v[72:75], v[168:171], v[216:219], v[72:75]
	v_mfma_f32_16x16x32_bf16 v[124:127], v[150:153], v[196:199], v[124:127]
	v_mfma_f32_16x16x32_bf16 v[120:123], v[172:175], v[196:199], v[120:123]
	v_mfma_f32_16x16x32_bf16 v[108:111], v[150:153], v[204:207], v[108:111]
	v_mfma_f32_16x16x32_bf16 v[104:107], v[172:175], v[204:207], v[104:107]
	v_mfma_f32_16x16x32_bf16 v[92:95], v[150:153], v[212:215], v[92:95]
	v_mfma_f32_16x16x32_bf16 v[88:91], v[172:175], v[212:215], v[88:91]
	v_mfma_f32_16x16x32_bf16 v[76:79], v[150:153], v[220:223], v[76:79]
	v_mfma_f32_16x16x32_bf16 v[72:75], v[172:175], v[220:223], v[72:75]
	s_setprio 0
	s_setprio 1
	v_mfma_f32_16x16x32_bf16 v[116:119], v[176:179], v[192:195], v[116:119]
	v_mfma_f32_16x16x32_bf16 v[112:115], v[184:187], v[192:195], v[112:115]
	v_mfma_f32_16x16x32_bf16 v[100:103], v[176:179], v[200:203], v[100:103]
	v_mfma_f32_16x16x32_bf16 v[96:99], v[184:187], v[200:203], v[96:99]
	v_mfma_f32_16x16x32_bf16 v[84:87], v[176:179], v[208:211], v[84:87]
	v_mfma_f32_16x16x32_bf16 v[80:83], v[184:187], v[208:211], v[80:83]
	v_mfma_f32_16x16x32_bf16 v[68:71], v[176:179], v[216:219], v[68:71]
	v_mfma_f32_16x16x32_bf16 v[64:67], v[184:187], v[216:219], v[64:67]
	v_mfma_f32_16x16x32_bf16 v[116:119], v[180:183], v[196:199], v[116:119]
	v_mfma_f32_16x16x32_bf16 v[112:115], v[188:191], v[196:199], v[112:115]
	v_mfma_f32_16x16x32_bf16 v[100:103], v[180:183], v[204:207], v[100:103]
	v_mfma_f32_16x16x32_bf16 v[96:99], v[188:191], v[204:207], v[96:99]
	v_mfma_f32_16x16x32_bf16 v[84:87], v[180:183], v[212:215], v[84:87]
	v_mfma_f32_16x16x32_bf16 v[80:83], v[188:191], v[212:215], v[80:83]
	v_mfma_f32_16x16x32_bf16 v[68:71], v[180:183], v[220:223], v[68:71]
	v_mfma_f32_16x16x32_bf16 v[64:67], v[188:191], v[220:223], v[64:67]
	s_setprio 0
	s_barrier
; #define PG8_STAGE(bufoff, gbase, voff) do { _Pragma("unroll") for (int _i = 0; _i < 2; ++_i) \
;         __builtin_amdgcn_global_load_lds((const unsigned*)((const char*)(gbase) + (voff)[_i]), (LAS unsigned*)(lds + (bufoff) + ldsw + _i * 8192), 16, 0, 0); } while (0)
; #define PG8_LDA(dst, b, h) do { _Pragma("unroll") for (int m = 0; m < 4; ++m) _Pragma("unroll") for (int k = 0; k < 2; ++k) dst[m][k] = *(const LAS bf16x8*)(lds + PG8_SA(b, h) + aoff + m * 2048 + k * 1024); } while (0)
; #define PG8_MMA(ai, bj, At, Bt) do { __builtin_amdgcn_s_setprio(1); _Pragma("unroll") for (int m = 0; m < 4; ++m) _Pragma("unroll") for (int n = 0; n < 2; ++n) _Pragma("unroll") for (int k = 0; k < 2; ++k) \
;         acc[ai][bj][m][n] = __builtin_amdgcn_mfma_f32_16x16x32_bf16(Bt[n][k], At[m][k], acc[ai][bj][m][n], 0, 0, 0); __builtin_amdgcn_s_setprio(0); } while (0)
; #define PG8_WAIT_V(n) asm volatile("s_waitcnt vmcnt(" #n ")" ::: "memory")
; #define PG8_WAIT_L(n) asm volatile("s_waitcnt lgkmcnt(" #n ")" ::: "memory")
; #define PG8_BAR __builtin_amdgcn_s_barrier()
; #define PG8_SCHED __builtin_amdgcn_sched_barrier(0)
; template <class Epi>
; __device__ __forceinline__ void gemm_phase(LAS unsigned char* lds, const Gemm g, const StaticOrder& S, const Epi& E) {
;     ...
;             PG8_LDA(At, 1, 1); PG8_STAGE(PG8_SB(1, 0), b3, voffB); PG8_STAGE(PG8_SB(1, 1), b3 + hsB, voffB); PG8_STAGE(PG8_SA(1, 0), a3, voffA);
;             PG8_WAIT_V(8); PG8_WAIT_L(0); PG8_BAR; PG8_MMA(1, 0, At, B0); PG8_MMA(1, 1, At, B1); PG8_BAR; PG8_SCHED;
;         }
	s_add_i32 s33, s33, s62
	v_lshl_add_u64 v[154:155], v[154:155], 0, s[10:11]
	s_mov_b32 m0, s33
	ds_read_b128 v[192:195], v165 offset:49152
	ds_read_b128 v[196:199], v165 offset:50176
	ds_read_b128 v[200:203], v165 offset:51200
	ds_read_b128 v[204:207], v165 offset:52224
	ds_read_b128 v[208:211], v165 offset:53248
	ds_read_b128 v[212:215], v165 offset:54272
	ds_read_b128 v[216:219], v165 offset:55296
	ds_read_b128 v[220:223], v165 offset:56320
	global_load_lds_dwordx4 v[154:155], off
	s_add_i32 m0, s33, 0x2000
	s_add_u32 s28, s28, 0x40080
	v_lshl_add_u64 v[154:155], v[224:225], 0, s[10:11]
	s_addc_u32 s29, s29, 0
	s_add_i32 s33, s91, s62
	global_load_lds_dwordx4 v[154:155], off
	v_lshl_add_u64 v[154:155], s[28:29], 0, v[132:133]
	s_mov_b32 m0, s33
	s_nop 0
	global_load_lds_dwordx4 v[154:155], off
	v_lshl_add_u64 v[154:155], s[28:29], 0, v[136:137]
	s_add_i32 m0, s33, 0x2000
	s_nop 0
	global_load_lds_dwordx4 v[154:155], off
	v_lshl_add_u64 v[154:155], v[226:227], 0, s[10:11]
	s_mov_b32 m0, s76
	s_nop 0
	global_load_lds_dwordx4 v[154:155], off
	v_lshl_add_u64 v[154:155], v[228:229], 0, s[10:11]
	s_mov_b32 m0, s77
	s_nop 0
	global_load_lds_dwordx4 v[154:155], off
	s_waitcnt vmcnt(8)
	s_waitcnt lgkmcnt(0)
	s_barrier
	s_setprio 1
	s_waitcnt lgkmcnt(0)
	v_mfma_f32_16x16x32_bf16 v[60:63], v[146:149], v[192:195], v[60:63]
	v_mfma_f32_16x16x32_bf16 v[56:59], v[168:171], v[192:195], v[56:59]
	v_mfma_f32_16x16x32_bf16 v[44:47], v[146:149], v[200:203], v[44:47]
	v_mfma_f32_16x16x32_bf16 v[40:43], v[168:171], v[200:203], v[40:43]
	v_mfma_f32_16x16x32_bf16 v[28:31], v[146:149], v[208:211], v[28:31]
	v_mfma_f32_16x16x32_bf16 v[24:27], v[168:171], v[208:211], v[24:27]
	v_mfma_f32_16x16x32_bf16 v[12:15], v[146:149], v[216:219], v[12:15]
	v_mfma_f32_16x16x32_bf16 v[8:11], v[168:171], v[216:219], v[8:11]
	v_mfma_f32_16x16x32_bf16 v[60:63], v[150:153], v[196:199], v[60:63]
	v_mfma_f32_16x16x32_bf16 v[56:59], v[172:175], v[196:199], v[56:59]
	v_mfma_f32_16x16x32_bf16 v[44:47], v[150:153], v[204:207], v[44:47]
	v_mfma_f32_16x16x32_bf16 v[40:43], v[172:175], v[204:207], v[40:43]
	v_mfma_f32_16x16x32_bf16 v[28:31], v[150:153], v[212:215], v[28:31]
	v_mfma_f32_16x16x32_bf16 v[24:27], v[172:175], v[212:215], v[24:27]
	v_mfma_f32_16x16x32_bf16 v[12:15], v[150:153], v[220:223], v[12:15]
	v_mfma_f32_16x16x32_bf16 v[8:11], v[172:175], v[220:223], v[8:11]
	s_setprio 0
	s_setprio 1
	v_mfma_f32_16x16x32_bf16 v[52:55], v[176:179], v[192:195], v[52:55]
	v_mfma_f32_16x16x32_bf16 v[48:51], v[184:187], v[192:195], v[48:51]
	v_mfma_f32_16x16x32_bf16 v[36:39], v[176:179], v[200:203], v[36:39]
	v_mfma_f32_16x16x32_bf16 v[32:35], v[184:187], v[200:203], v[32:35]
	v_mfma_f32_16x16x32_bf16 v[20:23], v[176:179], v[208:211], v[20:23]
	v_mfma_f32_16x16x32_bf16 v[16:19], v[184:187], v[208:211], v[16:19]
	v_mfma_f32_16x16x32_bf16 v[4:7], v[176:179], v[216:219], v[4:7]
	v_mfma_f32_16x16x32_bf16 v[0:3], v[184:187], v[216:219], v[0:3]
	v_mfma_f32_16x16x32_bf16 v[52:55], v[180:183], v[196:199], v[52:55]
	v_mfma_f32_16x16x32_bf16 v[48:51], v[188:191], v[196:199], v[48:51]
	v_mfma_f32_16x16x32_bf16 v[36:39], v[180:183], v[204:207], v[36:39]
	v_mfma_f32_16x16x32_bf16 v[32:35], v[188:191], v[204:207], v[32:35]
	v_mfma_f32_16x16x32_bf16 v[20:23], v[180:183], v[212:215], v[20:23]
	v_mfma_f32_16x16x32_bf16 v[16:19], v[188:191], v[212:215], v[16:19]
	v_mfma_f32_16x16x32_bf16 v[4:7], v[180:183], v[220:223], v[4:7]
	v_mfma_f32_16x16x32_bf16 v[0:3], v[188:191], v[220:223], v[0:3]
	s_setprio 0
	s_barrier
	s_add_i32 s90, s90, 2
	s_add_u32 s24, s24, 0x100
	s_addc_u32 s25, s25, 0
	s_add_u32 s88, s88, 0x100
	s_addc_u32 s89, s89, 0
	s_cmp_gt_u32 s90, 13
	s_cbranch_scc0 .LBB0_423
	s_branch .Lpeel_exit2

; #define PG8_BAR __builtin_amdgcn_s_barrier()
; template <class Epi>
; __device__ __forceinline__ void gemm_phase(LAS unsigned char* lds, const Gemm g, const StaticOrder& S, const Epi& E) {
;     ...
;         if (wr == 0) PG8_BAR;
;         E(acc, cur, wr, wc, fr, fq);
;         if (!has_next) break;
.Lpeel_exit2:
	s_and_b64 vcc, exec, s[12:13]
	s_cbranch_vccz .LBB0_426
	s_barrier

; #define PG8_STAGE(bufoff, gbase, voff) do { _Pragma("unroll") for (int _i = 0; _i < 2; ++_i) \
;         __builtin_amdgcn_global_load_lds((const unsigned*)((const char*)(gbase) + (voff)[_i]), (LAS unsigned*)(lds + (bufoff) + ldsw + _i * 8192), 16, 0, 0); } while (0)
; #define PG8_LDA(dst, b, h) do { _Pragma("unroll") for (int m = 0; m < 4; ++m) _Pragma("unroll") for (int k = 0; k < 2; ++k) dst[m][k] = *(const LAS bf16x8*)(lds + PG8_SA(b, h) + aoff + m * 2048 + k * 1024); } while (0)
; #define PG8_LDB(dst, b, h) do { _Pragma("unroll") for (int n = 0; n < 2; ++n) _Pragma("unroll") for (int k = 0; k < 2; ++k) dst[n][k] = *(const LAS bf16x8*)(lds + PG8_SB(b, h) + boff + n * 2048 + k * 1024); } while (0)
; #define PG8_WAIT_V(n) asm volatile("s_waitcnt vmcnt(" #n ")" ::: "memory")
; #define PG8_WAIT_L(n) asm volatile("s_waitcnt lgkmcnt(" #n ")" ::: "memory")
; template <class Epi>
; __device__ __forceinline__ void gemm_phase(LAS unsigned char* lds, const Gemm g, const StaticOrder& S, const Epi& E) {
;     ...
;         const bool has_next = S.next(ui + 1, nxt);
;         const char* nA = has_next ? (const char*)g.A + (size_t)nxt.pm * tsA : cA; const char* nB = has_next ? (const char*)g.Bt + (size_t)nxt.pn * tsB : cB;
;         for (int t = 0; t < nt; t += 2) {
;             const bool last = (t == nt - 2);
;             const char* a1 = cA + (size_t)(t + 1) * kstep;
;             const char* a2 = last ? nA : cA + (size_t)(t + 2) * kstep; const char* b2 = last ? nB : cB + (size_t)(t + 2) * kstep;
;             const char* a3 = a2 + kstep; const char* b3 = b2 + kstep;
;             PG8_LDB(B0, 0, 0); PG8_LDB(B1, 0, 1); PG8_SCHED; PG8_LDA(At, 0, 0); PG8_STAGE(PG8_SA(1, 1), a1 + hsA, voffA);
;             PG8_WAIT_V(8); PG8_WAIT_L(0); PG8_BAR; PG8_MMA(0, 0, At, B0); PG8_MMA(0, 1, At, B1); PG8_BAR; PG8_SCHED;
;             PG8_LDA(At, 0, 1); PG8_STAGE(PG8_SB(0, 0), b2, voffB); PG8_STAGE(PG8_SB(0, 1), b2 + hsB, voffB); PG8_STAGE(PG8_SA(0, 0), a2, voffA);
;             PG8_WAIT_V(8); PG8_WAIT_L(0); PG8_BAR; PG8_MMA(1, 0, At, B0); PG8_MMA(1, 1, At, B1); PG8_BAR; PG8_SCHED;
;     ...
;         for (int a = 0; a < 2; ++a)
; #pragma unroll
;             for (int b = 0; b < 2; ++b)
; #pragma unroll
;                 for (int m = 0; m < 4; ++m)
; #pragma unroll
;                     for (int n = 0; n < 2; ++n) acc[a][b][m][n] = (f32x4){0.f, 0.f, 0.f, 0.f};
.LBB0_593:
	s_ashr_i32 s23, s22, 31
	s_lshl_b64 s[24:25], s[22:23], 18
	s_add_u32 s24, s46, s24
	s_addc_u32 s25, s47, s25
	s_and_b64 s[26:27], s[4:5], exec
	s_cselect_b32 s23, s25, s37
	s_cselect_b32 s85, s24, s36
	s_ashr_i32 s21, s20, 31
	s_lshl_b64 s[26:27], s[20:21], 18
	s_add_u32 s26, s43, s26
	s_addc_u32 s27, s60, s27
	s_and_b64 s[40:41], s[4:5], exec
	s_cselect_b32 s21, s27, s39
	s_cselect_b32 s86, s26, s38
	s_add_u32 s36, s36, 0x20080
	s_addc_u32 s37, s37, 0
	s_add_u32 s87, s38, 0x100
	s_addc_u32 s88, s39, 0
	s_mov_b32 s89, -2
	ds_read_b128 v[152:155], v149
	ds_read_b128 v[158:161], v149 offset:1024
	ds_read_b128 v[166:169], v149 offset:2048
	ds_read_b128 v[170:173], v149 offset:3072
	ds_read_b128 v[174:177], v150
	ds_read_b128 v[178:181], v150 offset:1024
	ds_read_b128 v[182:185], v150 offset:2048
	ds_read_b128 v[186:189], v150 offset:3072
	s_add_u32 s33, s36, 0xfffe0080
	s_addc_u32 s38, s37, -1
	s_cmp_eq_u32 s89, 4
	s_cselect_b32 s41, s23, s38
	s_cselect_b32 s40, s85, s33
	s_cselect_b32 s39, s21, s88
	s_cselect_b32 s38, s86, s87
	v_lshl_add_u64 v[222:223], s[36:37], 0, v[138:139]
	s_add_i32 m0, s29, 0xc000
	ds_read_b128 v[190:193], v151
	ds_read_b128 v[194:197], v151 offset:1024
	ds_read_b128 v[198:201], v151 offset:2048
	ds_read_b128 v[202:205], v151 offset:3072
	ds_read_b128 v[206:209], v151 offset:4096
	ds_read_b128 v[210:213], v151 offset:5120
	ds_read_b128 v[214:217], v151 offset:6144
	ds_read_b128 v[218:221], v151 offset:7168
	global_load_lds_dwordx4 v[222:223], off
	v_lshl_add_u64 v[222:223], s[36:37], 0, v[140:141]
	s_add_i32 m0, s29, 0xe000
	s_nop 0
	global_load_lds_dwordx4 v[222:223], off
	s_waitcnt vmcnt(8)
	s_waitcnt lgkmcnt(0)
	s_barrier
	s_setprio 1
	s_waitcnt lgkmcnt(0)
	v_mfma_f32_16x16x32_bf16 v[124:127], v[152:155], v[190:193], 0
	v_mfma_f32_16x16x32_bf16 v[120:123], v[166:169], v[190:193], 0
	v_mfma_f32_16x16x32_bf16 v[116:119], v[152:155], v[198:201], 0
	v_mfma_f32_16x16x32_bf16 v[108:111], v[166:169], v[198:201], 0
	v_mfma_f32_16x16x32_bf16 v[100:103], v[152:155], v[206:209], 0
	v_mfma_f32_16x16x32_bf16 v[92:95], v[166:169], v[206:209], 0
	v_mfma_f32_16x16x32_bf16 v[84:87], v[152:155], v[214:217], 0
	v_mfma_f32_16x16x32_bf16 v[76:79], v[166:169], v[214:217], 0
	v_mfma_f32_16x16x32_bf16 v[124:127], v[158:161], v[194:197], v[124:127]
	v_mfma_f32_16x16x32_bf16 v[120:123], v[170:173], v[194:197], v[120:123]
	v_mfma_f32_16x16x32_bf16 v[116:119], v[158:161], v[202:205], v[116:119]
	v_mfma_f32_16x16x32_bf16 v[108:111], v[170:173], v[202:205], v[108:111]
	v_mfma_f32_16x16x32_bf16 v[100:103], v[158:161], v[210:213], v[100:103]
	v_mfma_f32_16x16x32_bf16 v[92:95], v[170:173], v[210:213], v[92:95]
	v_mfma_f32_16x16x32_bf16 v[84:87], v[158:161], v[218:221], v[84:87]
	v_mfma_f32_16x16x32_bf16 v[76:79], v[170:173], v[218:221], v[76:79]
	s_setprio 0
	s_setprio 1
	v_mfma_f32_16x16x32_bf16 v[112:115], v[174:177], v[190:193], 0
	v_mfma_f32_16x16x32_bf16 v[104:107], v[182:185], v[190:193], 0
	v_mfma_f32_16x16x32_bf16 v[96:99], v[174:177], v[198:201], 0
	v_mfma_f32_16x16x32_bf16 v[88:91], v[182:185], v[198:201], 0
	v_mfma_f32_16x16x32_bf16 v[80:83], v[174:177], v[206:209], 0
	v_mfma_f32_16x16x32_bf16 v[72:75], v[182:185], v[206:209], 0
	v_mfma_f32_16x16x32_bf16 v[68:71], v[174:177], v[214:217], 0
	v_mfma_f32_16x16x32_bf16 v[64:67], v[182:185], v[214:217], 0
	v_mfma_f32_16x16x32_bf16 v[112:115], v[178:181], v[194:197], v[112:115]
	v_mfma_f32_16x16x32_bf16 v[104:107], v[186:189], v[194:197], v[104:107]
	v_mfma_f32_16x16x32_bf16 v[96:99], v[178:181], v[202:205], v[96:99]
	v_mfma_f32_16x16x32_bf16 v[88:91], v[186:189], v[202:205], v[88:91]
	v_mfma_f32_16x16x32_bf16 v[80:83], v[178:181], v[210:213], v[80:83]
	v_mfma_f32_16x16x32_bf16 v[72:75], v[186:189], v[210:213], v[72:75]
	v_mfma_f32_16x16x32_bf16 v[68:71], v[178:181], v[218:221], v[68:71]
	v_mfma_f32_16x16x32_bf16 v[64:67], v[186:189], v[218:221], v[64:67]
	s_setprio 0
	s_barrier
	s_add_i32 s33, s78, s61
	v_lshl_add_u64 v[222:223], s[38:39], 0, v[132:133]
	s_mov_b32 m0, s33
	ds_read_b128 v[190:193], v151 offset:16384
	ds_read_b128 v[194:197], v151 offset:17408
	ds_read_b128 v[198:201], v151 offset:18432
	ds_read_b128 v[202:205], v151 offset:19456
	ds_read_b128 v[206:209], v151 offset:20480
	ds_read_b128 v[210:213], v151 offset:21504
	ds_read_b128 v[214:217], v151 offset:22528
	ds_read_b128 v[218:221], v151 offset:23552
	global_load_lds_dwordx4 v[222:223], off
	s_add_i32 m0, s33, 0x2000
	s_add_u32 s90, s38, 0x20000
	v_lshl_add_u64 v[224:225], s[38:39], 0, v[136:137]
	s_addc_u32 s91, s39, 0
	s_add_i32 s33, s79, s61
	global_load_lds_dwordx4 v[224:225], off
	v_lshl_add_u64 v[226:227], s[90:91], 0, v[132:133]
	s_mov_b32 m0, s33
	v_lshl_add_u64 v[228:229], s[40:41], 0, v[134:135]
	global_load_lds_dwordx4 v[226:227], off
	v_lshl_add_u64 v[226:227], s[90:91], 0, v[136:137]
	s_add_i32 m0, s33, 0x2000
	s_nop 0
	global_load_lds_dwordx4 v[226:227], off
	v_lshl_add_u64 v[226:227], s[40:41], 0, v[130:131]
	s_mov_b32 m0, s29
	s_nop 0
	global_load_lds_dwordx4 v[226:227], off
	s_mov_b32 m0, s62
	s_nop 0
	global_load_lds_dwordx4 v[228:229], off
	s_waitcnt vmcnt(8)
	s_waitcnt lgkmcnt(0)
	s_barrier
; #define PG8_STAGE(bufoff, gbase, voff) do { _Pragma("unroll") for (int _i = 0; _i < 2; ++_i) \
;         __builtin_amdgcn_global_load_lds((const unsigned*)((const char*)(gbase) + (voff)[_i]), (LAS unsigned*)(lds + (bufoff) + ldsw + _i * 8192), 16, 0, 0); } while (0)
; #define PG8_LDA(dst, b, h) do { _Pragma("unroll") for (int m = 0; m < 4; ++m) _Pragma("unroll") for (int k = 0; k < 2; ++k) dst[m][k] = *(const LAS bf16x8*)(lds + PG8_SA(b, h) + aoff + m * 2048 + k * 1024); } while (0)
; #define PG8_LDB(dst, b, h) do { _Pragma("unroll") for (int n = 0; n < 2; ++n) _Pragma("unroll") for (int k = 0; k < 2; ++k) dst[n][k] = *(const LAS bf16x8*)(lds + PG8_SB(b, h) + boff + n * 2048 + k * 1024); } while (0)
; #define PG8_MMA(ai, bj, At, Bt) do { __builtin_amdgcn_s_setprio(1); _Pragma("unroll") for (int m = 0; m < 4; ++m) _Pragma("unroll") for (int n = 0; n < 2; ++n) _Pragma("unroll") for (int k = 0; k < 2; ++k) \
;         acc[ai][bj][m][n] = __builtin_amdgcn_mfma_f32_16x16x32_bf16(Bt[n][k], At[m][k], acc[ai][bj][m][n], 0, 0, 0); __builtin_amdgcn_s_setprio(0); } while (0)
; #define PG8_WAIT_V(n) asm volatile("s_waitcnt vmcnt(" #n ")" ::: "memory")
; #define PG8_WAIT_L(n) asm volatile("s_waitcnt lgkmcnt(" #n ")" ::: "memory")
; #define PG8_BAR __builtin_amdgcn_s_barrier()
; #define PG8_SCHED __builtin_amdgcn_sched_barrier(0)
; template <class Epi>
; __device__ __forceinline__ void gemm_phase(LAS unsigned char* lds, const Gemm g, const StaticOrder& S, const Epi& E) {
;     ...
;             PG8_WAIT_V(8); PG8_WAIT_L(0); PG8_BAR; PG8_MMA(1, 0, At, B0); PG8_MMA(1, 1, At, B1); PG8_BAR; PG8_SCHED;
;             PG8_LDB(B0, 1, 0); PG8_LDB(B1, 1, 1); PG8_SCHED; PG8_LDA(At, 1, 0); PG8_STAGE(PG8_SA(0, 1), a2 + hsA, voffA);
;             PG8_WAIT_V(8); PG8_WAIT_L(0); PG8_BAR; PG8_MMA(0, 0, At, B0); PG8_MMA(0, 1, At, B1); PG8_BAR; PG8_SCHED;
	s_setprio 1
	s_waitcnt lgkmcnt(0)
	v_mfma_f32_16x16x32_bf16 v[60:63], v[152:155], v[190:193], 0
	v_mfma_f32_16x16x32_bf16 v[56:59], v[166:169], v[190:193], 0
	v_mfma_f32_16x16x32_bf16 v[52:55], v[152:155], v[198:201], 0
	v_mfma_f32_16x16x32_bf16 v[44:47], v[166:169], v[198:201], 0
	v_mfma_f32_16x16x32_bf16 v[36:39], v[152:155], v[206:209], 0
	v_mfma_f32_16x16x32_bf16 v[28:31], v[166:169], v[206:209], 0
	v_mfma_f32_16x16x32_bf16 v[20:23], v[152:155], v[214:217], 0
	v_mfma_f32_16x16x32_bf16 v[12:15], v[166:169], v[214:217], 0
	v_mfma_f32_16x16x32_bf16 v[60:63], v[158:161], v[194:197], v[60:63]
	v_mfma_f32_16x16x32_bf16 v[56:59], v[170:173], v[194:197], v[56:59]
	v_mfma_f32_16x16x32_bf16 v[52:55], v[158:161], v[202:205], v[52:55]
	v_mfma_f32_16x16x32_bf16 v[44:47], v[170:173], v[202:205], v[44:47]
	v_mfma_f32_16x16x32_bf16 v[36:39], v[158:161], v[210:213], v[36:39]
	v_mfma_f32_16x16x32_bf16 v[28:31], v[170:173], v[210:213], v[28:31]
	v_mfma_f32_16x16x32_bf16 v[20:23], v[158:161], v[218:221], v[20:23]
	v_mfma_f32_16x16x32_bf16 v[12:15], v[170:173], v[218:221], v[12:15]
	s_setprio 0
	s_setprio 1
	v_mfma_f32_16x16x32_bf16 v[48:51], v[174:177], v[190:193], 0
	v_mfma_f32_16x16x32_bf16 v[40:43], v[182:185], v[190:193], 0
	v_mfma_f32_16x16x32_bf16 v[32:35], v[174:177], v[198:201], 0
	v_mfma_f32_16x16x32_bf16 v[24:27], v[182:185], v[198:201], 0
	v_mfma_f32_16x16x32_bf16 v[16:19], v[174:177], v[206:209], 0
	v_mfma_f32_16x16x32_bf16 v[8:11], v[182:185], v[206:209], 0
	v_mfma_f32_16x16x32_bf16 v[4:7], v[174:177], v[214:217], 0
	v_mfma_f32_16x16x32_bf16 v[0:3], v[182:185], v[214:217], 0
	v_mfma_f32_16x16x32_bf16 v[48:51], v[178:181], v[194:197], v[48:51]
	v_mfma_f32_16x16x32_bf16 v[40:43], v[186:189], v[194:197], v[40:43]
	v_mfma_f32_16x16x32_bf16 v[32:35], v[178:181], v[202:205], v[32:35]
	v_mfma_f32_16x16x32_bf16 v[24:27], v[186:189], v[202:205], v[24:27]
	v_mfma_f32_16x16x32_bf16 v[16:19], v[178:181], v[210:213], v[16:19]
	v_mfma_f32_16x16x32_bf16 v[8:11], v[186:189], v[210:213], v[8:11]
	v_mfma_f32_16x16x32_bf16 v[4:7], v[178:181], v[218:221], v[4:7]
	v_mfma_f32_16x16x32_bf16 v[0:3], v[186:189], v[218:221], v[0:3]
	s_setprio 0
	s_barrier
	s_add_i32 s33, 0, 0x18000
	v_add_u32_e32 v165, s33, v147
	s_add_i32 s90, 0, 0x1c000
	ds_read_b128 v[152:155], v165
	ds_read_b128 v[158:161], v165 offset:1024
	ds_read_b128 v[166:169], v165 offset:2048
	ds_read_b128 v[170:173], v165 offset:3072
	v_add_u32_e32 v165, s90, v147
	ds_read_b128 v[174:177], v165
	ds_read_b128 v[178:181], v165 offset:1024
	ds_read_b128 v[182:185], v165 offset:2048
	ds_read_b128 v[186:189], v165 offset:3072
	s_add_u32 s40, s40, 0x20000
	s_addc_u32 s41, s41, 0
	s_mov_b32 m0, s63
	v_lshl_add_u64 v[230:231], s[40:41], 0, v[130:131]
	ds_read_b128 v[190:193], v151 offset:32768
	ds_read_b128 v[194:197], v151 offset:33792
	ds_read_b128 v[198:201], v151 offset:34816
	ds_read_b128 v[202:205], v151 offset:35840
	ds_read_b128 v[206:209], v151 offset:36864
	ds_read_b128 v[210:213], v151 offset:37888
	ds_read_b128 v[214:217], v151 offset:38912
	ds_read_b128 v[218:221], v151 offset:39936
	global_load_lds_dwordx4 v[230:231], off
	v_lshl_add_u64 v[230:231], s[40:41], 0, v[134:135]
	s_mov_b32 m0, s64
	s_nop 0
	global_load_lds_dwordx4 v[230:231], off
	s_waitcnt vmcnt(8)
	s_waitcnt lgkmcnt(0)
	s_barrier
	s_setprio 1
	s_waitcnt lgkmcnt(0)
	v_mfma_f32_16x16x32_bf16 v[124:127], v[152:155], v[190:193], v[124:127]
	v_mfma_f32_16x16x32_bf16 v[120:123], v[166:169], v[190:193], v[120:123]
	v_mfma_f32_16x16x32_bf16 v[116:119], v[152:155], v[198:201], v[116:119]
	v_mfma_f32_16x16x32_bf16 v[108:111], v[166:169], v[198:201], v[108:111]
	v_mfma_f32_16x16x32_bf16 v[100:103], v[152:155], v[206:209], v[100:103]
	v_mfma_f32_16x16x32_bf16 v[92:95], v[166:169], v[206:209], v[92:95]
	v_mfma_f32_16x16x32_bf16 v[84:87], v[152:155], v[214:217], v[84:87]
	v_mfma_f32_16x16x32_bf16 v[76:79], v[166:169], v[214:217], v[76:79]
	v_mfma_f32_16x16x32_bf16 v[124:127], v[158:161], v[194:197], v[124:127]
	v_mfma_f32_16x16x32_bf16 v[120:123], v[170:173], v[194:197], v[120:123]
	v_mfma_f32_16x16x32_bf16 v[116:119], v[158:161], v[202:205], v[116:119]
	v_mfma_f32_16x16x32_bf16 v[108:111], v[170:173], v[202:205], v[108:111]
	v_mfma_f32_16x16x32_bf16 v[100:103], v[158:161], v[210:213], v[100:103]
	v_mfma_f32_16x16x32_bf16 v[92:95], v[170:173], v[210:213], v[92:95]
	v_mfma_f32_16x16x32_bf16 v[84:87], v[158:161], v[218:221], v[84:87]
	v_mfma_f32_16x16x32_bf16 v[76:79], v[170:173], v[218:221], v[76:79]
	s_setprio 0
	s_setprio 1
	v_mfma_f32_16x16x32_bf16 v[112:115], v[174:177], v[190:193], v[112:115]
	v_mfma_f32_16x16x32_bf16 v[104:107], v[182:185], v[190:193], v[104:107]
	v_mfma_f32_16x16x32_bf16 v[96:99], v[174:177], v[198:201], v[96:99]
	v_mfma_f32_16x16x32_bf16 v[88:91], v[182:185], v[198:201], v[88:91]
	v_mfma_f32_16x16x32_bf16 v[80:83], v[174:177], v[206:209], v[80:83]
	v_mfma_f32_16x16x32_bf16 v[72:75], v[182:185], v[206:209], v[72:75]
	v_mfma_f32_16x16x32_bf16 v[68:71], v[174:177], v[214:217], v[68:71]
	v_mfma_f32_16x16x32_bf16 v[64:67], v[182:185], v[214:217], v[64:67]
	v_mfma_f32_16x16x32_bf16 v[112:115], v[178:181], v[194:197], v[112:115]
	v_mfma_f32_16x16x32_bf16 v[104:107], v[186:189], v[194:197], v[104:107]
	v_mfma_f32_16x16x32_bf16 v[96:99], v[178:181], v[202:205], v[96:99]
	v_mfma_f32_16x16x32_bf16 v[88:91], v[186:189], v[202:205], v[88:91]
	v_mfma_f32_16x16x32_bf16 v[80:83], v[178:181], v[210:213], v[80:83]
	v_mfma_f32_16x16x32_bf16 v[72:75], v[186:189], v[210:213], v[72:75]
	v_mfma_f32_16x16x32_bf16 v[68:71], v[178:181], v[218:221], v[68:71]
	v_mfma_f32_16x16x32_bf16 v[64:67], v[186:189], v[218:221], v[64:67]
	s_setprio 0
	s_barrier
; #define PG8_STAGE(bufoff, gbase, voff) do { _Pragma("unroll") for (int _i = 0; _i < 2; ++_i) \
;         __builtin_amdgcn_global_load_lds((const unsigned*)((const char*)(gbase) + (voff)[_i]), (LAS unsigned*)(lds + (bufoff) + ldsw + _i * 8192), 16, 0, 0); } while (0)
; #define PG8_LDA(dst, b, h) do { _Pragma("unroll") for (int m = 0; m < 4; ++m) _Pragma("unroll") for (int k = 0; k < 2; ++k) dst[m][k] = *(const LAS bf16x8*)(lds + PG8_SA(b, h) + aoff + m * 2048 + k * 1024); } while (0)
; #define PG8_MMA(ai, bj, At, Bt) do { __builtin_amdgcn_s_setprio(1); _Pragma("unroll") for (int m = 0; m < 4; ++m) _Pragma("unroll") for (int n = 0; n < 2; ++n) _Pragma("unroll") for (int k = 0; k < 2; ++k) \
;         acc[ai][bj][m][n] = __builtin_amdgcn_mfma_f32_16x16x32_bf16(Bt[n][k], At[m][k], acc[ai][bj][m][n], 0, 0, 0); __builtin_amdgcn_s_setprio(0); } while (0)
; #define PG8_WAIT_V(n) asm volatile("s_waitcnt vmcnt(" #n ")" ::: "memory")
; #define PG8_WAIT_L(n) asm volatile("s_waitcnt lgkmcnt(" #n ")" ::: "memory")
; #define PG8_BAR __builtin_amdgcn_s_barrier()
; #define PG8_SCHED __builtin_amdgcn_sched_barrier(0)
; template <class Epi>
; __device__ __forceinline__ void gemm_phase(LAS unsigned char* lds, const Gemm g, const StaticOrder& S, const Epi& E) {
;     ...
;             PG8_LDA(At, 1, 1); PG8_STAGE(PG8_SB(1, 0), b3, voffB); PG8_STAGE(PG8_SB(1, 1), b3 + hsB, voffB); PG8_STAGE(PG8_SA(1, 0), a3, voffA);
;             PG8_WAIT_V(8); PG8_WAIT_L(0); PG8_BAR; PG8_MMA(1, 0, At, B0); PG8_MMA(1, 1, At, B1); PG8_BAR; PG8_SCHED;
;         }
	s_add_i32 s33, s33, s61
	v_lshl_add_u64 v[222:223], v[222:223], 0, s[10:11]
	s_mov_b32 m0, s33
	ds_read_b128 v[190:193], v151 offset:49152
	ds_read_b128 v[194:197], v151 offset:50176
	ds_read_b128 v[198:201], v151 offset:51200
	ds_read_b128 v[202:205], v151 offset:52224
	ds_read_b128 v[206:209], v151 offset:53248
	ds_read_b128 v[210:213], v151 offset:54272
	ds_read_b128 v[214:217], v151 offset:55296
	ds_read_b128 v[218:221], v151 offset:56320
	global_load_lds_dwordx4 v[222:223], off
	s_add_i32 m0, s33, 0x2000
	s_add_u32 s38, s38, 0x20080
	v_lshl_add_u64 v[222:223], v[224:225], 0, s[10:11]
	s_addc_u32 s39, s39, 0
	s_add_i32 s33, s90, s61
	global_load_lds_dwordx4 v[222:223], off
	v_lshl_add_u64 v[222:223], s[38:39], 0, v[132:133]
	s_mov_b32 m0, s33
	s_nop 0
	global_load_lds_dwordx4 v[222:223], off
	v_lshl_add_u64 v[222:223], s[38:39], 0, v[136:137]
	s_add_i32 m0, s33, 0x2000
	s_nop 0
	global_load_lds_dwordx4 v[222:223], off
	v_lshl_add_u64 v[222:223], v[226:227], 0, s[10:11]
	s_mov_b32 m0, s66
	s_nop 0
	global_load_lds_dwordx4 v[222:223], off
	v_lshl_add_u64 v[222:223], v[228:229], 0, s[10:11]
	s_mov_b32 m0, s67
	s_nop 0
	global_load_lds_dwordx4 v[222:223], off
	s_waitcnt vmcnt(8)
	s_waitcnt lgkmcnt(0)
	s_barrier
	s_setprio 1
	s_waitcnt lgkmcnt(0)
	v_mfma_f32_16x16x32_bf16 v[60:63], v[152:155], v[190:193], v[60:63]
	v_mfma_f32_16x16x32_bf16 v[56:59], v[166:169], v[190:193], v[56:59]
	v_mfma_f32_16x16x32_bf16 v[52:55], v[152:155], v[198:201], v[52:55]
	v_mfma_f32_16x16x32_bf16 v[44:47], v[166:169], v[198:201], v[44:47]
	v_mfma_f32_16x16x32_bf16 v[36:39], v[152:155], v[206:209], v[36:39]
	v_mfma_f32_16x16x32_bf16 v[28:31], v[166:169], v[206:209], v[28:31]
	v_mfma_f32_16x16x32_bf16 v[20:23], v[152:155], v[214:217], v[20:23]
	v_mfma_f32_16x16x32_bf16 v[12:15], v[166:169], v[214:217], v[12:15]
	v_mfma_f32_16x16x32_bf16 v[60:63], v[158:161], v[194:197], v[60:63]
	v_mfma_f32_16x16x32_bf16 v[56:59], v[170:173], v[194:197], v[56:59]
	v_mfma_f32_16x16x32_bf16 v[52:55], v[158:161], v[202:205], v[52:55]
	v_mfma_f32_16x16x32_bf16 v[44:47], v[170:173], v[202:205], v[44:47]
	v_mfma_f32_16x16x32_bf16 v[36:39], v[158:161], v[210:213], v[36:39]
	v_mfma_f32_16x16x32_bf16 v[28:31], v[170:173], v[210:213], v[28:31]
	v_mfma_f32_16x16x32_bf16 v[20:23], v[158:161], v[218:221], v[20:23]
	v_mfma_f32_16x16x32_bf16 v[12:15], v[170:173], v[218:221], v[12:15]
	s_setprio 0
	s_setprio 1
	v_mfma_f32_16x16x32_bf16 v[48:51], v[174:177], v[190:193], v[48:51]
	v_mfma_f32_16x16x32_bf16 v[40:43], v[182:185], v[190:193], v[40:43]
	v_mfma_f32_16x16x32_bf16 v[32:35], v[174:177], v[198:201], v[32:35]
	v_mfma_f32_16x16x32_bf16 v[24:27], v[182:185], v[198:201], v[24:27]
	v_mfma_f32_16x16x32_bf16 v[16:19], v[174:177], v[206:209], v[16:19]
	v_mfma_f32_16x16x32_bf16 v[8:11], v[182:185], v[206:209], v[8:11]
	v_mfma_f32_16x16x32_bf16 v[4:7], v[174:177], v[214:217], v[4:7]
	v_mfma_f32_16x16x32_bf16 v[0:3], v[182:185], v[214:217], v[0:3]
	v_mfma_f32_16x16x32_bf16 v[48:51], v[178:181], v[194:197], v[48:51]
	v_mfma_f32_16x16x32_bf16 v[40:43], v[186:189], v[194:197], v[40:43]
	v_mfma_f32_16x16x32_bf16 v[32:35], v[178:181], v[202:205], v[32:35]
	v_mfma_f32_16x16x32_bf16 v[24:27], v[186:189], v[202:205], v[24:27]
	v_mfma_f32_16x16x32_bf16 v[16:19], v[178:181], v[210:213], v[16:19]
	v_mfma_f32_16x16x32_bf16 v[8:11], v[186:189], v[210:213], v[8:11]
	v_mfma_f32_16x16x32_bf16 v[4:7], v[178:181], v[218:221], v[4:7]
	v_mfma_f32_16x16x32_bf16 v[0:3], v[186:189], v[218:221], v[0:3]
	s_setprio 0
	s_barrier
	s_add_i32 s89, s89, 2
	s_add_u32 s36, s36, 0x100
	s_addc_u32 s37, s37, 0
	s_add_u32 s87, s87, 0x100
	s_addc_u32 s88, s88, 0
	s_cmp_gt_u32 s89, 5
	s_cbranch_scc0 .LBB0_594
	s_branch .Lpeel_exit3

; #define PG8_STAGE(bufoff, gbase, voff) do { _Pragma("unroll") for (int _i = 0; _i < 2; ++_i) \
;         __builtin_amdgcn_global_load_lds((const unsigned*)((const char*)(gbase) + (voff)[_i]), (LAS unsigned*)(lds + (bufoff) + ldsw + _i * 8192), 16, 0, 0); } while (0)
; #define PG8_LDA(dst, b, h) do { _Pragma("unroll") for (int m = 0; m < 4; ++m) _Pragma("unroll") for (int k = 0; k < 2; ++k) dst[m][k] = *(const LAS bf16x8*)(lds + PG8_SA(b, h) + aoff + m * 2048 + k * 1024); } while (0)
; #define PG8_LDB(dst, b, h) do { _Pragma("unroll") for (int n = 0; n < 2; ++n) _Pragma("unroll") for (int k = 0; k < 2; ++k) dst[n][k] = *(const LAS bf16x8*)(lds + PG8_SB(b, h) + boff + n * 2048 + k * 1024); } while (0)
; #define PG8_WAIT_V(n) asm volatile("s_waitcnt vmcnt(" #n ")" ::: "memory")
; #define PG8_WAIT_L(n) asm volatile("s_waitcnt lgkmcnt(" #n ")" ::: "memory")
; template <class Epi>
; __device__ __forceinline__ void gemm_phase(LAS unsigned char* lds, const Gemm g, const StaticOrder& S, const Epi& E) {
;     ...
;         const bool has_next = S.next(ui + 1, nxt);
;         const char* nA = has_next ? (const char*)g.A + (size_t)nxt.pm * tsA : cA; const char* nB = has_next ? (const char*)g.Bt + (size_t)nxt.pn * tsB : cB;
;         for (int t = 0; t < nt; t += 2) {
;             const bool last = (t == nt - 2);
;             const char* a1 = cA + (size_t)(t + 1) * kstep;
;             const char* a2 = last ? nA : cA + (size_t)(t + 2) * kstep; const char* b2 = last ? nB : cB + (size_t)(t + 2) * kstep;
;             const char* a3 = a2 + kstep; const char* b3 = b2 + kstep;
;             PG8_LDB(B0, 0, 0); PG8_LDB(B1, 0, 1); PG8_SCHED; PG8_LDA(At, 0, 0); PG8_STAGE(PG8_SA(1, 1), a1 + hsA, voffA);
;             PG8_WAIT_V(8); PG8_WAIT_L(0); PG8_BAR; PG8_MMA(0, 0, At, B0); PG8_MMA(0, 1, At, B1); PG8_BAR; PG8_SCHED;
;             PG8_LDA(At, 0, 1); PG8_STAGE(PG8_SB(0, 0), b2, voffB); PG8_STAGE(PG8_SB(0, 1), b2 + hsB, voffB); PG8_STAGE(PG8_SA(0, 0), a2, voffA);
;             PG8_WAIT_V(8); PG8_WAIT_L(0); PG8_BAR; PG8_MMA(1, 0, At, B0); PG8_MMA(1, 1, At, B1); PG8_BAR; PG8_SCHED;
;     ...
;         for (int a = 0; a < 2; ++a)
; #pragma unroll
;             for (int b = 0; b < 2; ++b)
; #pragma unroll
;                 for (int m = 0; m < 4; ++m)
; #pragma unroll
;                     for (int n = 0; n < 2; ++n) acc[a][b][m][n] = (f32x4){0.f, 0.f, 0.f, 0.f};
.LBB0_1369:
	s_ashr_i32 s15, s14, 31
	s_lshl_b64 s[18:19], s[14:15], 18
	s_add_u32 s18, s27, s18
	s_addc_u32 s19, s28, s19
	s_and_b64 s[6:7], s[6:7], exec
	s_cselect_b32 s15, s19, s23
	s_cselect_b32 s58, s18, s22
	s_add_u32 s59, s22, 0x100
	s_addc_u32 s60, s23, 0
	s_mov_b32 s61, -2
	s_add_u32 s6, s20, 0x100
	s_addc_u32 s7, s21, 0
	s_cmp_eq_u32 s61, 4
	s_cselect_b32 s25, s17, s7
	s_cselect_b32 s24, s16, s6
	s_cselect_b32 s23, s15, s60
	s_cselect_b32 s22, s58, s59
	s_add_i32 s33, 0, 0x14000
	v_add_u32_e32 v159, s33, v153
	ds_read_b128 v[144:147], v155
	ds_read_b128 v[148:151], v155 offset:1024
	ds_read_b128 v[160:163], v155 offset:2048
	ds_read_b128 v[164:167], v155 offset:3072
	ds_read_b128 v[168:171], v159
	ds_read_b128 v[172:175], v159 offset:1024
	ds_read_b128 v[176:179], v159 offset:2048
	ds_read_b128 v[180:183], v159 offset:3072
	v_lshl_add_u64 v[216:217], s[20:21], 0, v[136:137]
	s_add_i32 m0, s36, 0xc000
	ds_read_b128 v[184:187], v158
	ds_read_b128 v[188:191], v158 offset:1024
	ds_read_b128 v[192:195], v158 offset:2048
	ds_read_b128 v[196:199], v158 offset:3072
	ds_read_b128 v[200:203], v158 offset:4096
	ds_read_b128 v[204:207], v158 offset:5120
	ds_read_b128 v[208:211], v158 offset:6144
	ds_read_b128 v[212:215], v158 offset:7168
	global_load_lds_dwordx4 v[216:217], off
	v_lshl_add_u64 v[216:217], s[20:21], 0, v[138:139]
	s_add_i32 m0, s36, 0xe000
	s_nop 0
	global_load_lds_dwordx4 v[216:217], off
	s_waitcnt vmcnt(8)
	s_waitcnt lgkmcnt(0)
	s_barrier
	s_setprio 1
	s_waitcnt lgkmcnt(0)
	v_mfma_f32_16x16x32_bf16 v[124:127], v[144:147], v[184:187], 0
	v_mfma_f32_16x16x32_bf16 v[120:123], v[160:163], v[184:187], 0
	v_mfma_f32_16x16x32_bf16 v[108:111], v[144:147], v[192:195], 0
	v_mfma_f32_16x16x32_bf16 v[104:107], v[160:163], v[192:195], 0
	v_mfma_f32_16x16x32_bf16 v[92:95], v[144:147], v[200:203], 0
	v_mfma_f32_16x16x32_bf16 v[88:91], v[160:163], v[200:203], 0
	v_mfma_f32_16x16x32_bf16 v[76:79], v[144:147], v[208:211], 0
	v_mfma_f32_16x16x32_bf16 v[72:75], v[160:163], v[208:211], 0
	v_mfma_f32_16x16x32_bf16 v[124:127], v[148:151], v[188:191], v[124:127]
	v_mfma_f32_16x16x32_bf16 v[120:123], v[164:167], v[188:191], v[120:123]
	v_mfma_f32_16x16x32_bf16 v[108:111], v[148:151], v[196:199], v[108:111]
	v_mfma_f32_16x16x32_bf16 v[104:107], v[164:167], v[196:199], v[104:107]
	v_mfma_f32_16x16x32_bf16 v[92:95], v[148:151], v[204:207], v[92:95]
	v_mfma_f32_16x16x32_bf16 v[88:91], v[164:167], v[204:207], v[88:91]
	v_mfma_f32_16x16x32_bf16 v[76:79], v[148:151], v[212:215], v[76:79]
	v_mfma_f32_16x16x32_bf16 v[72:75], v[164:167], v[212:215], v[72:75]
	s_setprio 0
	s_setprio 1
	v_mfma_f32_16x16x32_bf16 v[116:119], v[168:171], v[184:187], 0
	v_mfma_f32_16x16x32_bf16 v[112:115], v[176:179], v[184:187], 0
	v_mfma_f32_16x16x32_bf16 v[100:103], v[168:171], v[192:195], 0
	v_mfma_f32_16x16x32_bf16 v[96:99], v[176:179], v[192:195], 0
	v_mfma_f32_16x16x32_bf16 v[84:87], v[168:171], v[200:203], 0
	v_mfma_f32_16x16x32_bf16 v[80:83], v[176:179], v[200:203], 0
	v_mfma_f32_16x16x32_bf16 v[68:71], v[168:171], v[208:211], 0
	v_mfma_f32_16x16x32_bf16 v[64:67], v[176:179], v[208:211], 0
	v_mfma_f32_16x16x32_bf16 v[116:119], v[172:175], v[188:191], v[116:119]
	v_mfma_f32_16x16x32_bf16 v[112:115], v[180:183], v[188:191], v[112:115]
	v_mfma_f32_16x16x32_bf16 v[100:103], v[172:175], v[196:199], v[100:103]
	v_mfma_f32_16x16x32_bf16 v[96:99], v[180:183], v[196:199], v[96:99]
	v_mfma_f32_16x16x32_bf16 v[84:87], v[172:175], v[204:207], v[84:87]
	v_mfma_f32_16x16x32_bf16 v[80:83], v[180:183], v[204:207], v[80:83]
	v_mfma_f32_16x16x32_bf16 v[68:71], v[172:175], v[212:215], v[68:71]
	v_mfma_f32_16x16x32_bf16 v[64:67], v[180:183], v[212:215], v[64:67]
	s_setprio 0
	s_barrier
	s_add_i32 s20, s49, s29
	v_lshl_add_u64 v[216:217], s[22:23], 0, v[130:131]
	s_mov_b32 m0, s20
	ds_read_b128 v[184:187], v158 offset:16384
	ds_read_b128 v[188:191], v158 offset:17408
	ds_read_b128 v[192:195], v158 offset:18432
	ds_read_b128 v[196:199], v158 offset:19456
	ds_read_b128 v[200:203], v158 offset:20480
	ds_read_b128 v[204:207], v158 offset:21504
	ds_read_b128 v[208:211], v158 offset:22528
	ds_read_b128 v[212:215], v158 offset:23552
	global_load_lds_dwordx4 v[216:217], off
	s_add_i32 m0, s20, 0x2000
	s_add_u32 s20, s22, 0x20000
	v_lshl_add_u64 v[218:219], s[22:23], 0, v[134:135]
	s_addc_u32 s21, s23, 0
	s_add_i32 s33, s33, s29
	global_load_lds_dwordx4 v[218:219], off
	v_lshl_add_u64 v[220:221], s[20:21], 0, v[130:131]
	s_mov_b32 m0, s33
	v_lshl_add_u64 v[222:223], s[24:25], 0, v[132:133]
	global_load_lds_dwordx4 v[220:221], off
	v_lshl_add_u64 v[220:221], s[20:21], 0, v[134:135]
	s_add_i32 m0, s33, 0x2000
	s_nop 0
	global_load_lds_dwordx4 v[220:221], off
	v_lshl_add_u64 v[220:221], s[24:25], 0, v[128:129]
	s_mov_b32 m0, s36
	s_nop 0
	global_load_lds_dwordx4 v[220:221], off
	s_mov_b32 m0, s37
	s_nop 0
	global_load_lds_dwordx4 v[222:223], off
	s_waitcnt vmcnt(8)
	s_waitcnt lgkmcnt(0)
	s_barrier
; #define PG8_STAGE(bufoff, gbase, voff) do { _Pragma("unroll") for (int _i = 0; _i < 2; ++_i) \
;         __builtin_amdgcn_global_load_lds((const unsigned*)((const char*)(gbase) + (voff)[_i]), (LAS unsigned*)(lds + (bufoff) + ldsw + _i * 8192), 16, 0, 0); } while (0)
; #define PG8_LDA(dst, b, h) do { _Pragma("unroll") for (int m = 0; m < 4; ++m) _Pragma("unroll") for (int k = 0; k < 2; ++k) dst[m][k] = *(const LAS bf16x8*)(lds + PG8_SA(b, h) + aoff + m * 2048 + k * 1024); } while (0)
; #define PG8_LDB(dst, b, h) do { _Pragma("unroll") for (int n = 0; n < 2; ++n) _Pragma("unroll") for (int k = 0; k < 2; ++k) dst[n][k] = *(const LAS bf16x8*)(lds + PG8_SB(b, h) + boff + n * 2048 + k * 1024); } while (0)
; #define PG8_MMA(ai, bj, At, Bt) do { __builtin_amdgcn_s_setprio(1); _Pragma("unroll") for (int m = 0; m < 4; ++m) _Pragma("unroll") for (int n = 0; n < 2; ++n) _Pragma("unroll") for (int k = 0; k < 2; ++k) \
;         acc[ai][bj][m][n] = __builtin_amdgcn_mfma_f32_16x16x32_bf16(Bt[n][k], At[m][k], acc[ai][bj][m][n], 0, 0, 0); __builtin_amdgcn_s_setprio(0); } while (0)
; #define PG8_WAIT_V(n) asm volatile("s_waitcnt vmcnt(" #n ")" ::: "memory")
; #define PG8_WAIT_L(n) asm volatile("s_waitcnt lgkmcnt(" #n ")" ::: "memory")
; #define PG8_BAR __builtin_amdgcn_s_barrier()
; #define PG8_SCHED __builtin_amdgcn_sched_barrier(0)
; template <class Epi>
; __device__ __forceinline__ void gemm_phase(LAS unsigned char* lds, const Gemm g, const StaticOrder& S, const Epi& E) {
;     ...
;             PG8_WAIT_V(8); PG8_WAIT_L(0); PG8_BAR; PG8_MMA(1, 0, At, B0); PG8_MMA(1, 1, At, B1); PG8_BAR; PG8_SCHED;
;             PG8_LDB(B0, 1, 0); PG8_LDB(B1, 1, 1); PG8_SCHED; PG8_LDA(At, 1, 0); PG8_STAGE(PG8_SA(0, 1), a2 + hsA, voffA);
;             PG8_WAIT_V(8); PG8_WAIT_L(0); PG8_BAR; PG8_MMA(0, 0, At, B0); PG8_MMA(0, 1, At, B1); PG8_BAR; PG8_SCHED;
	s_setprio 1
	s_waitcnt lgkmcnt(0)
	v_mfma_f32_16x16x32_bf16 v[60:63], v[144:147], v[184:187], 0
	v_mfma_f32_16x16x32_bf16 v[56:59], v[160:163], v[184:187], 0
	v_mfma_f32_16x16x32_bf16 v[44:47], v[144:147], v[192:195], 0
	v_mfma_f32_16x16x32_bf16 v[40:43], v[160:163], v[192:195], 0
	v_mfma_f32_16x16x32_bf16 v[28:31], v[144:147], v[200:203], 0
	v_mfma_f32_16x16x32_bf16 v[24:27], v[160:163], v[200:203], 0
	v_mfma_f32_16x16x32_bf16 v[12:15], v[144:147], v[208:211], 0
	v_mfma_f32_16x16x32_bf16 v[8:11], v[160:163], v[208:211], 0
	v_mfma_f32_16x16x32_bf16 v[60:63], v[148:151], v[188:191], v[60:63]
	v_mfma_f32_16x16x32_bf16 v[56:59], v[164:167], v[188:191], v[56:59]
	v_mfma_f32_16x16x32_bf16 v[44:47], v[148:151], v[196:199], v[44:47]
	v_mfma_f32_16x16x32_bf16 v[40:43], v[164:167], v[196:199], v[40:43]
	v_mfma_f32_16x16x32_bf16 v[28:31], v[148:151], v[204:207], v[28:31]
	v_mfma_f32_16x16x32_bf16 v[24:27], v[164:167], v[204:207], v[24:27]
	v_mfma_f32_16x16x32_bf16 v[12:15], v[148:151], v[212:215], v[12:15]
	v_mfma_f32_16x16x32_bf16 v[8:11], v[164:167], v[212:215], v[8:11]
	s_setprio 0
	s_setprio 1
	v_mfma_f32_16x16x32_bf16 v[52:55], v[168:171], v[184:187], 0
	v_mfma_f32_16x16x32_bf16 v[48:51], v[176:179], v[184:187], 0
	v_mfma_f32_16x16x32_bf16 v[36:39], v[168:171], v[192:195], 0
	v_mfma_f32_16x16x32_bf16 v[32:35], v[176:179], v[192:195], 0
	v_mfma_f32_16x16x32_bf16 v[20:23], v[168:171], v[200:203], 0
	v_mfma_f32_16x16x32_bf16 v[16:19], v[176:179], v[200:203], 0
	v_mfma_f32_16x16x32_bf16 v[4:7], v[168:171], v[208:211], 0
	v_mfma_f32_16x16x32_bf16 v[0:3], v[176:179], v[208:211], 0
	v_mfma_f32_16x16x32_bf16 v[52:55], v[172:175], v[188:191], v[52:55]
	v_mfma_f32_16x16x32_bf16 v[48:51], v[180:183], v[188:191], v[48:51]
	v_mfma_f32_16x16x32_bf16 v[36:39], v[172:175], v[196:199], v[36:39]
	v_mfma_f32_16x16x32_bf16 v[32:35], v[180:183], v[196:199], v[32:35]
	v_mfma_f32_16x16x32_bf16 v[20:23], v[172:175], v[204:207], v[20:23]
	v_mfma_f32_16x16x32_bf16 v[16:19], v[180:183], v[204:207], v[16:19]
	v_mfma_f32_16x16x32_bf16 v[4:7], v[172:175], v[212:215], v[4:7]
	v_mfma_f32_16x16x32_bf16 v[0:3], v[180:183], v[212:215], v[0:3]
	s_setprio 0
	s_barrier
	s_add_i32 s33, 0, 0x18000
	v_add_u32_e32 v159, s33, v153
	s_add_i32 s62, 0, 0x1c000
	ds_read_b128 v[144:147], v159
	ds_read_b128 v[148:151], v159 offset:1024
	ds_read_b128 v[160:163], v159 offset:2048
	ds_read_b128 v[164:167], v159 offset:3072
	v_add_u32_e32 v159, s62, v153
	ds_read_b128 v[168:171], v159
	ds_read_b128 v[172:175], v159 offset:1024
	ds_read_b128 v[176:179], v159 offset:2048
	ds_read_b128 v[180:183], v159 offset:3072
	s_add_u32 s20, s24, 0x140000
	s_addc_u32 s21, s25, 0
	s_mov_b32 m0, s38
	v_lshl_add_u64 v[224:225], s[20:21], 0, v[128:129]
	ds_read_b128 v[184:187], v158 offset:32768
	ds_read_b128 v[188:191], v158 offset:33792
	ds_read_b128 v[192:195], v158 offset:34816
	ds_read_b128 v[196:199], v158 offset:35840
	ds_read_b128 v[200:203], v158 offset:36864
	ds_read_b128 v[204:207], v158 offset:37888
	ds_read_b128 v[208:211], v158 offset:38912
	ds_read_b128 v[212:215], v158 offset:39936
	global_load_lds_dwordx4 v[224:225], off
	v_lshl_add_u64 v[224:225], s[20:21], 0, v[132:133]
	s_mov_b32 m0, s39
	s_nop 0
	global_load_lds_dwordx4 v[224:225], off
	s_waitcnt vmcnt(8)
	s_waitcnt lgkmcnt(0)
	s_barrier
	s_setprio 1
	s_waitcnt lgkmcnt(0)
	v_mfma_f32_16x16x32_bf16 v[124:127], v[144:147], v[184:187], v[124:127]
	v_mfma_f32_16x16x32_bf16 v[120:123], v[160:163], v[184:187], v[120:123]
	v_mfma_f32_16x16x32_bf16 v[108:111], v[144:147], v[192:195], v[108:111]
	v_mfma_f32_16x16x32_bf16 v[104:107], v[160:163], v[192:195], v[104:107]
	v_mfma_f32_16x16x32_bf16 v[92:95], v[144:147], v[200:203], v[92:95]
	v_mfma_f32_16x16x32_bf16 v[88:91], v[160:163], v[200:203], v[88:91]
	v_mfma_f32_16x16x32_bf16 v[76:79], v[144:147], v[208:211], v[76:79]
	v_mfma_f32_16x16x32_bf16 v[72:75], v[160:163], v[208:211], v[72:75]
	v_mfma_f32_16x16x32_bf16 v[124:127], v[148:151], v[188:191], v[124:127]
	v_mfma_f32_16x16x32_bf16 v[120:123], v[164:167], v[188:191], v[120:123]
	v_mfma_f32_16x16x32_bf16 v[108:111], v[148:151], v[196:199], v[108:111]
	v_mfma_f32_16x16x32_bf16 v[104:107], v[164:167], v[196:199], v[104:107]
	v_mfma_f32_16x16x32_bf16 v[92:95], v[148:151], v[204:207], v[92:95]
	v_mfma_f32_16x16x32_bf16 v[88:91], v[164:167], v[204:207], v[88:91]
	v_mfma_f32_16x16x32_bf16 v[76:79], v[148:151], v[212:215], v[76:79]
	v_mfma_f32_16x16x32_bf16 v[72:75], v[164:167], v[212:215], v[72:75]
	s_setprio 0
	s_setprio 1
	v_mfma_f32_16x16x32_bf16 v[116:119], v[168:171], v[184:187], v[116:119]
	v_mfma_f32_16x16x32_bf16 v[112:115], v[176:179], v[184:187], v[112:115]
	v_mfma_f32_16x16x32_bf16 v[100:103], v[168:171], v[192:195], v[100:103]
	v_mfma_f32_16x16x32_bf16 v[96:99], v[176:179], v[192:195], v[96:99]
	v_mfma_f32_16x16x32_bf16 v[84:87], v[168:171], v[200:203], v[84:87]
	v_mfma_f32_16x16x32_bf16 v[80:83], v[176:179], v[200:203], v[80:83]
	v_mfma_f32_16x16x32_bf16 v[68:71], v[168:171], v[208:211], v[68:71]
	v_mfma_f32_16x16x32_bf16 v[64:67], v[176:179], v[208:211], v[64:67]
	v_mfma_f32_16x16x32_bf16 v[116:119], v[172:175], v[188:191], v[116:119]
	v_mfma_f32_16x16x32_bf16 v[112:115], v[180:183], v[188:191], v[112:115]
	v_mfma_f32_16x16x32_bf16 v[100:103], v[172:175], v[196:199], v[100:103]
	v_mfma_f32_16x16x32_bf16 v[96:99], v[180:183], v[196:199], v[96:99]
	v_mfma_f32_16x16x32_bf16 v[84:87], v[172:175], v[204:207], v[84:87]
	v_mfma_f32_16x16x32_bf16 v[80:83], v[180:183], v[204:207], v[80:83]
	v_mfma_f32_16x16x32_bf16 v[68:71], v[172:175], v[212:215], v[68:71]
	v_mfma_f32_16x16x32_bf16 v[64:67], v[180:183], v[212:215], v[64:67]
	s_setprio 0
	s_barrier
; #define PG8_STAGE(bufoff, gbase, voff) do { _Pragma("unroll") for (int _i = 0; _i < 2; ++_i) \
;         __builtin_amdgcn_global_load_lds((const unsigned*)((const char*)(gbase) + (voff)[_i]), (LAS unsigned*)(lds + (bufoff) + ldsw + _i * 8192), 16, 0, 0); } while (0)
; #define PG8_LDA(dst, b, h) do { _Pragma("unroll") for (int m = 0; m < 4; ++m) _Pragma("unroll") for (int k = 0; k < 2; ++k) dst[m][k] = *(const LAS bf16x8*)(lds + PG8_SA(b, h) + aoff + m * 2048 + k * 1024); } while (0)
; #define PG8_MMA(ai, bj, At, Bt) do { __builtin_amdgcn_s_setprio(1); _Pragma("unroll") for (int m = 0; m < 4; ++m) _Pragma("unroll") for (int n = 0; n < 2; ++n) _Pragma("unroll") for (int k = 0; k < 2; ++k) \
;         acc[ai][bj][m][n] = __builtin_amdgcn_mfma_f32_16x16x32_bf16(Bt[n][k], At[m][k], acc[ai][bj][m][n], 0, 0, 0); __builtin_amdgcn_s_setprio(0); } while (0)
; #define PG8_WAIT_V(n) asm volatile("s_waitcnt vmcnt(" #n ")" ::: "memory")
; #define PG8_WAIT_L(n) asm volatile("s_waitcnt lgkmcnt(" #n ")" ::: "memory")
; #define PG8_BAR __builtin_amdgcn_s_barrier()
; #define PG8_SCHED __builtin_amdgcn_sched_barrier(0)
; template <class Epi>
; __device__ __forceinline__ void gemm_phase(LAS unsigned char* lds, const Gemm g, const StaticOrder& S, const Epi& E) {
;     ...
;             PG8_LDA(At, 1, 1); PG8_STAGE(PG8_SB(1, 0), b3, voffB); PG8_STAGE(PG8_SB(1, 1), b3 + hsB, voffB); PG8_STAGE(PG8_SA(1, 0), a3, voffA);
;             PG8_WAIT_V(8); PG8_WAIT_L(0); PG8_BAR; PG8_MMA(1, 0, At, B0); PG8_MMA(1, 1, At, B1); PG8_BAR; PG8_SCHED;
;         }
	s_add_i32 s20, s33, s29
	v_lshl_add_u64 v[216:217], v[216:217], 0, s[8:9]
	s_mov_b32 m0, s20
	ds_read_b128 v[184:187], v158 offset:49152
	ds_read_b128 v[188:191], v158 offset:50176
	ds_read_b128 v[192:195], v158 offset:51200
	ds_read_b128 v[196:199], v158 offset:52224
	ds_read_b128 v[200:203], v158 offset:53248
	ds_read_b128 v[204:207], v158 offset:54272
	ds_read_b128 v[208:211], v158 offset:55296
	ds_read_b128 v[212:215], v158 offset:56320
	global_load_lds_dwordx4 v[216:217], off
	s_add_i32 m0, s20, 0x2000
	s_add_u32 s20, s22, 0x20080
	v_lshl_add_u64 v[216:217], v[218:219], 0, s[8:9]
	s_addc_u32 s21, s23, 0
	s_add_i32 s22, s62, s29
	global_load_lds_dwordx4 v[216:217], off
	v_lshl_add_u64 v[216:217], s[20:21], 0, v[130:131]
	s_mov_b32 m0, s22
	s_nop 0
	global_load_lds_dwordx4 v[216:217], off
	v_lshl_add_u64 v[216:217], s[20:21], 0, v[134:135]
	s_add_i32 m0, s22, 0x2000
	s_nop 0
	global_load_lds_dwordx4 v[216:217], off
	v_lshl_add_u64 v[216:217], v[220:221], 0, s[8:9]
	s_mov_b32 m0, s41
	s_nop 0
	global_load_lds_dwordx4 v[216:217], off
	v_lshl_add_u64 v[216:217], v[222:223], 0, s[8:9]
	s_mov_b32 m0, s42
	s_nop 0
	global_load_lds_dwordx4 v[216:217], off
	s_waitcnt vmcnt(8)
	s_waitcnt lgkmcnt(0)
	s_barrier
	s_setprio 1
	s_waitcnt lgkmcnt(0)
	v_mfma_f32_16x16x32_bf16 v[60:63], v[144:147], v[184:187], v[60:63]
	v_mfma_f32_16x16x32_bf16 v[56:59], v[160:163], v[184:187], v[56:59]
	v_mfma_f32_16x16x32_bf16 v[44:47], v[144:147], v[192:195], v[44:47]
	v_mfma_f32_16x16x32_bf16 v[40:43], v[160:163], v[192:195], v[40:43]
	v_mfma_f32_16x16x32_bf16 v[28:31], v[144:147], v[200:203], v[28:31]
	v_mfma_f32_16x16x32_bf16 v[24:27], v[160:163], v[200:203], v[24:27]
	v_mfma_f32_16x16x32_bf16 v[12:15], v[144:147], v[208:211], v[12:15]
	v_mfma_f32_16x16x32_bf16 v[8:11], v[160:163], v[208:211], v[8:11]
	v_mfma_f32_16x16x32_bf16 v[60:63], v[148:151], v[188:191], v[60:63]
	v_mfma_f32_16x16x32_bf16 v[56:59], v[164:167], v[188:191], v[56:59]
	v_mfma_f32_16x16x32_bf16 v[44:47], v[148:151], v[196:199], v[44:47]
	v_mfma_f32_16x16x32_bf16 v[40:43], v[164:167], v[196:199], v[40:43]
	v_mfma_f32_16x16x32_bf16 v[28:31], v[148:151], v[204:207], v[28:31]
	v_mfma_f32_16x16x32_bf16 v[24:27], v[164:167], v[204:207], v[24:27]
	v_mfma_f32_16x16x32_bf16 v[12:15], v[148:151], v[212:215], v[12:15]
	v_mfma_f32_16x16x32_bf16 v[8:11], v[164:167], v[212:215], v[8:11]
	s_setprio 0
	s_setprio 1
	v_mfma_f32_16x16x32_bf16 v[52:55], v[168:171], v[184:187], v[52:55]
	v_mfma_f32_16x16x32_bf16 v[48:51], v[176:179], v[184:187], v[48:51]
	v_mfma_f32_16x16x32_bf16 v[36:39], v[168:171], v[192:195], v[36:39]
	v_mfma_f32_16x16x32_bf16 v[32:35], v[176:179], v[192:195], v[32:35]
	v_mfma_f32_16x16x32_bf16 v[20:23], v[168:171], v[200:203], v[20:23]
	v_mfma_f32_16x16x32_bf16 v[16:19], v[176:179], v[200:203], v[16:19]
	v_mfma_f32_16x16x32_bf16 v[4:7], v[168:171], v[208:211], v[4:7]
	v_mfma_f32_16x16x32_bf16 v[0:3], v[176:179], v[208:211], v[0:3]
	v_mfma_f32_16x16x32_bf16 v[52:55], v[172:175], v[188:191], v[52:55]
	v_mfma_f32_16x16x32_bf16 v[48:51], v[180:183], v[188:191], v[48:51]
	v_mfma_f32_16x16x32_bf16 v[36:39], v[172:175], v[196:199], v[36:39]
	v_mfma_f32_16x16x32_bf16 v[32:35], v[180:183], v[196:199], v[32:35]
	v_mfma_f32_16x16x32_bf16 v[20:23], v[172:175], v[204:207], v[20:23]
	v_mfma_f32_16x16x32_bf16 v[16:19], v[180:183], v[204:207], v[16:19]
	v_mfma_f32_16x16x32_bf16 v[4:7], v[172:175], v[212:215], v[4:7]
	v_mfma_f32_16x16x32_bf16 v[0:3], v[180:183], v[212:215], v[0:3]
	s_setprio 0
	s_barrier
	s_add_i32 s61, s61, 2
	s_add_u32 s59, s59, 0x100
	s_addc_u32 s60, s60, 0
	s_cmp_gt_u32 s61, 5
	s_mov_b64 s[20:21], s[6:7]
	s_cbranch_scc0 .LBB0_1370
	s_branch .Lpeel_exit4

; #define PG8_STAGE(bufoff, gbase, voff) do { _Pragma("unroll") for (int _i = 0; _i < 2; ++_i) \
;         __builtin_amdgcn_global_load_lds((const unsigned*)((const char*)(gbase) + (voff)[_i]), (LAS unsigned*)(lds + (bufoff) + ldsw + _i * 8192), 16, 0, 0); } while (0)
; #define PG8_LDA(dst, b, h) do { _Pragma("unroll") for (int m = 0; m < 4; ++m) _Pragma("unroll") for (int k = 0; k < 2; ++k) dst[m][k] = *(const LAS bf16x8*)(lds + PG8_SA(b, h) + aoff + m * 2048 + k * 1024); } while (0)
; #define PG8_LDB(dst, b, h) do { _Pragma("unroll") for (int n = 0; n < 2; ++n) _Pragma("unroll") for (int k = 0; k < 2; ++k) dst[n][k] = *(const LAS bf16x8*)(lds + PG8_SB(b, h) + boff + n * 2048 + k * 1024); } while (0)
; #define PG8_WAIT_V(n) asm volatile("s_waitcnt vmcnt(" #n ")" ::: "memory")
; #define PG8_WAIT_L(n) asm volatile("s_waitcnt lgkmcnt(" #n ")" ::: "memory")
; template <class Epi>
; __device__ __forceinline__ void gemm_phase(LAS unsigned char* lds, const Gemm g, const StaticOrder& S, const Epi& E) {
;     ...
;         const bool has_next = S.next(ui + 1, nxt);
;         const char* nA = has_next ? (const char*)g.A + (size_t)nxt.pm * tsA : cA; const char* nB = has_next ? (const char*)g.Bt + (size_t)nxt.pn * tsB : cB;
;         for (int t = 0; t < nt; t += 2) {
;             const bool last = (t == nt - 2);
;             const char* a1 = cA + (size_t)(t + 1) * kstep;
;             const char* a2 = last ? nA : cA + (size_t)(t + 2) * kstep; const char* b2 = last ? nB : cB + (size_t)(t + 2) * kstep;
;             const char* a3 = a2 + kstep; const char* b3 = b2 + kstep;
;             PG8_LDB(B0, 0, 0); PG8_LDB(B1, 0, 1); PG8_SCHED; PG8_LDA(At, 0, 0); PG8_STAGE(PG8_SA(1, 1), a1 + hsA, voffA);
;             PG8_WAIT_V(8); PG8_WAIT_L(0); PG8_BAR; PG8_MMA(0, 0, At, B0); PG8_MMA(0, 1, At, B1); PG8_BAR; PG8_SCHED;
;             PG8_LDA(At, 0, 1); PG8_STAGE(PG8_SB(0, 0), b2, voffB); PG8_STAGE(PG8_SB(0, 1), b2 + hsB, voffB); PG8_STAGE(PG8_SA(0, 0), a2, voffA);
;             PG8_WAIT_V(8); PG8_WAIT_L(0); PG8_BAR; PG8_MMA(1, 0, At, B0); PG8_MMA(1, 1, At, B1); PG8_BAR; PG8_SCHED;
;     ...
;         for (int a = 0; a < 2; ++a)
; #pragma unroll
;             for (int b = 0; b < 2; ++b)
; #pragma unroll
;                 for (int m = 0; m < 4; ++m)
; #pragma unroll
;                     for (int n = 0; n < 2; ++n) acc[a][b][m][n] = (f32x4){0.f, 0.f, 0.f, 0.f};
.LBB0_1395:
	s_ashr_i32 s15, s14, 31
	s_lshl_b64 s[18:19], s[14:15], 18
	s_add_u32 s18, s29, s18
	s_addc_u32 s19, s36, s19
	s_and_b64 s[6:7], s[6:7], exec
	s_cselect_b32 s15, s19, s23
	s_cselect_b32 s60, s18, s22
	s_add_u32 s61, s22, 0x100
	s_addc_u32 s62, s23, 0
	s_mov_b32 s63, -2
	s_add_u32 s6, s20, 0x100
	s_addc_u32 s7, s21, 0
	s_cmp_eq_u32 s63, 4
	s_cselect_b32 s25, s17, s7
	s_cselect_b32 s24, s16, s6
	s_cselect_b32 s23, s15, s62
	s_cselect_b32 s22, s60, s61
	s_add_i32 s33, 0, 0x14000
	v_add_u32_e32 v152, s33, v155
	ds_read_b128 v[144:147], v159
	ds_read_b128 v[148:151], v159 offset:1024
	ds_read_b128 v[162:165], v159 offset:2048
	ds_read_b128 v[166:169], v159 offset:3072
	ds_read_b128 v[170:173], v152
	ds_read_b128 v[174:177], v152 offset:1024
	ds_read_b128 v[178:181], v152 offset:2048
	ds_read_b128 v[182:185], v152 offset:3072
	v_lshl_add_u64 v[152:153], s[20:21], 0, v[136:137]
	s_add_i32 m0, s38, 0xc000
	ds_read_b128 v[186:189], v160
	ds_read_b128 v[190:193], v160 offset:1024
	ds_read_b128 v[194:197], v160 offset:2048
	ds_read_b128 v[198:201], v160 offset:3072
	ds_read_b128 v[202:205], v160 offset:4096
	ds_read_b128 v[206:209], v160 offset:5120
	ds_read_b128 v[210:213], v160 offset:6144
	ds_read_b128 v[214:217], v160 offset:7168
	global_load_lds_dwordx4 v[152:153], off
	v_lshl_add_u64 v[152:153], s[20:21], 0, v[138:139]
	s_add_i32 m0, s38, 0xe000
	s_nop 0
	global_load_lds_dwordx4 v[152:153], off
	s_waitcnt vmcnt(8)
	s_waitcnt lgkmcnt(0)
	s_barrier
	s_setprio 1
	s_waitcnt lgkmcnt(0)
	v_mfma_f32_16x16x32_bf16 v[124:127], v[144:147], v[186:189], 0
	v_mfma_f32_16x16x32_bf16 v[120:123], v[162:165], v[186:189], 0
	v_mfma_f32_16x16x32_bf16 v[108:111], v[144:147], v[194:197], 0
	v_mfma_f32_16x16x32_bf16 v[104:107], v[162:165], v[194:197], 0
	v_mfma_f32_16x16x32_bf16 v[92:95], v[144:147], v[202:205], 0
	v_mfma_f32_16x16x32_bf16 v[88:91], v[162:165], v[202:205], 0
	v_mfma_f32_16x16x32_bf16 v[76:79], v[144:147], v[210:213], 0
	v_mfma_f32_16x16x32_bf16 v[72:75], v[162:165], v[210:213], 0
	v_mfma_f32_16x16x32_bf16 v[124:127], v[148:151], v[190:193], v[124:127]
	v_mfma_f32_16x16x32_bf16 v[120:123], v[166:169], v[190:193], v[120:123]
	v_mfma_f32_16x16x32_bf16 v[108:111], v[148:151], v[198:201], v[108:111]
	v_mfma_f32_16x16x32_bf16 v[104:107], v[166:169], v[198:201], v[104:107]
	v_mfma_f32_16x16x32_bf16 v[92:95], v[148:151], v[206:209], v[92:95]
	v_mfma_f32_16x16x32_bf16 v[88:91], v[166:169], v[206:209], v[88:91]
	v_mfma_f32_16x16x32_bf16 v[76:79], v[148:151], v[214:217], v[76:79]
	v_mfma_f32_16x16x32_bf16 v[72:75], v[166:169], v[214:217], v[72:75]
	s_setprio 0
	s_setprio 1
	v_mfma_f32_16x16x32_bf16 v[116:119], v[170:173], v[186:189], 0
	v_mfma_f32_16x16x32_bf16 v[112:115], v[178:181], v[186:189], 0
	v_mfma_f32_16x16x32_bf16 v[100:103], v[170:173], v[194:197], 0
	v_mfma_f32_16x16x32_bf16 v[96:99], v[178:181], v[194:197], 0
	v_mfma_f32_16x16x32_bf16 v[84:87], v[170:173], v[202:205], 0
	v_mfma_f32_16x16x32_bf16 v[80:83], v[178:181], v[202:205], 0
	v_mfma_f32_16x16x32_bf16 v[68:71], v[170:173], v[210:213], 0
	v_mfma_f32_16x16x32_bf16 v[64:67], v[178:181], v[210:213], 0
	v_mfma_f32_16x16x32_bf16 v[116:119], v[174:177], v[190:193], v[116:119]
	v_mfma_f32_16x16x32_bf16 v[112:115], v[182:185], v[190:193], v[112:115]
	v_mfma_f32_16x16x32_bf16 v[100:103], v[174:177], v[198:201], v[100:103]
	v_mfma_f32_16x16x32_bf16 v[96:99], v[182:185], v[198:201], v[96:99]
	v_mfma_f32_16x16x32_bf16 v[84:87], v[174:177], v[206:209], v[84:87]
	v_mfma_f32_16x16x32_bf16 v[80:83], v[182:185], v[206:209], v[80:83]
	v_mfma_f32_16x16x32_bf16 v[68:71], v[174:177], v[214:217], v[68:71]
	v_mfma_f32_16x16x32_bf16 v[64:67], v[182:185], v[214:217], v[64:67]
	s_setprio 0
	s_barrier
	s_add_i32 s20, s51, s37
	v_lshl_add_u64 v[152:153], s[22:23], 0, v[130:131]
	s_mov_b32 m0, s20
	ds_read_b128 v[186:189], v160 offset:16384
	ds_read_b128 v[190:193], v160 offset:17408
	ds_read_b128 v[194:197], v160 offset:18432
	ds_read_b128 v[198:201], v160 offset:19456
	ds_read_b128 v[202:205], v160 offset:20480
	ds_read_b128 v[206:209], v160 offset:21504
	ds_read_b128 v[210:213], v160 offset:22528
	ds_read_b128 v[214:217], v160 offset:23552
	global_load_lds_dwordx4 v[152:153], off
	s_add_i32 m0, s20, 0x2000
	s_add_u32 s20, s22, 0x20000
	v_lshl_add_u64 v[218:219], s[22:23], 0, v[134:135]
	s_addc_u32 s21, s23, 0
	s_add_i32 s33, s33, s37
	global_load_lds_dwordx4 v[218:219], off
	v_lshl_add_u64 v[220:221], s[20:21], 0, v[130:131]
	s_mov_b32 m0, s33
	v_lshl_add_u64 v[222:223], s[24:25], 0, v[132:133]
	global_load_lds_dwordx4 v[220:221], off
	v_lshl_add_u64 v[220:221], s[20:21], 0, v[134:135]
	s_add_i32 m0, s33, 0x2000
	s_nop 0
	global_load_lds_dwordx4 v[220:221], off
	v_lshl_add_u64 v[220:221], s[24:25], 0, v[128:129]
	s_mov_b32 m0, s38
	s_nop 0
	global_load_lds_dwordx4 v[220:221], off
	s_mov_b32 m0, s39
	s_nop 0
	global_load_lds_dwordx4 v[222:223], off
	s_waitcnt vmcnt(8)
	s_waitcnt lgkmcnt(0)
	s_barrier
; #define PG8_STAGE(bufoff, gbase, voff) do { _Pragma("unroll") for (int _i = 0; _i < 2; ++_i) \
;         __builtin_amdgcn_global_load_lds((const unsigned*)((const char*)(gbase) + (voff)[_i]), (LAS unsigned*)(lds + (bufoff) + ldsw + _i * 8192), 16, 0, 0); } while (0)
; #define PG8_LDA(dst, b, h) do { _Pragma("unroll") for (int m = 0; m < 4; ++m) _Pragma("unroll") for (int k = 0; k < 2; ++k) dst[m][k] = *(const LAS bf16x8*)(lds + PG8_SA(b, h) + aoff + m * 2048 + k * 1024); } while (0)
; #define PG8_LDB(dst, b, h) do { _Pragma("unroll") for (int n = 0; n < 2; ++n) _Pragma("unroll") for (int k = 0; k < 2; ++k) dst[n][k] = *(const LAS bf16x8*)(lds + PG8_SB(b, h) + boff + n * 2048 + k * 1024); } while (0)
; #define PG8_MMA(ai, bj, At, Bt) do { __builtin_amdgcn_s_setprio(1); _Pragma("unroll") for (int m = 0; m < 4; ++m) _Pragma("unroll") for (int n = 0; n < 2; ++n) _Pragma("unroll") for (int k = 0; k < 2; ++k) \
;         acc[ai][bj][m][n] = __builtin_amdgcn_mfma_f32_16x16x32_bf16(Bt[n][k], At[m][k], acc[ai][bj][m][n], 0, 0, 0); __builtin_amdgcn_s_setprio(0); } while (0)
; #define PG8_WAIT_V(n) asm volatile("s_waitcnt vmcnt(" #n ")" ::: "memory")
; #define PG8_WAIT_L(n) asm volatile("s_waitcnt lgkmcnt(" #n ")" ::: "memory")
; #define PG8_BAR __builtin_amdgcn_s_barrier()
; #define PG8_SCHED __builtin_amdgcn_sched_barrier(0)
; template <class Epi>
; __device__ __forceinline__ void gemm_phase(LAS unsigned char* lds, const Gemm g, const StaticOrder& S, const Epi& E) {
;     ...
;             PG8_WAIT_V(8); PG8_WAIT_L(0); PG8_BAR; PG8_MMA(1, 0, At, B0); PG8_MMA(1, 1, At, B1); PG8_BAR; PG8_SCHED;
;             PG8_LDB(B0, 1, 0); PG8_LDB(B1, 1, 1); PG8_SCHED; PG8_LDA(At, 1, 0); PG8_STAGE(PG8_SA(0, 1), a2 + hsA, voffA);
;             PG8_WAIT_V(8); PG8_WAIT_L(0); PG8_BAR; PG8_MMA(0, 0, At, B0); PG8_MMA(0, 1, At, B1); PG8_BAR; PG8_SCHED;
	s_setprio 1
	s_waitcnt lgkmcnt(0)
	v_mfma_f32_16x16x32_bf16 v[60:63], v[144:147], v[186:189], 0
	v_mfma_f32_16x16x32_bf16 v[56:59], v[162:165], v[186:189], 0
	v_mfma_f32_16x16x32_bf16 v[44:47], v[144:147], v[194:197], 0
	v_mfma_f32_16x16x32_bf16 v[40:43], v[162:165], v[194:197], 0
	v_mfma_f32_16x16x32_bf16 v[28:31], v[144:147], v[202:205], 0
	v_mfma_f32_16x16x32_bf16 v[24:27], v[162:165], v[202:205], 0
	v_mfma_f32_16x16x32_bf16 v[12:15], v[144:147], v[210:213], 0
	v_mfma_f32_16x16x32_bf16 v[8:11], v[162:165], v[210:213], 0
	v_mfma_f32_16x16x32_bf16 v[60:63], v[148:151], v[190:193], v[60:63]
	v_mfma_f32_16x16x32_bf16 v[56:59], v[166:169], v[190:193], v[56:59]
	v_mfma_f32_16x16x32_bf16 v[44:47], v[148:151], v[198:201], v[44:47]
	v_mfma_f32_16x16x32_bf16 v[40:43], v[166:169], v[198:201], v[40:43]
	v_mfma_f32_16x16x32_bf16 v[28:31], v[148:151], v[206:209], v[28:31]
	v_mfma_f32_16x16x32_bf16 v[24:27], v[166:169], v[206:209], v[24:27]
	v_mfma_f32_16x16x32_bf16 v[12:15], v[148:151], v[214:217], v[12:15]
	v_mfma_f32_16x16x32_bf16 v[8:11], v[166:169], v[214:217], v[8:11]
	s_setprio 0
	s_setprio 1
	v_mfma_f32_16x16x32_bf16 v[52:55], v[170:173], v[186:189], 0
	v_mfma_f32_16x16x32_bf16 v[48:51], v[178:181], v[186:189], 0
	v_mfma_f32_16x16x32_bf16 v[36:39], v[170:173], v[194:197], 0
	v_mfma_f32_16x16x32_bf16 v[32:35], v[178:181], v[194:197], 0
	v_mfma_f32_16x16x32_bf16 v[20:23], v[170:173], v[202:205], 0
	v_mfma_f32_16x16x32_bf16 v[16:19], v[178:181], v[202:205], 0
	v_mfma_f32_16x16x32_bf16 v[4:7], v[170:173], v[210:213], 0
	v_mfma_f32_16x16x32_bf16 v[0:3], v[178:181], v[210:213], 0
	v_mfma_f32_16x16x32_bf16 v[52:55], v[174:177], v[190:193], v[52:55]
	v_mfma_f32_16x16x32_bf16 v[48:51], v[182:185], v[190:193], v[48:51]
	v_mfma_f32_16x16x32_bf16 v[36:39], v[174:177], v[198:201], v[36:39]
	v_mfma_f32_16x16x32_bf16 v[32:35], v[182:185], v[198:201], v[32:35]
	v_mfma_f32_16x16x32_bf16 v[20:23], v[174:177], v[206:209], v[20:23]
	v_mfma_f32_16x16x32_bf16 v[16:19], v[182:185], v[206:209], v[16:19]
	v_mfma_f32_16x16x32_bf16 v[4:7], v[174:177], v[214:217], v[4:7]
	v_mfma_f32_16x16x32_bf16 v[0:3], v[182:185], v[214:217], v[0:3]
	s_setprio 0
	s_barrier
	s_add_i32 s33, 0, 0x18000
	v_add_u32_e32 v161, s33, v155
	s_add_i32 s64, 0, 0x1c000
	ds_read_b128 v[144:147], v161
	ds_read_b128 v[148:151], v161 offset:1024
	ds_read_b128 v[162:165], v161 offset:2048
	ds_read_b128 v[166:169], v161 offset:3072
	v_add_u32_e32 v161, s64, v155
	ds_read_b128 v[170:173], v161
	ds_read_b128 v[174:177], v161 offset:1024
	ds_read_b128 v[178:181], v161 offset:2048
	ds_read_b128 v[182:185], v161 offset:3072
	s_add_u32 s20, s24, 0x140000
	s_addc_u32 s21, s25, 0
	s_mov_b32 m0, s40
	v_lshl_add_u64 v[224:225], s[20:21], 0, v[128:129]
	ds_read_b128 v[186:189], v160 offset:32768
	ds_read_b128 v[190:193], v160 offset:33792
	ds_read_b128 v[194:197], v160 offset:34816
	ds_read_b128 v[198:201], v160 offset:35840
	ds_read_b128 v[202:205], v160 offset:36864
	ds_read_b128 v[206:209], v160 offset:37888
	ds_read_b128 v[210:213], v160 offset:38912
	ds_read_b128 v[214:217], v160 offset:39936
	global_load_lds_dwordx4 v[224:225], off
	v_lshl_add_u64 v[224:225], s[20:21], 0, v[132:133]
	s_mov_b32 m0, s41
	s_nop 0
	global_load_lds_dwordx4 v[224:225], off
	s_waitcnt vmcnt(8)
	s_waitcnt lgkmcnt(0)
	s_barrier
	s_setprio 1
	s_waitcnt lgkmcnt(0)
	v_mfma_f32_16x16x32_bf16 v[124:127], v[144:147], v[186:189], v[124:127]
	v_mfma_f32_16x16x32_bf16 v[120:123], v[162:165], v[186:189], v[120:123]
	v_mfma_f32_16x16x32_bf16 v[108:111], v[144:147], v[194:197], v[108:111]
	v_mfma_f32_16x16x32_bf16 v[104:107], v[162:165], v[194:197], v[104:107]
	v_mfma_f32_16x16x32_bf16 v[92:95], v[144:147], v[202:205], v[92:95]
	v_mfma_f32_16x16x32_bf16 v[88:91], v[162:165], v[202:205], v[88:91]
	v_mfma_f32_16x16x32_bf16 v[76:79], v[144:147], v[210:213], v[76:79]
	v_mfma_f32_16x16x32_bf16 v[72:75], v[162:165], v[210:213], v[72:75]
	v_mfma_f32_16x16x32_bf16 v[124:127], v[148:151], v[190:193], v[124:127]
	v_mfma_f32_16x16x32_bf16 v[120:123], v[166:169], v[190:193], v[120:123]
	v_mfma_f32_16x16x32_bf16 v[108:111], v[148:151], v[198:201], v[108:111]
	v_mfma_f32_16x16x32_bf16 v[104:107], v[166:169], v[198:201], v[104:107]
	v_mfma_f32_16x16x32_bf16 v[92:95], v[148:151], v[206:209], v[92:95]
	v_mfma_f32_16x16x32_bf16 v[88:91], v[166:169], v[206:209], v[88:91]
	v_mfma_f32_16x16x32_bf16 v[76:79], v[148:151], v[214:217], v[76:79]
	v_mfma_f32_16x16x32_bf16 v[72:75], v[166:169], v[214:217], v[72:75]
	s_setprio 0
	s_setprio 1
	v_mfma_f32_16x16x32_bf16 v[116:119], v[170:173], v[186:189], v[116:119]
	v_mfma_f32_16x16x32_bf16 v[112:115], v[178:181], v[186:189], v[112:115]
	v_mfma_f32_16x16x32_bf16 v[100:103], v[170:173], v[194:197], v[100:103]
	v_mfma_f32_16x16x32_bf16 v[96:99], v[178:181], v[194:197], v[96:99]
	v_mfma_f32_16x16x32_bf16 v[84:87], v[170:173], v[202:205], v[84:87]
	v_mfma_f32_16x16x32_bf16 v[80:83], v[178:181], v[202:205], v[80:83]
	v_mfma_f32_16x16x32_bf16 v[68:71], v[170:173], v[210:213], v[68:71]
	v_mfma_f32_16x16x32_bf16 v[64:67], v[178:181], v[210:213], v[64:67]
	v_mfma_f32_16x16x32_bf16 v[116:119], v[174:177], v[190:193], v[116:119]
	v_mfma_f32_16x16x32_bf16 v[112:115], v[182:185], v[190:193], v[112:115]
	v_mfma_f32_16x16x32_bf16 v[100:103], v[174:177], v[198:201], v[100:103]
	v_mfma_f32_16x16x32_bf16 v[96:99], v[182:185], v[198:201], v[96:99]
	v_mfma_f32_16x16x32_bf16 v[84:87], v[174:177], v[206:209], v[84:87]
	v_mfma_f32_16x16x32_bf16 v[80:83], v[182:185], v[206:209], v[80:83]
	v_mfma_f32_16x16x32_bf16 v[68:71], v[174:177], v[214:217], v[68:71]
	v_mfma_f32_16x16x32_bf16 v[64:67], v[182:185], v[214:217], v[64:67]
	s_setprio 0
	s_barrier
; #define PG8_STAGE(bufoff, gbase, voff) do { _Pragma("unroll") for (int _i = 0; _i < 2; ++_i) \
;         __builtin_amdgcn_global_load_lds((const unsigned*)((const char*)(gbase) + (voff)[_i]), (LAS unsigned*)(lds + (bufoff) + ldsw + _i * 8192), 16, 0, 0); } while (0)
; #define PG8_LDA(dst, b, h) do { _Pragma("unroll") for (int m = 0; m < 4; ++m) _Pragma("unroll") for (int k = 0; k < 2; ++k) dst[m][k] = *(const LAS bf16x8*)(lds + PG8_SA(b, h) + aoff + m * 2048 + k * 1024); } while (0)
; #define PG8_MMA(ai, bj, At, Bt) do { __builtin_amdgcn_s_setprio(1); _Pragma("unroll") for (int m = 0; m < 4; ++m) _Pragma("unroll") for (int n = 0; n < 2; ++n) _Pragma("unroll") for (int k = 0; k < 2; ++k) \
;         acc[ai][bj][m][n] = __builtin_amdgcn_mfma_f32_16x16x32_bf16(Bt[n][k], At[m][k], acc[ai][bj][m][n], 0, 0, 0); __builtin_amdgcn_s_setprio(0); } while (0)
; #define PG8_WAIT_V(n) asm volatile("s_waitcnt vmcnt(" #n ")" ::: "memory")
; #define PG8_WAIT_L(n) asm volatile("s_waitcnt lgkmcnt(" #n ")" ::: "memory")
; #define PG8_BAR __builtin_amdgcn_s_barrier()
; #define PG8_SCHED __builtin_amdgcn_sched_barrier(0)
; template <class Epi>
; __device__ __forceinline__ void gemm_phase(LAS unsigned char* lds, const Gemm g, const StaticOrder& S, const Epi& E) {
;     ...
;             PG8_LDA(At, 1, 1); PG8_STAGE(PG8_SB(1, 0), b3, voffB); PG8_STAGE(PG8_SB(1, 1), b3 + hsB, voffB); PG8_STAGE(PG8_SA(1, 0), a3, voffA);
;             PG8_WAIT_V(8); PG8_WAIT_L(0); PG8_BAR; PG8_MMA(1, 0, At, B0); PG8_MMA(1, 1, At, B1); PG8_BAR; PG8_SCHED;
;         }
	s_add_i32 s20, s33, s37
	v_lshl_add_u64 v[152:153], v[152:153], 0, s[8:9]
	s_mov_b32 m0, s20
	ds_read_b128 v[186:189], v160 offset:49152
	ds_read_b128 v[190:193], v160 offset:50176
	ds_read_b128 v[194:197], v160 offset:51200
	ds_read_b128 v[198:201], v160 offset:52224
	ds_read_b128 v[202:205], v160 offset:53248
	ds_read_b128 v[206:209], v160 offset:54272
	ds_read_b128 v[210:213], v160 offset:55296
	ds_read_b128 v[214:217], v160 offset:56320
	global_load_lds_dwordx4 v[152:153], off
	s_add_i32 m0, s20, 0x2000
	s_add_u32 s20, s22, 0x20080
	v_lshl_add_u64 v[152:153], v[218:219], 0, s[8:9]
	s_addc_u32 s21, s23, 0
	s_add_i32 s22, s64, s37
	global_load_lds_dwordx4 v[152:153], off
	v_lshl_add_u64 v[152:153], s[20:21], 0, v[130:131]
	s_mov_b32 m0, s22
	s_nop 0
	global_load_lds_dwordx4 v[152:153], off
	v_lshl_add_u64 v[152:153], s[20:21], 0, v[134:135]
	s_add_i32 m0, s22, 0x2000
	s_nop 0
	global_load_lds_dwordx4 v[152:153], off
	v_lshl_add_u64 v[152:153], v[220:221], 0, s[8:9]
	s_mov_b32 m0, s43
	s_nop 0
	global_load_lds_dwordx4 v[152:153], off
	v_lshl_add_u64 v[152:153], v[222:223], 0, s[8:9]
	s_mov_b32 m0, s48
	s_nop 0
	global_load_lds_dwordx4 v[152:153], off
	s_waitcnt vmcnt(8)
	s_waitcnt lgkmcnt(0)
	s_barrier
	s_setprio 1
	s_waitcnt lgkmcnt(0)
	v_mfma_f32_16x16x32_bf16 v[60:63], v[144:147], v[186:189], v[60:63]
	v_mfma_f32_16x16x32_bf16 v[56:59], v[162:165], v[186:189], v[56:59]
	v_mfma_f32_16x16x32_bf16 v[44:47], v[144:147], v[194:197], v[44:47]
	v_mfma_f32_16x16x32_bf16 v[40:43], v[162:165], v[194:197], v[40:43]
	v_mfma_f32_16x16x32_bf16 v[28:31], v[144:147], v[202:205], v[28:31]
	v_mfma_f32_16x16x32_bf16 v[24:27], v[162:165], v[202:205], v[24:27]
	v_mfma_f32_16x16x32_bf16 v[12:15], v[144:147], v[210:213], v[12:15]
	v_mfma_f32_16x16x32_bf16 v[8:11], v[162:165], v[210:213], v[8:11]
	v_mfma_f32_16x16x32_bf16 v[60:63], v[148:151], v[190:193], v[60:63]
	v_mfma_f32_16x16x32_bf16 v[56:59], v[166:169], v[190:193], v[56:59]
	v_mfma_f32_16x16x32_bf16 v[44:47], v[148:151], v[198:201], v[44:47]
	v_mfma_f32_16x16x32_bf16 v[40:43], v[166:169], v[198:201], v[40:43]
	v_mfma_f32_16x16x32_bf16 v[28:31], v[148:151], v[206:209], v[28:31]
	v_mfma_f32_16x16x32_bf16 v[24:27], v[166:169], v[206:209], v[24:27]
	v_mfma_f32_16x16x32_bf16 v[12:15], v[148:151], v[214:217], v[12:15]
	v_mfma_f32_16x16x32_bf16 v[8:11], v[166:169], v[214:217], v[8:11]
	s_setprio 0
	s_setprio 1
	v_mfma_f32_16x16x32_bf16 v[52:55], v[170:173], v[186:189], v[52:55]
	v_mfma_f32_16x16x32_bf16 v[48:51], v[178:181], v[186:189], v[48:51]
	v_mfma_f32_16x16x32_bf16 v[36:39], v[170:173], v[194:197], v[36:39]
	v_mfma_f32_16x16x32_bf16 v[32:35], v[178:181], v[194:197], v[32:35]
	v_mfma_f32_16x16x32_bf16 v[20:23], v[170:173], v[202:205], v[20:23]
	v_mfma_f32_16x16x32_bf16 v[16:19], v[178:181], v[202:205], v[16:19]
	v_mfma_f32_16x16x32_bf16 v[4:7], v[170:173], v[210:213], v[4:7]
	v_mfma_f32_16x16x32_bf16 v[0:3], v[178:181], v[210:213], v[0:3]
	v_mfma_f32_16x16x32_bf16 v[52:55], v[174:177], v[190:193], v[52:55]
	v_mfma_f32_16x16x32_bf16 v[48:51], v[182:185], v[190:193], v[48:51]
	v_mfma_f32_16x16x32_bf16 v[36:39], v[174:177], v[198:201], v[36:39]
	v_mfma_f32_16x16x32_bf16 v[32:35], v[182:185], v[198:201], v[32:35]
	v_mfma_f32_16x16x32_bf16 v[20:23], v[174:177], v[206:209], v[20:23]
	v_mfma_f32_16x16x32_bf16 v[16:19], v[182:185], v[206:209], v[16:19]
	v_mfma_f32_16x16x32_bf16 v[4:7], v[174:177], v[214:217], v[4:7]
	v_mfma_f32_16x16x32_bf16 v[0:3], v[182:185], v[214:217], v[0:3]
	s_setprio 0
	s_barrier
	s_add_i32 s63, s63, 2
	s_add_u32 s61, s61, 0x100
	s_addc_u32 s62, s62, 0
	s_cmp_gt_u32 s63, 5
	s_mov_b64 s[20:21], s[6:7]
	s_cbranch_scc0 .LBB0_1396
	s_branch .Lpeel_exit5

; #define PG8_STAGE(bufoff, gbase, voff) do { _Pragma("unroll") for (int _i = 0; _i < 2; ++_i) \
;         __builtin_amdgcn_global_load_lds((const unsigned*)((const char*)(gbase) + (voff)[_i]), (LAS unsigned*)(lds + (bufoff) + ldsw + _i * 8192), 16, 0, 0); } while (0)
; #define PG8_LDA(dst, b, h) do { _Pragma("unroll") for (int m = 0; m < 4; ++m) _Pragma("unroll") for (int k = 0; k < 2; ++k) dst[m][k] = *(const LAS bf16x8*)(lds + PG8_SA(b, h) + aoff + m * 2048 + k * 1024); } while (0)
; #define PG8_LDB(dst, b, h) do { _Pragma("unroll") for (int n = 0; n < 2; ++n) _Pragma("unroll") for (int k = 0; k < 2; ++k) dst[n][k] = *(const LAS bf16x8*)(lds + PG8_SB(b, h) + boff + n * 2048 + k * 1024); } while (0)
; #define PG8_WAIT_V(n) asm volatile("s_waitcnt vmcnt(" #n ")" ::: "memory")
; #define PG8_WAIT_L(n) asm volatile("s_waitcnt lgkmcnt(" #n ")" ::: "memory")
; template <class Epi>
; __device__ __forceinline__ void gemm_phase(LAS unsigned char* lds, const Gemm g, const StaticOrder& S, const Epi& E) {
;     ...
;         const bool has_next = S.next(ui + 1, nxt);
;         const char* nA = has_next ? (const char*)g.A + (size_t)nxt.pm * tsA : cA; const char* nB = has_next ? (const char*)g.Bt + (size_t)nxt.pn * tsB : cB;
;         for (int t = 0; t < nt; t += 2) {
;             const bool last = (t == nt - 2);
;             const char* a1 = cA + (size_t)(t + 1) * kstep;
;             const char* a2 = last ? nA : cA + (size_t)(t + 2) * kstep; const char* b2 = last ? nB : cB + (size_t)(t + 2) * kstep;
;             const char* a3 = a2 + kstep; const char* b3 = b2 + kstep;
;             PG8_LDB(B0, 0, 0); PG8_LDB(B1, 0, 1); PG8_SCHED; PG8_LDA(At, 0, 0); PG8_STAGE(PG8_SA(1, 1), a1 + hsA, voffA);
;             PG8_WAIT_V(8); PG8_WAIT_L(0); PG8_BAR; PG8_MMA(0, 0, At, B0); PG8_MMA(0, 1, At, B1); PG8_BAR; PG8_SCHED;
;             PG8_LDA(At, 0, 1); PG8_STAGE(PG8_SB(0, 0), b2, voffB); PG8_STAGE(PG8_SB(0, 1), b2 + hsB, voffB); PG8_STAGE(PG8_SA(0, 0), a2, voffA);
;             PG8_WAIT_V(8); PG8_WAIT_L(0); PG8_BAR; PG8_MMA(1, 0, At, B0); PG8_MMA(1, 1, At, B1); PG8_BAR; PG8_SCHED;
;     ...
;         for (int a = 0; a < 2; ++a)
; #pragma unroll
;             for (int b = 0; b < 2; ++b)
; #pragma unroll
;                 for (int m = 0; m < 4; ++m)
; #pragma unroll
;                     for (int n = 0; n < 2; ++n) acc[a][b][m][n] = (f32x4){0.f, 0.f, 0.f, 0.f};
.LBB0_1473:
	s_ashr_i32 s17, s16, 31
	s_lshl_b64 s[18:19], s[16:17], 19
	s_add_u32 s18, s56, s18
	s_addc_u32 s19, s57, s19
	s_and_b64 s[20:21], s[6:7], exec
	s_cselect_b32 s17, s19, s27
	s_cselect_b32 s23, s18, s26
	s_ashr_i32 s15, s14, 31
	s_lshl_b64 s[20:21], s[14:15], 19
	s_add_u32 s20, s38, s20
	s_addc_u32 s21, s39, s21
	s_and_b64 s[36:37], s[6:7], exec
	s_cselect_b32 s15, s21, s29
	s_cselect_b32 s60, s20, s28
	s_add_u32 s26, s26, 0x40080
	s_addc_u32 s27, s27, 0
	s_add_u32 s61, s28, 0x100
	s_addc_u32 s62, s29, 0
	s_mov_b32 s63, -2
	s_waitcnt lgkmcnt(0)
	ds_read_b128 v[144:147], v151
	ds_read_b128 v[158:161], v151 offset:1024
	ds_read_b128 v[162:165], v151 offset:2048
	ds_read_b128 v[166:169], v151 offset:3072
	ds_read_b128 v[170:173], v152
	ds_read_b128 v[174:177], v152 offset:1024
	ds_read_b128 v[178:181], v152 offset:2048
	ds_read_b128 v[182:185], v152 offset:3072
	s_add_u32 s28, s26, 0xfffc0080
	s_addc_u32 s29, s27, -1
	s_cmp_eq_u32 s63, 12
	s_cselect_b32 s37, s17, s29
	s_cselect_b32 s36, s23, s28
	s_cselect_b32 s29, s15, s62
	s_cselect_b32 s28, s60, s61
	v_lshl_add_u64 v[218:219], s[26:27], 0, v[136:137]
	s_add_i32 m0, s25, 0xc000
	ds_read_b128 v[186:189], v153
	ds_read_b128 v[190:193], v153 offset:1024
	ds_read_b128 v[194:197], v153 offset:2048
	ds_read_b128 v[198:201], v153 offset:3072
	ds_read_b128 v[202:205], v153 offset:4096
	ds_read_b128 v[206:209], v153 offset:5120
	ds_read_b128 v[210:213], v153 offset:6144
	ds_read_b128 v[214:217], v153 offset:7168
	global_load_lds_dwordx4 v[218:219], off
	v_lshl_add_u64 v[218:219], s[26:27], 0, v[138:139]
	s_add_i32 m0, s25, 0xe000
	s_nop 0
	global_load_lds_dwordx4 v[218:219], off
	s_waitcnt vmcnt(8)
	s_waitcnt lgkmcnt(0)
	s_barrier
	s_setprio 1
	s_waitcnt lgkmcnt(0)
	v_mfma_f32_16x16x32_bf16 v[124:127], v[144:147], v[186:189], 0
	v_mfma_f32_16x16x32_bf16 v[120:123], v[162:165], v[186:189], 0
	v_mfma_f32_16x16x32_bf16 v[108:111], v[144:147], v[194:197], 0
	v_mfma_f32_16x16x32_bf16 v[104:107], v[162:165], v[194:197], 0
	v_mfma_f32_16x16x32_bf16 v[92:95], v[144:147], v[202:205], 0
	v_mfma_f32_16x16x32_bf16 v[88:91], v[162:165], v[202:205], 0
	v_mfma_f32_16x16x32_bf16 v[76:79], v[144:147], v[210:213], 0
	v_mfma_f32_16x16x32_bf16 v[72:75], v[162:165], v[210:213], 0
	v_mfma_f32_16x16x32_bf16 v[124:127], v[158:161], v[190:193], v[124:127]
	v_mfma_f32_16x16x32_bf16 v[120:123], v[166:169], v[190:193], v[120:123]
	v_mfma_f32_16x16x32_bf16 v[108:111], v[158:161], v[198:201], v[108:111]
	v_mfma_f32_16x16x32_bf16 v[104:107], v[166:169], v[198:201], v[104:107]
	v_mfma_f32_16x16x32_bf16 v[92:95], v[158:161], v[206:209], v[92:95]
	v_mfma_f32_16x16x32_bf16 v[88:91], v[166:169], v[206:209], v[88:91]
	v_mfma_f32_16x16x32_bf16 v[76:79], v[158:161], v[214:217], v[76:79]
	v_mfma_f32_16x16x32_bf16 v[72:75], v[166:169], v[214:217], v[72:75]
	s_setprio 0
	s_setprio 1
	v_mfma_f32_16x16x32_bf16 v[116:119], v[170:173], v[186:189], 0
	v_mfma_f32_16x16x32_bf16 v[112:115], v[178:181], v[186:189], 0
	v_mfma_f32_16x16x32_bf16 v[100:103], v[170:173], v[194:197], 0
	v_mfma_f32_16x16x32_bf16 v[96:99], v[178:181], v[194:197], 0
	v_mfma_f32_16x16x32_bf16 v[84:87], v[170:173], v[202:205], 0
	v_mfma_f32_16x16x32_bf16 v[80:83], v[178:181], v[202:205], 0
	v_mfma_f32_16x16x32_bf16 v[68:71], v[170:173], v[210:213], 0
	v_mfma_f32_16x16x32_bf16 v[64:67], v[178:181], v[210:213], 0
	v_mfma_f32_16x16x32_bf16 v[116:119], v[174:177], v[190:193], v[116:119]
	v_mfma_f32_16x16x32_bf16 v[112:115], v[182:185], v[190:193], v[112:115]
	v_mfma_f32_16x16x32_bf16 v[100:103], v[174:177], v[198:201], v[100:103]
	v_mfma_f32_16x16x32_bf16 v[96:99], v[182:185], v[198:201], v[96:99]
	v_mfma_f32_16x16x32_bf16 v[84:87], v[174:177], v[206:209], v[84:87]
	v_mfma_f32_16x16x32_bf16 v[80:83], v[182:185], v[206:209], v[80:83]
	v_mfma_f32_16x16x32_bf16 v[68:71], v[174:177], v[214:217], v[68:71]
	v_mfma_f32_16x16x32_bf16 v[64:67], v[182:185], v[214:217], v[64:67]
	s_setprio 0
	s_barrier
	s_add_i32 s33, s58, s40
	v_lshl_add_u64 v[218:219], s[28:29], 0, v[130:131]
	s_mov_b32 m0, s33
	ds_read_b128 v[186:189], v153 offset:16384
	ds_read_b128 v[190:193], v153 offset:17408
	ds_read_b128 v[194:197], v153 offset:18432
	ds_read_b128 v[198:201], v153 offset:19456
	ds_read_b128 v[202:205], v153 offset:20480
	ds_read_b128 v[206:209], v153 offset:21504
	ds_read_b128 v[210:213], v153 offset:22528
	ds_read_b128 v[214:217], v153 offset:23552
	global_load_lds_dwordx4 v[218:219], off
	s_add_i32 m0, s33, 0x2000
	s_add_u32 s64, s28, 0x40000
	v_lshl_add_u64 v[220:221], s[28:29], 0, v[134:135]
	s_addc_u32 s65, s29, 0
	s_add_i32 s33, s59, s40
	global_load_lds_dwordx4 v[220:221], off
	v_lshl_add_u64 v[222:223], s[64:65], 0, v[130:131]
	s_mov_b32 m0, s33
	v_lshl_add_u64 v[224:225], s[36:37], 0, v[132:133]
	global_load_lds_dwordx4 v[222:223], off
	v_lshl_add_u64 v[222:223], s[64:65], 0, v[134:135]
	s_add_i32 m0, s33, 0x2000
	s_nop 0
	global_load_lds_dwordx4 v[222:223], off
	v_lshl_add_u64 v[222:223], s[36:37], 0, v[128:129]
	s_mov_b32 m0, s25
	s_nop 0
	global_load_lds_dwordx4 v[222:223], off
	s_mov_b32 m0, s41
	s_nop 0
	global_load_lds_dwordx4 v[224:225], off
	s_waitcnt vmcnt(8)
	s_waitcnt lgkmcnt(0)
	s_barrier
; #define PG8_STAGE(bufoff, gbase, voff) do { _Pragma("unroll") for (int _i = 0; _i < 2; ++_i) \
;         __builtin_amdgcn_global_load_lds((const unsigned*)((const char*)(gbase) + (voff)[_i]), (LAS unsigned*)(lds + (bufoff) + ldsw + _i * 8192), 16, 0, 0); } while (0)
; #define PG8_LDA(dst, b, h) do { _Pragma("unroll") for (int m = 0; m < 4; ++m) _Pragma("unroll") for (int k = 0; k < 2; ++k) dst[m][k] = *(const LAS bf16x8*)(lds + PG8_SA(b, h) + aoff + m * 2048 + k * 1024); } while (0)
; #define PG8_LDB(dst, b, h) do { _Pragma("unroll") for (int n = 0; n < 2; ++n) _Pragma("unroll") for (int k = 0; k < 2; ++k) dst[n][k] = *(const LAS bf16x8*)(lds + PG8_SB(b, h) + boff + n * 2048 + k * 1024); } while (0)
; #define PG8_MMA(ai, bj, At, Bt) do { __builtin_amdgcn_s_setprio(1); _Pragma("unroll") for (int m = 0; m < 4; ++m) _Pragma("unroll") for (int n = 0; n < 2; ++n) _Pragma("unroll") for (int k = 0; k < 2; ++k) \
;         acc[ai][bj][m][n] = __builtin_amdgcn_mfma_f32_16x16x32_bf16(Bt[n][k], At[m][k], acc[ai][bj][m][n], 0, 0, 0); __builtin_amdgcn_s_setprio(0); } while (0)
; #define PG8_WAIT_V(n) asm volatile("s_waitcnt vmcnt(" #n ")" ::: "memory")
; #define PG8_WAIT_L(n) asm volatile("s_waitcnt lgkmcnt(" #n ")" ::: "memory")
; #define PG8_BAR __builtin_amdgcn_s_barrier()
; #define PG8_SCHED __builtin_amdgcn_sched_barrier(0)
; template <class Epi>
; __device__ __forceinline__ void gemm_phase(LAS unsigned char* lds, const Gemm g, const StaticOrder& S, const Epi& E) {
;     ...
;             PG8_WAIT_V(8); PG8_WAIT_L(0); PG8_BAR; PG8_MMA(0, 0, At, B0); PG8_MMA(0, 1, At, B1); PG8_BAR; PG8_SCHED;
;             PG8_LDA(At, 0, 1); PG8_STAGE(PG8_SB(0, 0), b2, voffB); PG8_STAGE(PG8_SB(0, 1), b2 + hsB, voffB); PG8_STAGE(PG8_SA(0, 0), a2, voffA);
;             PG8_WAIT_V(8); PG8_WAIT_L(0); PG8_BAR; PG8_MMA(1, 0, At, B0); PG8_MMA(1, 1, At, B1); PG8_BAR; PG8_SCHED;
;             PG8_LDB(B0, 1, 0); PG8_LDB(B1, 1, 1); PG8_SCHED; PG8_LDA(At, 1, 0); PG8_STAGE(PG8_SA(0, 1), a2 + hsA, voffA);
;             PG8_WAIT_V(8); PG8_WAIT_L(0); PG8_BAR; PG8_MMA(0, 0, At, B0); PG8_MMA(0, 1, At, B1); PG8_BAR; PG8_SCHED;
	s_setprio 1
	s_waitcnt lgkmcnt(0)
	v_mfma_f32_16x16x32_bf16 v[60:63], v[144:147], v[186:189], 0
	v_mfma_f32_16x16x32_bf16 v[56:59], v[162:165], v[186:189], 0
	v_mfma_f32_16x16x32_bf16 v[44:47], v[144:147], v[194:197], 0
	v_mfma_f32_16x16x32_bf16 v[40:43], v[162:165], v[194:197], 0
	v_mfma_f32_16x16x32_bf16 v[28:31], v[144:147], v[202:205], 0
	v_mfma_f32_16x16x32_bf16 v[24:27], v[162:165], v[202:205], 0
	v_mfma_f32_16x16x32_bf16 v[12:15], v[144:147], v[210:213], 0
	v_mfma_f32_16x16x32_bf16 v[8:11], v[162:165], v[210:213], 0
	v_mfma_f32_16x16x32_bf16 v[60:63], v[158:161], v[190:193], v[60:63]
	v_mfma_f32_16x16x32_bf16 v[56:59], v[166:169], v[190:193], v[56:59]
	v_mfma_f32_16x16x32_bf16 v[44:47], v[158:161], v[198:201], v[44:47]
	v_mfma_f32_16x16x32_bf16 v[40:43], v[166:169], v[198:201], v[40:43]
	v_mfma_f32_16x16x32_bf16 v[28:31], v[158:161], v[206:209], v[28:31]
	v_mfma_f32_16x16x32_bf16 v[24:27], v[166:169], v[206:209], v[24:27]
	v_mfma_f32_16x16x32_bf16 v[12:15], v[158:161], v[214:217], v[12:15]
	v_mfma_f32_16x16x32_bf16 v[8:11], v[166:169], v[214:217], v[8:11]
	s_setprio 0
	s_setprio 1
	v_mfma_f32_16x16x32_bf16 v[52:55], v[170:173], v[186:189], 0
	v_mfma_f32_16x16x32_bf16 v[48:51], v[178:181], v[186:189], 0
	v_mfma_f32_16x16x32_bf16 v[36:39], v[170:173], v[194:197], 0
	v_mfma_f32_16x16x32_bf16 v[32:35], v[178:181], v[194:197], 0
	v_mfma_f32_16x16x32_bf16 v[20:23], v[170:173], v[202:205], 0
	v_mfma_f32_16x16x32_bf16 v[16:19], v[178:181], v[202:205], 0
	v_mfma_f32_16x16x32_bf16 v[4:7], v[170:173], v[210:213], 0
	v_mfma_f32_16x16x32_bf16 v[0:3], v[178:181], v[210:213], 0
	v_mfma_f32_16x16x32_bf16 v[52:55], v[174:177], v[190:193], v[52:55]
	v_mfma_f32_16x16x32_bf16 v[48:51], v[182:185], v[190:193], v[48:51]
	v_mfma_f32_16x16x32_bf16 v[36:39], v[174:177], v[198:201], v[36:39]
	v_mfma_f32_16x16x32_bf16 v[32:35], v[182:185], v[198:201], v[32:35]
	v_mfma_f32_16x16x32_bf16 v[20:23], v[174:177], v[206:209], v[20:23]
	v_mfma_f32_16x16x32_bf16 v[16:19], v[182:185], v[206:209], v[16:19]
	v_mfma_f32_16x16x32_bf16 v[4:7], v[174:177], v[214:217], v[4:7]
	v_mfma_f32_16x16x32_bf16 v[0:3], v[182:185], v[214:217], v[0:3]
	s_setprio 0
	s_barrier
	s_add_i32 s33, 0, 0x18000
	v_add_u32_e32 v155, s33, v149
	s_add_i32 s64, 0, 0x1c000
	ds_read_b128 v[144:147], v155
	ds_read_b128 v[158:161], v155 offset:1024
	ds_read_b128 v[162:165], v155 offset:2048
	ds_read_b128 v[166:169], v155 offset:3072
	v_add_u32_e32 v155, s64, v149
	ds_read_b128 v[170:173], v155
	ds_read_b128 v[174:177], v155 offset:1024
	ds_read_b128 v[178:181], v155 offset:2048
	ds_read_b128 v[182:185], v155 offset:3072
	s_add_u32 s36, s36, 0x40000
	s_addc_u32 s37, s37, 0
	s_mov_b32 m0, s42
	v_lshl_add_u64 v[226:227], s[36:37], 0, v[128:129]
	ds_read_b128 v[186:189], v153 offset:32768
	ds_read_b128 v[190:193], v153 offset:33792
	ds_read_b128 v[194:197], v153 offset:34816
	ds_read_b128 v[198:201], v153 offset:35840
	ds_read_b128 v[202:205], v153 offset:36864
	ds_read_b128 v[206:209], v153 offset:37888
	ds_read_b128 v[210:213], v153 offset:38912
	ds_read_b128 v[214:217], v153 offset:39936
	global_load_lds_dwordx4 v[226:227], off
	v_lshl_add_u64 v[226:227], s[36:37], 0, v[132:133]
	s_mov_b32 m0, s43
	s_nop 0
	global_load_lds_dwordx4 v[226:227], off
	s_waitcnt vmcnt(8)
	s_waitcnt lgkmcnt(0)
	s_barrier
	s_setprio 1
	s_waitcnt lgkmcnt(0)
	v_mfma_f32_16x16x32_bf16 v[124:127], v[144:147], v[186:189], v[124:127]
	v_mfma_f32_16x16x32_bf16 v[120:123], v[162:165], v[186:189], v[120:123]
	v_mfma_f32_16x16x32_bf16 v[108:111], v[144:147], v[194:197], v[108:111]
	v_mfma_f32_16x16x32_bf16 v[104:107], v[162:165], v[194:197], v[104:107]
	v_mfma_f32_16x16x32_bf16 v[92:95], v[144:147], v[202:205], v[92:95]
	v_mfma_f32_16x16x32_bf16 v[88:91], v[162:165], v[202:205], v[88:91]
	v_mfma_f32_16x16x32_bf16 v[76:79], v[144:147], v[210:213], v[76:79]
	v_mfma_f32_16x16x32_bf16 v[72:75], v[162:165], v[210:213], v[72:75]
	v_mfma_f32_16x16x32_bf16 v[124:127], v[158:161], v[190:193], v[124:127]
	v_mfma_f32_16x16x32_bf16 v[120:123], v[166:169], v[190:193], v[120:123]
	v_mfma_f32_16x16x32_bf16 v[108:111], v[158:161], v[198:201], v[108:111]
	v_mfma_f32_16x16x32_bf16 v[104:107], v[166:169], v[198:201], v[104:107]
	v_mfma_f32_16x16x32_bf16 v[92:95], v[158:161], v[206:209], v[92:95]
	v_mfma_f32_16x16x32_bf16 v[88:91], v[166:169], v[206:209], v[88:91]
	v_mfma_f32_16x16x32_bf16 v[76:79], v[158:161], v[214:217], v[76:79]
	v_mfma_f32_16x16x32_bf16 v[72:75], v[166:169], v[214:217], v[72:75]
	s_setprio 0
	s_setprio 1
	v_mfma_f32_16x16x32_bf16 v[116:119], v[170:173], v[186:189], v[116:119]
	v_mfma_f32_16x16x32_bf16 v[112:115], v[178:181], v[186:189], v[112:115]
	v_mfma_f32_16x16x32_bf16 v[100:103], v[170:173], v[194:197], v[100:103]
	v_mfma_f32_16x16x32_bf16 v[96:99], v[178:181], v[194:197], v[96:99]
	v_mfma_f32_16x16x32_bf16 v[84:87], v[170:173], v[202:205], v[84:87]
	v_mfma_f32_16x16x32_bf16 v[80:83], v[178:181], v[202:205], v[80:83]
	v_mfma_f32_16x16x32_bf16 v[68:71], v[170:173], v[210:213], v[68:71]
	v_mfma_f32_16x16x32_bf16 v[64:67], v[178:181], v[210:213], v[64:67]
	v_mfma_f32_16x16x32_bf16 v[116:119], v[174:177], v[190:193], v[116:119]
	v_mfma_f32_16x16x32_bf16 v[112:115], v[182:185], v[190:193], v[112:115]
	v_mfma_f32_16x16x32_bf16 v[100:103], v[174:177], v[198:201], v[100:103]
	v_mfma_f32_16x16x32_bf16 v[96:99], v[182:185], v[198:201], v[96:99]
	v_mfma_f32_16x16x32_bf16 v[84:87], v[174:177], v[206:209], v[84:87]
	v_mfma_f32_16x16x32_bf16 v[80:83], v[182:185], v[206:209], v[80:83]
	v_mfma_f32_16x16x32_bf16 v[68:71], v[174:177], v[214:217], v[68:71]
	v_mfma_f32_16x16x32_bf16 v[64:67], v[182:185], v[214:217], v[64:67]
	s_setprio 0
	s_barrier
; #define PG8_STAGE(bufoff, gbase, voff) do { _Pragma("unroll") for (int _i = 0; _i < 2; ++_i) \
;         __builtin_amdgcn_global_load_lds((const unsigned*)((const char*)(gbase) + (voff)[_i]), (LAS unsigned*)(lds + (bufoff) + ldsw + _i * 8192), 16, 0, 0); } while (0)
; #define PG8_LDA(dst, b, h) do { _Pragma("unroll") for (int m = 0; m < 4; ++m) _Pragma("unroll") for (int k = 0; k < 2; ++k) dst[m][k] = *(const LAS bf16x8*)(lds + PG8_SA(b, h) + aoff + m * 2048 + k * 1024); } while (0)
; #define PG8_MMA(ai, bj, At, Bt) do { __builtin_amdgcn_s_setprio(1); _Pragma("unroll") for (int m = 0; m < 4; ++m) _Pragma("unroll") for (int n = 0; n < 2; ++n) _Pragma("unroll") for (int k = 0; k < 2; ++k) \
;         acc[ai][bj][m][n] = __builtin_amdgcn_mfma_f32_16x16x32_bf16(Bt[n][k], At[m][k], acc[ai][bj][m][n], 0, 0, 0); __builtin_amdgcn_s_setprio(0); } while (0)
; #define PG8_WAIT_V(n) asm volatile("s_waitcnt vmcnt(" #n ")" ::: "memory")
; #define PG8_WAIT_L(n) asm volatile("s_waitcnt lgkmcnt(" #n ")" ::: "memory")
; #define PG8_BAR __builtin_amdgcn_s_barrier()
; #define PG8_SCHED __builtin_amdgcn_sched_barrier(0)
; template <class Epi>
; __device__ __forceinline__ void gemm_phase(LAS unsigned char* lds, const Gemm g, const StaticOrder& S, const Epi& E) {
;     ...
;             PG8_LDA(At, 1, 1); PG8_STAGE(PG8_SB(1, 0), b3, voffB); PG8_STAGE(PG8_SB(1, 1), b3 + hsB, voffB); PG8_STAGE(PG8_SA(1, 0), a3, voffA);
;             PG8_WAIT_V(8); PG8_WAIT_L(0); PG8_BAR; PG8_MMA(1, 0, At, B0); PG8_MMA(1, 1, At, B1); PG8_BAR; PG8_SCHED;
;         }
	s_add_i32 s33, s33, s40
	v_lshl_add_u64 v[218:219], v[218:219], 0, s[10:11]
	s_mov_b32 m0, s33
	ds_read_b128 v[186:189], v153 offset:49152
	ds_read_b128 v[190:193], v153 offset:50176
	ds_read_b128 v[194:197], v153 offset:51200
	ds_read_b128 v[198:201], v153 offset:52224
	ds_read_b128 v[202:205], v153 offset:53248
	ds_read_b128 v[206:209], v153 offset:54272
	ds_read_b128 v[210:213], v153 offset:55296
	ds_read_b128 v[214:217], v153 offset:56320
	global_load_lds_dwordx4 v[218:219], off
	s_add_i32 m0, s33, 0x2000
	s_add_u32 s28, s28, 0x40080
	v_lshl_add_u64 v[218:219], v[220:221], 0, s[10:11]
	s_addc_u32 s29, s29, 0
	s_add_i32 s33, s64, s40
	global_load_lds_dwordx4 v[218:219], off
	v_lshl_add_u64 v[218:219], s[28:29], 0, v[130:131]
	s_mov_b32 m0, s33
	s_nop 0
	global_load_lds_dwordx4 v[218:219], off
	v_lshl_add_u64 v[218:219], s[28:29], 0, v[134:135]
	s_add_i32 m0, s33, 0x2000
	s_nop 0
	global_load_lds_dwordx4 v[218:219], off
	v_lshl_add_u64 v[218:219], v[222:223], 0, s[10:11]
	s_mov_b32 m0, s49
	s_nop 0
	global_load_lds_dwordx4 v[218:219], off
	v_lshl_add_u64 v[218:219], v[224:225], 0, s[10:11]
	s_mov_b32 m0, s50
	s_nop 0
	global_load_lds_dwordx4 v[218:219], off
	s_waitcnt vmcnt(8)
	s_waitcnt lgkmcnt(0)
	s_barrier
	s_setprio 1
	s_waitcnt lgkmcnt(0)
	v_mfma_f32_16x16x32_bf16 v[60:63], v[144:147], v[186:189], v[60:63]
	v_mfma_f32_16x16x32_bf16 v[56:59], v[162:165], v[186:189], v[56:59]
	v_mfma_f32_16x16x32_bf16 v[44:47], v[144:147], v[194:197], v[44:47]
	v_mfma_f32_16x16x32_bf16 v[40:43], v[162:165], v[194:197], v[40:43]
	v_mfma_f32_16x16x32_bf16 v[28:31], v[144:147], v[202:205], v[28:31]
	v_mfma_f32_16x16x32_bf16 v[24:27], v[162:165], v[202:205], v[24:27]
	v_mfma_f32_16x16x32_bf16 v[12:15], v[144:147], v[210:213], v[12:15]
	v_mfma_f32_16x16x32_bf16 v[8:11], v[162:165], v[210:213], v[8:11]
	v_mfma_f32_16x16x32_bf16 v[60:63], v[158:161], v[190:193], v[60:63]
	v_mfma_f32_16x16x32_bf16 v[56:59], v[166:169], v[190:193], v[56:59]
	v_mfma_f32_16x16x32_bf16 v[44:47], v[158:161], v[198:201], v[44:47]
	v_mfma_f32_16x16x32_bf16 v[40:43], v[166:169], v[198:201], v[40:43]
	v_mfma_f32_16x16x32_bf16 v[28:31], v[158:161], v[206:209], v[28:31]
	v_mfma_f32_16x16x32_bf16 v[24:27], v[166:169], v[206:209], v[24:27]
	v_mfma_f32_16x16x32_bf16 v[12:15], v[158:161], v[214:217], v[12:15]
	v_mfma_f32_16x16x32_bf16 v[8:11], v[166:169], v[214:217], v[8:11]
	s_setprio 0
	s_setprio 1
	v_mfma_f32_16x16x32_bf16 v[52:55], v[170:173], v[186:189], v[52:55]
	v_mfma_f32_16x16x32_bf16 v[48:51], v[178:181], v[186:189], v[48:51]
	v_mfma_f32_16x16x32_bf16 v[36:39], v[170:173], v[194:197], v[36:39]
	v_mfma_f32_16x16x32_bf16 v[32:35], v[178:181], v[194:197], v[32:35]
	v_mfma_f32_16x16x32_bf16 v[20:23], v[170:173], v[202:205], v[20:23]
	v_mfma_f32_16x16x32_bf16 v[16:19], v[178:181], v[202:205], v[16:19]
	v_mfma_f32_16x16x32_bf16 v[4:7], v[170:173], v[210:213], v[4:7]
	v_mfma_f32_16x16x32_bf16 v[0:3], v[178:181], v[210:213], v[0:3]
	v_mfma_f32_16x16x32_bf16 v[52:55], v[174:177], v[190:193], v[52:55]
	v_mfma_f32_16x16x32_bf16 v[48:51], v[182:185], v[190:193], v[48:51]
	v_mfma_f32_16x16x32_bf16 v[36:39], v[174:177], v[198:201], v[36:39]
	v_mfma_f32_16x16x32_bf16 v[32:35], v[182:185], v[198:201], v[32:35]
	v_mfma_f32_16x16x32_bf16 v[20:23], v[174:177], v[206:209], v[20:23]
	v_mfma_f32_16x16x32_bf16 v[16:19], v[182:185], v[206:209], v[16:19]
	v_mfma_f32_16x16x32_bf16 v[4:7], v[174:177], v[214:217], v[4:7]
	v_mfma_f32_16x16x32_bf16 v[0:3], v[182:185], v[214:217], v[0:3]
	s_setprio 0
	s_barrier
	s_add_i32 s63, s63, 2
	s_add_u32 s26, s26, 0x100
	s_addc_u32 s27, s27, 0
	s_add_u32 s61, s61, 0x100
	s_addc_u32 s62, s62, 0
	s_cmp_gt_u32 s63, 13
	s_cbranch_scc0 .LBB0_1474
	s_branch .Lpeel_exit6

; #define PG8_STAGE(bufoff, gbase, voff) do { _Pragma("unroll") for (int _i = 0; _i < 2; ++_i) \
;         __builtin_amdgcn_global_load_lds((const unsigned*)((const char*)(gbase) + (voff)[_i]), (LAS unsigned*)(lds + (bufoff) + ldsw + _i * 8192), 16, 0, 0); } while (0)
; #define PG8_LDA(dst, b, h) do { _Pragma("unroll") for (int m = 0; m < 4; ++m) _Pragma("unroll") for (int k = 0; k < 2; ++k) dst[m][k] = *(const LAS bf16x8*)(lds + PG8_SA(b, h) + aoff + m * 2048 + k * 1024); } while (0)
; #define PG8_LDB(dst, b, h) do { _Pragma("unroll") for (int n = 0; n < 2; ++n) _Pragma("unroll") for (int k = 0; k < 2; ++k) dst[n][k] = *(const LAS bf16x8*)(lds + PG8_SB(b, h) + boff + n * 2048 + k * 1024); } while (0)
; #define PG8_MMA(ai, bj, At, Bt) do { __builtin_amdgcn_s_setprio(1); _Pragma("unroll") for (int m = 0; m < 4; ++m) _Pragma("unroll") for (int n = 0; n < 2; ++n) _Pragma("unroll") for (int k = 0; k < 2; ++k) \
;         acc[ai][bj][m][n] = __builtin_amdgcn_mfma_f32_16x16x32_bf16(Bt[n][k], At[m][k], acc[ai][bj][m][n], 0, 0, 0); __builtin_amdgcn_s_setprio(0); } while (0)
; #define PG8_WAIT_V(n) asm volatile("s_waitcnt vmcnt(" #n ")" ::: "memory")
; template <class Epi>
; __device__ __forceinline__ void gemm_phase(LAS unsigned char* lds, const Gemm g, const StaticOrder& S, const Epi& E) {
;     ...
;         const bool has_next = S.next(ui + 1, nxt);
;         const char* nA = has_next ? (const char*)g.A + (size_t)nxt.pm * tsA : cA; const char* nB = has_next ? (const char*)g.Bt + (size_t)nxt.pn * tsB : cB;
;         for (int t = 0; t < nt; t += 2) {
;             const bool last = (t == nt - 2);
;             const char* a1 = cA + (size_t)(t + 1) * kstep;
;             const char* a2 = last ? nA : cA + (size_t)(t + 2) * kstep; const char* b2 = last ? nB : cB + (size_t)(t + 2) * kstep;
;             const char* a3 = a2 + kstep; const char* b3 = b2 + kstep;
;             PG8_LDB(B0, 0, 0); PG8_LDB(B1, 0, 1); PG8_SCHED; PG8_LDA(At, 0, 0); PG8_STAGE(PG8_SA(1, 1), a1 + hsA, voffA);
;             PG8_WAIT_V(8); PG8_WAIT_L(0); PG8_BAR; PG8_MMA(0, 0, At, B0); PG8_MMA(0, 1, At, B1); PG8_BAR; PG8_SCHED;
;             PG8_LDA(At, 0, 1); PG8_STAGE(PG8_SB(0, 0), b2, voffB); PG8_STAGE(PG8_SB(0, 1), b2 + hsB, voffB); PG8_STAGE(PG8_SA(0, 0), a2, voffA);
;             PG8_WAIT_V(8); PG8_WAIT_L(0); PG8_BAR; PG8_MMA(1, 0, At, B0); PG8_MMA(1, 1, At, B1); PG8_BAR; PG8_SCHED;
.LBB0_1557:
	s_ashr_i32 s17, s16, 31
	s_lshl_b64 s[18:19], s[16:17], 19
	s_add_u32 s18, s46, s18
	s_addc_u32 s19, s47, s19
	s_and_b64 s[20:21], s[4:5], exec
	s_cselect_b32 s17, s19, s23
	s_cselect_b32 s56, s18, s22
	s_ashr_i32 s15, s14, 31
	s_lshl_b64 s[20:21], s[14:15], 19
	s_add_u32 s20, s28, s20
	s_addc_u32 s21, s29, s21
	s_and_b64 s[26:27], s[4:5], exec
	s_cselect_b32 s15, s21, s25
	s_cselect_b32 s57, s20, s24
	s_add_u32 s22, s22, 0x40080
	s_addc_u32 s23, s23, 0
	s_add_u32 s58, s24, 0x100
	s_addc_u32 s59, s25, 0
	s_mov_b32 s60, -2
	ds_read_b128 v[144:147], v151
	ds_read_b128 v[158:161], v151 offset:1024
	ds_read_b128 v[162:165], v151 offset:2048
	ds_read_b128 v[166:169], v151 offset:3072
	ds_read_b128 v[170:173], v152
	ds_read_b128 v[174:177], v152 offset:1024
	ds_read_b128 v[178:181], v152 offset:2048
	ds_read_b128 v[182:185], v152 offset:3072
	s_add_u32 s24, s22, 0xfffc0080
	s_addc_u32 s25, s23, -1
	s_cmp_eq_u32 s60, 12
	s_cselect_b32 s27, s17, s25
	s_cselect_b32 s26, s56, s24
	s_cselect_b32 s25, s15, s59
	s_cselect_b32 s24, s57, s58
	v_lshl_add_u64 v[218:219], s[22:23], 0, v[136:137]
	s_add_i32 m0, s39, 0xc000
	ds_read_b128 v[186:189], v153
	ds_read_b128 v[190:193], v153 offset:1024
	ds_read_b128 v[194:197], v153 offset:2048
	ds_read_b128 v[198:201], v153 offset:3072
	ds_read_b128 v[202:205], v153 offset:4096
	ds_read_b128 v[206:209], v153 offset:5120
	ds_read_b128 v[210:213], v153 offset:6144
	ds_read_b128 v[214:217], v153 offset:7168
	global_load_lds_dwordx4 v[218:219], off
	v_lshl_add_u64 v[218:219], s[22:23], 0, v[138:139]
	s_add_i32 m0, s39, 0xe000
	s_nop 0
	global_load_lds_dwordx4 v[218:219], off
	s_waitcnt vmcnt(8)
	s_waitcnt lgkmcnt(0)
	s_barrier
	s_setprio 1
	s_waitcnt lgkmcnt(0)
	v_mfma_f32_16x16x32_bf16 v[124:127], v[144:147], v[186:189], 0
	v_mfma_f32_16x16x32_bf16 v[120:123], v[162:165], v[186:189], 0
	v_mfma_f32_16x16x32_bf16 v[108:111], v[144:147], v[194:197], 0
	v_mfma_f32_16x16x32_bf16 v[104:107], v[162:165], v[194:197], 0
	v_mfma_f32_16x16x32_bf16 v[92:95], v[144:147], v[202:205], 0
	v_mfma_f32_16x16x32_bf16 v[88:91], v[162:165], v[202:205], 0
	v_mfma_f32_16x16x32_bf16 v[76:79], v[144:147], v[210:213], 0
	v_mfma_f32_16x16x32_bf16 v[72:75], v[162:165], v[210:213], 0
	v_mfma_f32_16x16x32_bf16 v[124:127], v[158:161], v[190:193], v[124:127]
	v_mfma_f32_16x16x32_bf16 v[120:123], v[166:169], v[190:193], v[120:123]
	v_mfma_f32_16x16x32_bf16 v[108:111], v[158:161], v[198:201], v[108:111]
	v_mfma_f32_16x16x32_bf16 v[104:107], v[166:169], v[198:201], v[104:107]
	v_mfma_f32_16x16x32_bf16 v[92:95], v[158:161], v[206:209], v[92:95]
	v_mfma_f32_16x16x32_bf16 v[88:91], v[166:169], v[206:209], v[88:91]
	v_mfma_f32_16x16x32_bf16 v[76:79], v[158:161], v[214:217], v[76:79]
	v_mfma_f32_16x16x32_bf16 v[72:75], v[166:169], v[214:217], v[72:75]
	s_setprio 0
	s_setprio 1
	v_mfma_f32_16x16x32_bf16 v[116:119], v[170:173], v[186:189], 0
	v_mfma_f32_16x16x32_bf16 v[112:115], v[178:181], v[186:189], 0
	v_mfma_f32_16x16x32_bf16 v[100:103], v[170:173], v[194:197], 0
	v_mfma_f32_16x16x32_bf16 v[96:99], v[178:181], v[194:197], 0
	v_mfma_f32_16x16x32_bf16 v[84:87], v[170:173], v[202:205], 0
	v_mfma_f32_16x16x32_bf16 v[80:83], v[178:181], v[202:205], 0
	v_mfma_f32_16x16x32_bf16 v[68:71], v[170:173], v[210:213], 0
	v_mfma_f32_16x16x32_bf16 v[64:67], v[178:181], v[210:213], 0
	v_mfma_f32_16x16x32_bf16 v[116:119], v[174:177], v[190:193], v[116:119]
	v_mfma_f32_16x16x32_bf16 v[112:115], v[182:185], v[190:193], v[112:115]
	v_mfma_f32_16x16x32_bf16 v[100:103], v[174:177], v[198:201], v[100:103]
	v_mfma_f32_16x16x32_bf16 v[96:99], v[182:185], v[198:201], v[96:99]
	v_mfma_f32_16x16x32_bf16 v[84:87], v[174:177], v[206:209], v[84:87]
	v_mfma_f32_16x16x32_bf16 v[80:83], v[182:185], v[206:209], v[80:83]
	v_mfma_f32_16x16x32_bf16 v[68:71], v[174:177], v[214:217], v[68:71]
	v_mfma_f32_16x16x32_bf16 v[64:67], v[182:185], v[214:217], v[64:67]
	s_setprio 0
	s_barrier
	s_add_i32 s33, s52, s36
	v_lshl_add_u64 v[218:219], s[24:25], 0, v[132:133]
	s_mov_b32 m0, s33
	ds_read_b128 v[186:189], v153 offset:16384
	ds_read_b128 v[190:193], v153 offset:17408
	ds_read_b128 v[194:197], v153 offset:18432
	ds_read_b128 v[198:201], v153 offset:19456
	ds_read_b128 v[202:205], v153 offset:20480
	ds_read_b128 v[206:209], v153 offset:21504
	ds_read_b128 v[210:213], v153 offset:22528
	ds_read_b128 v[214:217], v153 offset:23552
	global_load_lds_dwordx4 v[218:219], off
	s_add_i32 m0, s33, 0x2000
	s_add_u32 s62, s24, 0x40000
	v_lshl_add_u64 v[220:221], s[24:25], 0, v[128:129]
	s_addc_u32 s63, s25, 0
	s_add_i32 s33, s53, s36
	global_load_lds_dwordx4 v[220:221], off
	v_lshl_add_u64 v[222:223], s[62:63], 0, v[132:133]
	s_mov_b32 m0, s33
	v_lshl_add_u64 v[224:225], s[26:27], 0, v[130:131]
	global_load_lds_dwordx4 v[222:223], off
	v_lshl_add_u64 v[222:223], s[62:63], 0, v[128:129]
	s_add_i32 m0, s33, 0x2000
	s_nop 0
	global_load_lds_dwordx4 v[222:223], off
	v_lshl_add_u64 v[222:223], s[26:27], 0, v[134:135]
	s_mov_b32 m0, s39
	s_nop 0
	global_load_lds_dwordx4 v[222:223], off
	s_mov_b32 m0, s40
	s_nop 0
	global_load_lds_dwordx4 v[224:225], off
	s_waitcnt vmcnt(8)
	s_waitcnt lgkmcnt(0)
	s_barrier
; #define PG8_STAGE(bufoff, gbase, voff) do { _Pragma("unroll") for (int _i = 0; _i < 2; ++_i) \
;         __builtin_amdgcn_global_load_lds((const unsigned*)((const char*)(gbase) + (voff)[_i]), (LAS unsigned*)(lds + (bufoff) + ldsw + _i * 8192), 16, 0, 0); } while (0)
; #define PG8_LDA(dst, b, h) do { _Pragma("unroll") for (int m = 0; m < 4; ++m) _Pragma("unroll") for (int k = 0; k < 2; ++k) dst[m][k] = *(const LAS bf16x8*)(lds + PG8_SA(b, h) + aoff + m * 2048 + k * 1024); } while (0)
; #define PG8_LDB(dst, b, h) do { _Pragma("unroll") for (int n = 0; n < 2; ++n) _Pragma("unroll") for (int k = 0; k < 2; ++k) dst[n][k] = *(const LAS bf16x8*)(lds + PG8_SB(b, h) + boff + n * 2048 + k * 1024); } while (0)
; #define PG8_MMA(ai, bj, At, Bt) do { __builtin_amdgcn_s_setprio(1); _Pragma("unroll") for (int m = 0; m < 4; ++m) _Pragma("unroll") for (int n = 0; n < 2; ++n) _Pragma("unroll") for (int k = 0; k < 2; ++k) \
;         acc[ai][bj][m][n] = __builtin_amdgcn_mfma_f32_16x16x32_bf16(Bt[n][k], At[m][k], acc[ai][bj][m][n], 0, 0, 0); __builtin_amdgcn_s_setprio(0); } while (0)
; #define PG8_WAIT_V(n) asm volatile("s_waitcnt vmcnt(" #n ")" ::: "memory")
; #define PG8_WAIT_L(n) asm volatile("s_waitcnt lgkmcnt(" #n ")" ::: "memory")
; #define PG8_BAR __builtin_amdgcn_s_barrier()
; #define PG8_SCHED __builtin_amdgcn_sched_barrier(0)
; template <class Epi>
; __device__ __forceinline__ void gemm_phase(LAS unsigned char* lds, const Gemm g, const StaticOrder& S, const Epi& E) {
;     ...
;             PG8_WAIT_V(8); PG8_WAIT_L(0); PG8_BAR; PG8_MMA(1, 0, At, B0); PG8_MMA(1, 1, At, B1); PG8_BAR; PG8_SCHED;
;             PG8_LDB(B0, 1, 0); PG8_LDB(B1, 1, 1); PG8_SCHED; PG8_LDA(At, 1, 0); PG8_STAGE(PG8_SA(0, 1), a2 + hsA, voffA);
;             PG8_WAIT_V(8); PG8_WAIT_L(0); PG8_BAR; PG8_MMA(0, 0, At, B0); PG8_MMA(0, 1, At, B1); PG8_BAR; PG8_SCHED;
	s_setprio 1
	s_waitcnt lgkmcnt(0)
	v_mfma_f32_16x16x32_bf16 v[60:63], v[144:147], v[186:189], 0
	v_mfma_f32_16x16x32_bf16 v[56:59], v[162:165], v[186:189], 0
	v_mfma_f32_16x16x32_bf16 v[44:47], v[144:147], v[194:197], 0
	v_mfma_f32_16x16x32_bf16 v[40:43], v[162:165], v[194:197], 0
	v_mfma_f32_16x16x32_bf16 v[28:31], v[144:147], v[202:205], 0
	v_mfma_f32_16x16x32_bf16 v[24:27], v[162:165], v[202:205], 0
	v_mfma_f32_16x16x32_bf16 v[12:15], v[144:147], v[210:213], 0
	v_mfma_f32_16x16x32_bf16 v[8:11], v[162:165], v[210:213], 0
	v_mfma_f32_16x16x32_bf16 v[60:63], v[158:161], v[190:193], v[60:63]
	v_mfma_f32_16x16x32_bf16 v[56:59], v[166:169], v[190:193], v[56:59]
	v_mfma_f32_16x16x32_bf16 v[44:47], v[158:161], v[198:201], v[44:47]
	v_mfma_f32_16x16x32_bf16 v[40:43], v[166:169], v[198:201], v[40:43]
	v_mfma_f32_16x16x32_bf16 v[28:31], v[158:161], v[206:209], v[28:31]
	v_mfma_f32_16x16x32_bf16 v[24:27], v[166:169], v[206:209], v[24:27]
	v_mfma_f32_16x16x32_bf16 v[12:15], v[158:161], v[214:217], v[12:15]
	v_mfma_f32_16x16x32_bf16 v[8:11], v[166:169], v[214:217], v[8:11]
	s_setprio 0
	s_setprio 1
	v_mfma_f32_16x16x32_bf16 v[52:55], v[170:173], v[186:189], 0
	v_mfma_f32_16x16x32_bf16 v[48:51], v[178:181], v[186:189], 0
	v_mfma_f32_16x16x32_bf16 v[36:39], v[170:173], v[194:197], 0
	v_mfma_f32_16x16x32_bf16 v[32:35], v[178:181], v[194:197], 0
	v_mfma_f32_16x16x32_bf16 v[20:23], v[170:173], v[202:205], 0
	v_mfma_f32_16x16x32_bf16 v[16:19], v[178:181], v[202:205], 0
	v_mfma_f32_16x16x32_bf16 v[4:7], v[170:173], v[210:213], 0
	v_mfma_f32_16x16x32_bf16 v[0:3], v[178:181], v[210:213], 0
	v_mfma_f32_16x16x32_bf16 v[52:55], v[174:177], v[190:193], v[52:55]
	v_mfma_f32_16x16x32_bf16 v[48:51], v[182:185], v[190:193], v[48:51]
	v_mfma_f32_16x16x32_bf16 v[36:39], v[174:177], v[198:201], v[36:39]
	v_mfma_f32_16x16x32_bf16 v[32:35], v[182:185], v[198:201], v[32:35]
	v_mfma_f32_16x16x32_bf16 v[20:23], v[174:177], v[206:209], v[20:23]
	v_mfma_f32_16x16x32_bf16 v[16:19], v[182:185], v[206:209], v[16:19]
	v_mfma_f32_16x16x32_bf16 v[4:7], v[174:177], v[214:217], v[4:7]
	v_mfma_f32_16x16x32_bf16 v[0:3], v[182:185], v[214:217], v[0:3]
	s_setprio 0
	s_barrier
	s_add_i32 s33, 0, 0x18000
	v_add_u32_e32 v155, s33, v149
	s_add_i32 s61, 0, 0x1c000
	ds_read_b128 v[144:147], v155
	ds_read_b128 v[158:161], v155 offset:1024
	ds_read_b128 v[162:165], v155 offset:2048
	ds_read_b128 v[166:169], v155 offset:3072
	v_add_u32_e32 v155, s61, v149
	ds_read_b128 v[170:173], v155
	ds_read_b128 v[174:177], v155 offset:1024
	ds_read_b128 v[178:181], v155 offset:2048
	ds_read_b128 v[182:185], v155 offset:3072
	s_add_u32 s26, s26, 0x40000
	s_addc_u32 s27, s27, 0
	s_mov_b32 m0, s41
	v_lshl_add_u64 v[226:227], s[26:27], 0, v[134:135]
	ds_read_b128 v[186:189], v153 offset:32768
	ds_read_b128 v[190:193], v153 offset:33792
	ds_read_b128 v[194:197], v153 offset:34816
	ds_read_b128 v[198:201], v153 offset:35840
	ds_read_b128 v[202:205], v153 offset:36864
	ds_read_b128 v[206:209], v153 offset:37888
	ds_read_b128 v[210:213], v153 offset:38912
	ds_read_b128 v[214:217], v153 offset:39936
	global_load_lds_dwordx4 v[226:227], off
	v_lshl_add_u64 v[226:227], s[26:27], 0, v[130:131]
	s_mov_b32 m0, s42
	s_nop 0
	global_load_lds_dwordx4 v[226:227], off
	s_waitcnt vmcnt(8)
	s_waitcnt lgkmcnt(0)
	s_barrier
	s_setprio 1
	s_waitcnt lgkmcnt(0)
	v_mfma_f32_16x16x32_bf16 v[124:127], v[144:147], v[186:189], v[124:127]
	v_mfma_f32_16x16x32_bf16 v[120:123], v[162:165], v[186:189], v[120:123]
	v_mfma_f32_16x16x32_bf16 v[108:111], v[144:147], v[194:197], v[108:111]
	v_mfma_f32_16x16x32_bf16 v[104:107], v[162:165], v[194:197], v[104:107]
	v_mfma_f32_16x16x32_bf16 v[92:95], v[144:147], v[202:205], v[92:95]
	v_mfma_f32_16x16x32_bf16 v[88:91], v[162:165], v[202:205], v[88:91]
	v_mfma_f32_16x16x32_bf16 v[76:79], v[144:147], v[210:213], v[76:79]
	v_mfma_f32_16x16x32_bf16 v[72:75], v[162:165], v[210:213], v[72:75]
	v_mfma_f32_16x16x32_bf16 v[124:127], v[158:161], v[190:193], v[124:127]
	v_mfma_f32_16x16x32_bf16 v[120:123], v[166:169], v[190:193], v[120:123]
	v_mfma_f32_16x16x32_bf16 v[108:111], v[158:161], v[198:201], v[108:111]
	v_mfma_f32_16x16x32_bf16 v[104:107], v[166:169], v[198:201], v[104:107]
	v_mfma_f32_16x16x32_bf16 v[92:95], v[158:161], v[206:209], v[92:95]
	v_mfma_f32_16x16x32_bf16 v[88:91], v[166:169], v[206:209], v[88:91]
	v_mfma_f32_16x16x32_bf16 v[76:79], v[158:161], v[214:217], v[76:79]
	v_mfma_f32_16x16x32_bf16 v[72:75], v[166:169], v[214:217], v[72:75]
	s_setprio 0
	s_setprio 1
	v_mfma_f32_16x16x32_bf16 v[116:119], v[170:173], v[186:189], v[116:119]
	v_mfma_f32_16x16x32_bf16 v[112:115], v[178:181], v[186:189], v[112:115]
	v_mfma_f32_16x16x32_bf16 v[100:103], v[170:173], v[194:197], v[100:103]
	v_mfma_f32_16x16x32_bf16 v[96:99], v[178:181], v[194:197], v[96:99]
	v_mfma_f32_16x16x32_bf16 v[84:87], v[170:173], v[202:205], v[84:87]
	v_mfma_f32_16x16x32_bf16 v[80:83], v[178:181], v[202:205], v[80:83]
	v_mfma_f32_16x16x32_bf16 v[68:71], v[170:173], v[210:213], v[68:71]
	v_mfma_f32_16x16x32_bf16 v[64:67], v[178:181], v[210:213], v[64:67]
	v_mfma_f32_16x16x32_bf16 v[116:119], v[174:177], v[190:193], v[116:119]
	v_mfma_f32_16x16x32_bf16 v[112:115], v[182:185], v[190:193], v[112:115]
	v_mfma_f32_16x16x32_bf16 v[100:103], v[174:177], v[198:201], v[100:103]
	v_mfma_f32_16x16x32_bf16 v[96:99], v[182:185], v[198:201], v[96:99]
	v_mfma_f32_16x16x32_bf16 v[84:87], v[174:177], v[206:209], v[84:87]
	v_mfma_f32_16x16x32_bf16 v[80:83], v[182:185], v[206:209], v[80:83]
	v_mfma_f32_16x16x32_bf16 v[68:71], v[174:177], v[214:217], v[68:71]
	v_mfma_f32_16x16x32_bf16 v[64:67], v[182:185], v[214:217], v[64:67]
	s_setprio 0
	s_barrier
; #define PG8_STAGE(bufoff, gbase, voff) do { _Pragma("unroll") for (int _i = 0; _i < 2; ++_i) \
;         __builtin_amdgcn_global_load_lds((const unsigned*)((const char*)(gbase) + (voff)[_i]), (LAS unsigned*)(lds + (bufoff) + ldsw + _i * 8192), 16, 0, 0); } while (0)
; #define PG8_LDA(dst, b, h) do { _Pragma("unroll") for (int m = 0; m < 4; ++m) _Pragma("unroll") for (int k = 0; k < 2; ++k) dst[m][k] = *(const LAS bf16x8*)(lds + PG8_SA(b, h) + aoff + m * 2048 + k * 1024); } while (0)
; #define PG8_MMA(ai, bj, At, Bt) do { __builtin_amdgcn_s_setprio(1); _Pragma("unroll") for (int m = 0; m < 4; ++m) _Pragma("unroll") for (int n = 0; n < 2; ++n) _Pragma("unroll") for (int k = 0; k < 2; ++k) \
;         acc[ai][bj][m][n] = __builtin_amdgcn_mfma_f32_16x16x32_bf16(Bt[n][k], At[m][k], acc[ai][bj][m][n], 0, 0, 0); __builtin_amdgcn_s_setprio(0); } while (0)
; #define PG8_WAIT_V(n) asm volatile("s_waitcnt vmcnt(" #n ")" ::: "memory")
; #define PG8_WAIT_L(n) asm volatile("s_waitcnt lgkmcnt(" #n ")" ::: "memory")
; #define PG8_BAR __builtin_amdgcn_s_barrier()
; #define PG8_SCHED __builtin_amdgcn_sched_barrier(0)
; template <class Epi>
; __device__ __forceinline__ void gemm_phase(LAS unsigned char* lds, const Gemm g, const StaticOrder& S, const Epi& E) {
;     ...
;             PG8_LDA(At, 1, 1); PG8_STAGE(PG8_SB(1, 0), b3, voffB); PG8_STAGE(PG8_SB(1, 1), b3 + hsB, voffB); PG8_STAGE(PG8_SA(1, 0), a3, voffA);
;             PG8_WAIT_V(8); PG8_WAIT_L(0); PG8_BAR; PG8_MMA(1, 0, At, B0); PG8_MMA(1, 1, At, B1); PG8_BAR; PG8_SCHED;
;         }
	s_add_i32 s26, s33, s36
	v_lshl_add_u64 v[218:219], v[218:219], 0, s[10:11]
	s_mov_b32 m0, s26
	ds_read_b128 v[186:189], v153 offset:49152
	ds_read_b128 v[190:193], v153 offset:50176
	ds_read_b128 v[194:197], v153 offset:51200
	ds_read_b128 v[198:201], v153 offset:52224
	ds_read_b128 v[202:205], v153 offset:53248
	ds_read_b128 v[206:209], v153 offset:54272
	ds_read_b128 v[210:213], v153 offset:55296
	ds_read_b128 v[214:217], v153 offset:56320
	global_load_lds_dwordx4 v[218:219], off
	s_add_i32 m0, s26, 0x2000
	s_add_u32 s24, s24, 0x40080
	v_lshl_add_u64 v[218:219], v[220:221], 0, s[10:11]
	s_addc_u32 s25, s25, 0
	s_add_i32 s26, s61, s36
	global_load_lds_dwordx4 v[218:219], off
	v_lshl_add_u64 v[218:219], s[24:25], 0, v[132:133]
	s_mov_b32 m0, s26
	s_nop 0
	global_load_lds_dwordx4 v[218:219], off
	v_lshl_add_u64 v[218:219], s[24:25], 0, v[128:129]
	s_add_i32 m0, s26, 0x2000
	s_nop 0
	global_load_lds_dwordx4 v[218:219], off
	v_lshl_add_u64 v[218:219], v[222:223], 0, s[10:11]
	s_mov_b32 m0, s48
	s_nop 0
	global_load_lds_dwordx4 v[218:219], off
	v_lshl_add_u64 v[218:219], v[224:225], 0, s[10:11]
	s_mov_b32 m0, s49
	s_nop 0
	global_load_lds_dwordx4 v[218:219], off
	s_waitcnt vmcnt(8)
	s_waitcnt lgkmcnt(0)
	s_barrier
	s_setprio 1
	s_waitcnt lgkmcnt(0)
	v_mfma_f32_16x16x32_bf16 v[60:63], v[144:147], v[186:189], v[60:63]
	v_mfma_f32_16x16x32_bf16 v[56:59], v[162:165], v[186:189], v[56:59]
	v_mfma_f32_16x16x32_bf16 v[44:47], v[144:147], v[194:197], v[44:47]
	v_mfma_f32_16x16x32_bf16 v[40:43], v[162:165], v[194:197], v[40:43]
	v_mfma_f32_16x16x32_bf16 v[28:31], v[144:147], v[202:205], v[28:31]
	v_mfma_f32_16x16x32_bf16 v[24:27], v[162:165], v[202:205], v[24:27]
	v_mfma_f32_16x16x32_bf16 v[12:15], v[144:147], v[210:213], v[12:15]
	v_mfma_f32_16x16x32_bf16 v[8:11], v[162:165], v[210:213], v[8:11]
	v_mfma_f32_16x16x32_bf16 v[60:63], v[158:161], v[190:193], v[60:63]
	v_mfma_f32_16x16x32_bf16 v[56:59], v[166:169], v[190:193], v[56:59]
	v_mfma_f32_16x16x32_bf16 v[44:47], v[158:161], v[198:201], v[44:47]
	v_mfma_f32_16x16x32_bf16 v[40:43], v[166:169], v[198:201], v[40:43]
	v_mfma_f32_16x16x32_bf16 v[28:31], v[158:161], v[206:209], v[28:31]
	v_mfma_f32_16x16x32_bf16 v[24:27], v[166:169], v[206:209], v[24:27]
	v_mfma_f32_16x16x32_bf16 v[12:15], v[158:161], v[214:217], v[12:15]
	v_mfma_f32_16x16x32_bf16 v[8:11], v[166:169], v[214:217], v[8:11]
	s_setprio 0
	s_setprio 1
	v_mfma_f32_16x16x32_bf16 v[52:55], v[170:173], v[186:189], v[52:55]
	v_mfma_f32_16x16x32_bf16 v[48:51], v[178:181], v[186:189], v[48:51]
	v_mfma_f32_16x16x32_bf16 v[36:39], v[170:173], v[194:197], v[36:39]
	v_mfma_f32_16x16x32_bf16 v[32:35], v[178:181], v[194:197], v[32:35]
	v_mfma_f32_16x16x32_bf16 v[20:23], v[170:173], v[202:205], v[20:23]
	v_mfma_f32_16x16x32_bf16 v[16:19], v[178:181], v[202:205], v[16:19]
	v_mfma_f32_16x16x32_bf16 v[4:7], v[170:173], v[210:213], v[4:7]
	v_mfma_f32_16x16x32_bf16 v[0:3], v[178:181], v[210:213], v[0:3]
	v_mfma_f32_16x16x32_bf16 v[52:55], v[174:177], v[190:193], v[52:55]
	v_mfma_f32_16x16x32_bf16 v[48:51], v[182:185], v[190:193], v[48:51]
	v_mfma_f32_16x16x32_bf16 v[36:39], v[174:177], v[198:201], v[36:39]
	v_mfma_f32_16x16x32_bf16 v[32:35], v[182:185], v[198:201], v[32:35]
	v_mfma_f32_16x16x32_bf16 v[20:23], v[174:177], v[206:209], v[20:23]
	v_mfma_f32_16x16x32_bf16 v[16:19], v[182:185], v[206:209], v[16:19]
	v_mfma_f32_16x16x32_bf16 v[4:7], v[174:177], v[214:217], v[4:7]
	v_mfma_f32_16x16x32_bf16 v[0:3], v[182:185], v[214:217], v[0:3]
	s_setprio 0
	s_barrier
	s_add_i32 s60, s60, 2
	s_add_u32 s22, s22, 0x100
	s_addc_u32 s23, s23, 0
	s_add_u32 s58, s58, 0x100
	s_addc_u32 s59, s59, 0
	s_cmp_gt_u32 s60, 13
	s_cbranch_scc0 .LBB0_1558
	s_branch .Lpeel_exit7

; #define PG8_STAGE(bufoff, gbase, voff) do { _Pragma("unroll") for (int _i = 0; _i < 2; ++_i) \
;         __builtin_amdgcn_global_load_lds((const unsigned*)((const char*)(gbase) + (voff)[_i]), (LAS unsigned*)(lds + (bufoff) + ldsw + _i * 8192), 16, 0, 0); } while (0)
; #define PG8_LDA(dst, b, h) do { _Pragma("unroll") for (int m = 0; m < 4; ++m) _Pragma("unroll") for (int k = 0; k < 2; ++k) dst[m][k] = *(const LAS bf16x8*)(lds + PG8_SA(b, h) + aoff + m * 2048 + k * 1024); } while (0)
; #define PG8_LDB(dst, b, h) do { _Pragma("unroll") for (int n = 0; n < 2; ++n) _Pragma("unroll") for (int k = 0; k < 2; ++k) dst[n][k] = *(const LAS bf16x8*)(lds + PG8_SB(b, h) + boff + n * 2048 + k * 1024); } while (0)
; #define PG8_MMA(ai, bj, At, Bt) do { __builtin_amdgcn_s_setprio(1); _Pragma("unroll") for (int m = 0; m < 4; ++m) _Pragma("unroll") for (int n = 0; n < 2; ++n) _Pragma("unroll") for (int k = 0; k < 2; ++k) \
;         acc[ai][bj][m][n] = __builtin_amdgcn_mfma_f32_16x16x32_bf16(Bt[n][k], At[m][k], acc[ai][bj][m][n], 0, 0, 0); __builtin_amdgcn_s_setprio(0); } while (0)
; #define PG8_WAIT_V(n) asm volatile("s_waitcnt vmcnt(" #n ")" ::: "memory")
; template <class Epi>
; __device__ __forceinline__ void gemm_phase(LAS unsigned char* lds, const Gemm g, const StaticOrder& S, const Epi& E) {
;     ...
;         const bool has_next = S.next(ui + 1, nxt);
;         const char* nA = has_next ? (const char*)g.A + (size_t)nxt.pm * tsA : cA; const char* nB = has_next ? (const char*)g.Bt + (size_t)nxt.pn * tsB : cB;
;         for (int t = 0; t < nt; t += 2) {
;             const bool last = (t == nt - 2);
;             const char* a1 = cA + (size_t)(t + 1) * kstep;
;             const char* a2 = last ? nA : cA + (size_t)(t + 2) * kstep; const char* b2 = last ? nB : cB + (size_t)(t + 2) * kstep;
;             const char* a3 = a2 + kstep; const char* b3 = b2 + kstep;
;             PG8_LDB(B0, 0, 0); PG8_LDB(B1, 0, 1); PG8_SCHED; PG8_LDA(At, 0, 0); PG8_STAGE(PG8_SA(1, 1), a1 + hsA, voffA);
;             PG8_WAIT_V(8); PG8_WAIT_L(0); PG8_BAR; PG8_MMA(0, 0, At, B0); PG8_MMA(0, 1, At, B1); PG8_BAR; PG8_SCHED;
;             PG8_LDA(At, 0, 1); PG8_STAGE(PG8_SB(0, 0), b2, voffB); PG8_STAGE(PG8_SB(0, 1), b2 + hsB, voffB); PG8_STAGE(PG8_SA(0, 0), a2, voffA);
;             PG8_WAIT_V(8); PG8_WAIT_L(0); PG8_BAR; PG8_MMA(1, 0, At, B0); PG8_MMA(1, 1, At, B1); PG8_BAR; PG8_SCHED;
.LBB0_1637:
	s_add_u32 s52, s24, 0x100
	s_addc_u32 s53, s25, 0
	s_mov_b32 s54, -2
	ds_read_b128 v[144:147], v153
	ds_read_b128 v[156:159], v153 offset:1024
	ds_read_b128 v[160:163], v153 offset:2048
	ds_read_b128 v[164:167], v153 offset:3072
	ds_read_b128 v[168:171], v154
	ds_read_b128 v[172:175], v154 offset:1024
	ds_read_b128 v[176:179], v154 offset:2048
	ds_read_b128 v[180:183], v154 offset:3072
	s_add_u32 s24, s22, 0x100
	s_addc_u32 s25, s23, 0
	s_cmp_eq_u32 s54, 40
	s_cselect_b32 s29, s5, s25
	s_cselect_b32 s28, s4, s24
	s_cselect_b32 s27, s21, s53
	s_cselect_b32 s26, s20, s52
	v_lshl_add_u64 v[148:149], s[22:23], 0, v[136:137]
	s_add_i32 m0, s34, 0xc000
	ds_read_b128 v[184:187], v155
	ds_read_b128 v[188:191], v155 offset:1024
	ds_read_b128 v[192:195], v155 offset:2048
	ds_read_b128 v[196:199], v155 offset:3072
	ds_read_b128 v[200:203], v155 offset:4096
	ds_read_b128 v[204:207], v155 offset:5120
	ds_read_b128 v[208:211], v155 offset:6144
	ds_read_b128 v[212:215], v155 offset:7168
	global_load_lds_dwordx4 v[148:149], off
	v_lshl_add_u64 v[148:149], s[22:23], 0, v[138:139]
	s_add_i32 m0, s34, 0xe000
	s_nop 0
	global_load_lds_dwordx4 v[148:149], off
	s_waitcnt vmcnt(8)
	s_waitcnt lgkmcnt(0)
	s_barrier
	s_setprio 1
	s_waitcnt lgkmcnt(0)
	v_mfma_f32_16x16x32_bf16 v[124:127], v[144:147], v[184:187], 0
	v_mfma_f32_16x16x32_bf16 v[120:123], v[160:163], v[184:187], 0
	v_mfma_f32_16x16x32_bf16 v[108:111], v[144:147], v[192:195], 0
	v_mfma_f32_16x16x32_bf16 v[104:107], v[160:163], v[192:195], 0
	v_mfma_f32_16x16x32_bf16 v[92:95], v[144:147], v[200:203], 0
	v_mfma_f32_16x16x32_bf16 v[88:91], v[160:163], v[200:203], 0
	v_mfma_f32_16x16x32_bf16 v[76:79], v[144:147], v[208:211], 0
	v_mfma_f32_16x16x32_bf16 v[72:75], v[160:163], v[208:211], 0
	v_mfma_f32_16x16x32_bf16 v[124:127], v[156:159], v[188:191], v[124:127]
	v_mfma_f32_16x16x32_bf16 v[120:123], v[164:167], v[188:191], v[120:123]
	v_mfma_f32_16x16x32_bf16 v[108:111], v[156:159], v[196:199], v[108:111]
	v_mfma_f32_16x16x32_bf16 v[104:107], v[164:167], v[196:199], v[104:107]
	v_mfma_f32_16x16x32_bf16 v[92:95], v[156:159], v[204:207], v[92:95]
	v_mfma_f32_16x16x32_bf16 v[88:91], v[164:167], v[204:207], v[88:91]
	v_mfma_f32_16x16x32_bf16 v[76:79], v[156:159], v[212:215], v[76:79]
	v_mfma_f32_16x16x32_bf16 v[72:75], v[164:167], v[212:215], v[72:75]
	s_setprio 0
	s_setprio 1
	v_mfma_f32_16x16x32_bf16 v[116:119], v[168:171], v[184:187], 0
	v_mfma_f32_16x16x32_bf16 v[112:115], v[176:179], v[184:187], 0
	v_mfma_f32_16x16x32_bf16 v[100:103], v[168:171], v[192:195], 0
	v_mfma_f32_16x16x32_bf16 v[96:99], v[176:179], v[192:195], 0
	v_mfma_f32_16x16x32_bf16 v[84:87], v[168:171], v[200:203], 0
	v_mfma_f32_16x16x32_bf16 v[80:83], v[176:179], v[200:203], 0
	v_mfma_f32_16x16x32_bf16 v[68:71], v[168:171], v[208:211], 0
	v_mfma_f32_16x16x32_bf16 v[64:67], v[176:179], v[208:211], 0
	v_mfma_f32_16x16x32_bf16 v[116:119], v[172:175], v[188:191], v[116:119]
	v_mfma_f32_16x16x32_bf16 v[112:115], v[180:183], v[188:191], v[112:115]
	v_mfma_f32_16x16x32_bf16 v[100:103], v[172:175], v[196:199], v[100:103]
	v_mfma_f32_16x16x32_bf16 v[96:99], v[180:183], v[196:199], v[96:99]
	v_mfma_f32_16x16x32_bf16 v[84:87], v[172:175], v[204:207], v[84:87]
	v_mfma_f32_16x16x32_bf16 v[80:83], v[180:183], v[204:207], v[80:83]
	v_mfma_f32_16x16x32_bf16 v[68:71], v[172:175], v[212:215], v[68:71]
	v_mfma_f32_16x16x32_bf16 v[64:67], v[180:183], v[212:215], v[64:67]
	s_setprio 0
	s_barrier
	s_add_i32 s22, s42, s33
	v_lshl_add_u64 v[148:149], s[26:27], 0, v[130:131]
	s_mov_b32 m0, s22
	ds_read_b128 v[184:187], v155 offset:16384
	ds_read_b128 v[188:191], v155 offset:17408
	ds_read_b128 v[192:195], v155 offset:18432
	ds_read_b128 v[196:199], v155 offset:19456
	ds_read_b128 v[200:203], v155 offset:20480
	ds_read_b128 v[204:207], v155 offset:21504
	ds_read_b128 v[208:211], v155 offset:22528
	ds_read_b128 v[212:215], v155 offset:23552
	global_load_lds_dwordx4 v[148:149], off
	s_add_i32 m0, s22, 0x2000
	s_add_u32 s22, s26, 0xb0000
	v_lshl_add_u64 v[216:217], s[26:27], 0, v[134:135]
	s_addc_u32 s23, s27, 0
	s_add_i32 s55, s43, s33
	global_load_lds_dwordx4 v[216:217], off
	v_lshl_add_u64 v[218:219], s[22:23], 0, v[130:131]
	s_mov_b32 m0, s55
	v_lshl_add_u64 v[220:221], s[28:29], 0, v[132:133]
	global_load_lds_dwordx4 v[218:219], off
	v_lshl_add_u64 v[218:219], s[22:23], 0, v[134:135]
	s_add_i32 m0, s55, 0x2000
	s_nop 0
	global_load_lds_dwordx4 v[218:219], off
	v_lshl_add_u64 v[218:219], s[28:29], 0, v[128:129]
	s_mov_b32 m0, s34
	s_nop 0
	global_load_lds_dwordx4 v[218:219], off
	s_mov_b32 m0, s35
	s_nop 0
	global_load_lds_dwordx4 v[220:221], off
	s_waitcnt vmcnt(8)
	s_waitcnt lgkmcnt(0)
	s_barrier
; #define PG8_STAGE(bufoff, gbase, voff) do { _Pragma("unroll") for (int _i = 0; _i < 2; ++_i) \
;         __builtin_amdgcn_global_load_lds((const unsigned*)((const char*)(gbase) + (voff)[_i]), (LAS unsigned*)(lds + (bufoff) + ldsw + _i * 8192), 16, 0, 0); } while (0)
; #define PG8_LDA(dst, b, h) do { _Pragma("unroll") for (int m = 0; m < 4; ++m) _Pragma("unroll") for (int k = 0; k < 2; ++k) dst[m][k] = *(const LAS bf16x8*)(lds + PG8_SA(b, h) + aoff + m * 2048 + k * 1024); } while (0)
; #define PG8_LDB(dst, b, h) do { _Pragma("unroll") for (int n = 0; n < 2; ++n) _Pragma("unroll") for (int k = 0; k < 2; ++k) dst[n][k] = *(const LAS bf16x8*)(lds + PG8_SB(b, h) + boff + n * 2048 + k * 1024); } while (0)
; #define PG8_MMA(ai, bj, At, Bt) do { __builtin_amdgcn_s_setprio(1); _Pragma("unroll") for (int m = 0; m < 4; ++m) _Pragma("unroll") for (int n = 0; n < 2; ++n) _Pragma("unroll") for (int k = 0; k < 2; ++k) \
;         acc[ai][bj][m][n] = __builtin_amdgcn_mfma_f32_16x16x32_bf16(Bt[n][k], At[m][k], acc[ai][bj][m][n], 0, 0, 0); __builtin_amdgcn_s_setprio(0); } while (0)
; #define PG8_WAIT_V(n) asm volatile("s_waitcnt vmcnt(" #n ")" ::: "memory")
; #define PG8_WAIT_L(n) asm volatile("s_waitcnt lgkmcnt(" #n ")" ::: "memory")
; #define PG8_BAR __builtin_amdgcn_s_barrier()
; #define PG8_SCHED __builtin_amdgcn_sched_barrier(0)
; template <class Epi>
; __device__ __forceinline__ void gemm_phase(LAS unsigned char* lds, const Gemm g, const StaticOrder& S, const Epi& E) {
;     ...
;             PG8_WAIT_V(8); PG8_WAIT_L(0); PG8_BAR; PG8_MMA(1, 0, At, B0); PG8_MMA(1, 1, At, B1); PG8_BAR; PG8_SCHED;
;             PG8_LDB(B0, 1, 0); PG8_LDB(B1, 1, 1); PG8_SCHED; PG8_LDA(At, 1, 0); PG8_STAGE(PG8_SA(0, 1), a2 + hsA, voffA);
;             PG8_WAIT_V(8); PG8_WAIT_L(0); PG8_BAR; PG8_MMA(0, 0, At, B0); PG8_MMA(0, 1, At, B1); PG8_BAR; PG8_SCHED;
	s_setprio 1
	s_waitcnt lgkmcnt(0)
	v_mfma_f32_16x16x32_bf16 v[60:63], v[144:147], v[184:187], 0
	v_mfma_f32_16x16x32_bf16 v[56:59], v[160:163], v[184:187], 0
	v_mfma_f32_16x16x32_bf16 v[44:47], v[144:147], v[192:195], 0
	v_mfma_f32_16x16x32_bf16 v[40:43], v[160:163], v[192:195], 0
	v_mfma_f32_16x16x32_bf16 v[28:31], v[144:147], v[200:203], 0
	v_mfma_f32_16x16x32_bf16 v[24:27], v[160:163], v[200:203], 0
	v_mfma_f32_16x16x32_bf16 v[12:15], v[144:147], v[208:211], 0
	v_mfma_f32_16x16x32_bf16 v[8:11], v[160:163], v[208:211], 0
	v_mfma_f32_16x16x32_bf16 v[60:63], v[156:159], v[188:191], v[60:63]
	v_mfma_f32_16x16x32_bf16 v[56:59], v[164:167], v[188:191], v[56:59]
	v_mfma_f32_16x16x32_bf16 v[44:47], v[156:159], v[196:199], v[44:47]
	v_mfma_f32_16x16x32_bf16 v[40:43], v[164:167], v[196:199], v[40:43]
	v_mfma_f32_16x16x32_bf16 v[28:31], v[156:159], v[204:207], v[28:31]
	v_mfma_f32_16x16x32_bf16 v[24:27], v[164:167], v[204:207], v[24:27]
	v_mfma_f32_16x16x32_bf16 v[12:15], v[156:159], v[212:215], v[12:15]
	v_mfma_f32_16x16x32_bf16 v[8:11], v[164:167], v[212:215], v[8:11]
	s_setprio 0
	s_setprio 1
	v_mfma_f32_16x16x32_bf16 v[52:55], v[168:171], v[184:187], 0
	v_mfma_f32_16x16x32_bf16 v[48:51], v[176:179], v[184:187], 0
	v_mfma_f32_16x16x32_bf16 v[36:39], v[168:171], v[192:195], 0
	v_mfma_f32_16x16x32_bf16 v[32:35], v[176:179], v[192:195], 0
	v_mfma_f32_16x16x32_bf16 v[20:23], v[168:171], v[200:203], 0
	v_mfma_f32_16x16x32_bf16 v[16:19], v[176:179], v[200:203], 0
	v_mfma_f32_16x16x32_bf16 v[4:7], v[168:171], v[208:211], 0
	v_mfma_f32_16x16x32_bf16 v[0:3], v[176:179], v[208:211], 0
	v_mfma_f32_16x16x32_bf16 v[52:55], v[172:175], v[188:191], v[52:55]
	v_mfma_f32_16x16x32_bf16 v[48:51], v[180:183], v[188:191], v[48:51]
	v_mfma_f32_16x16x32_bf16 v[36:39], v[172:175], v[196:199], v[36:39]
	v_mfma_f32_16x16x32_bf16 v[32:35], v[180:183], v[196:199], v[32:35]
	v_mfma_f32_16x16x32_bf16 v[20:23], v[172:175], v[204:207], v[20:23]
	v_mfma_f32_16x16x32_bf16 v[16:19], v[180:183], v[204:207], v[16:19]
	v_mfma_f32_16x16x32_bf16 v[4:7], v[172:175], v[212:215], v[4:7]
	v_mfma_f32_16x16x32_bf16 v[0:3], v[180:183], v[212:215], v[0:3]
	s_setprio 0
	s_barrier
	s_add_i32 s55, 0, 0x18000
	s_add_i32 s56, 0, 0x1c000
	v_add_u32_e32 v164, s55, v151
	v_add_u32_e32 v180, s56, v151
	ds_read_b128 v[144:147], v164
	ds_read_b128 v[156:159], v164 offset:1024
	ds_read_b128 v[160:163], v164 offset:2048
	ds_read_b128 v[164:167], v164 offset:3072
	ds_read_b128 v[168:171], v180
	ds_read_b128 v[172:175], v180 offset:1024
	ds_read_b128 v[176:179], v180 offset:2048
	ds_read_b128 v[180:183], v180 offset:3072
	s_add_u32 s22, s28, 0xb0000
	s_addc_u32 s23, s29, 0
	s_mov_b32 m0, s36
	v_lshl_add_u64 v[222:223], s[22:23], 0, v[128:129]
	ds_read_b128 v[184:187], v155 offset:32768
	ds_read_b128 v[188:191], v155 offset:33792
	ds_read_b128 v[192:195], v155 offset:34816
	ds_read_b128 v[196:199], v155 offset:35840
	ds_read_b128 v[200:203], v155 offset:36864
	ds_read_b128 v[204:207], v155 offset:37888
	ds_read_b128 v[208:211], v155 offset:38912
	ds_read_b128 v[212:215], v155 offset:39936
	global_load_lds_dwordx4 v[222:223], off
	v_lshl_add_u64 v[222:223], s[22:23], 0, v[132:133]
	s_mov_b32 m0, s37
	s_nop 0
	global_load_lds_dwordx4 v[222:223], off
	s_waitcnt vmcnt(8)
	s_waitcnt lgkmcnt(0)
	s_barrier
	s_setprio 1
	s_waitcnt lgkmcnt(0)
	v_mfma_f32_16x16x32_bf16 v[124:127], v[144:147], v[184:187], v[124:127]
	v_mfma_f32_16x16x32_bf16 v[120:123], v[160:163], v[184:187], v[120:123]
	v_mfma_f32_16x16x32_bf16 v[108:111], v[144:147], v[192:195], v[108:111]
	v_mfma_f32_16x16x32_bf16 v[104:107], v[160:163], v[192:195], v[104:107]
	v_mfma_f32_16x16x32_bf16 v[92:95], v[144:147], v[200:203], v[92:95]
	v_mfma_f32_16x16x32_bf16 v[88:91], v[160:163], v[200:203], v[88:91]
	v_mfma_f32_16x16x32_bf16 v[76:79], v[144:147], v[208:211], v[76:79]
	v_mfma_f32_16x16x32_bf16 v[72:75], v[160:163], v[208:211], v[72:75]
	v_mfma_f32_16x16x32_bf16 v[124:127], v[156:159], v[188:191], v[124:127]
	v_mfma_f32_16x16x32_bf16 v[120:123], v[164:167], v[188:191], v[120:123]
	v_mfma_f32_16x16x32_bf16 v[108:111], v[156:159], v[196:199], v[108:111]
	v_mfma_f32_16x16x32_bf16 v[104:107], v[164:167], v[196:199], v[104:107]
	v_mfma_f32_16x16x32_bf16 v[92:95], v[156:159], v[204:207], v[92:95]
	v_mfma_f32_16x16x32_bf16 v[88:91], v[164:167], v[204:207], v[88:91]
	v_mfma_f32_16x16x32_bf16 v[76:79], v[156:159], v[212:215], v[76:79]
	v_mfma_f32_16x16x32_bf16 v[72:75], v[164:167], v[212:215], v[72:75]
	s_setprio 0
	s_setprio 1
	v_mfma_f32_16x16x32_bf16 v[116:119], v[168:171], v[184:187], v[116:119]
	v_mfma_f32_16x16x32_bf16 v[112:115], v[176:179], v[184:187], v[112:115]
	v_mfma_f32_16x16x32_bf16 v[100:103], v[168:171], v[192:195], v[100:103]
	v_mfma_f32_16x16x32_bf16 v[96:99], v[176:179], v[192:195], v[96:99]
	v_mfma_f32_16x16x32_bf16 v[84:87], v[168:171], v[200:203], v[84:87]
	v_mfma_f32_16x16x32_bf16 v[80:83], v[176:179], v[200:203], v[80:83]
	v_mfma_f32_16x16x32_bf16 v[68:71], v[168:171], v[208:211], v[68:71]
	v_mfma_f32_16x16x32_bf16 v[64:67], v[176:179], v[208:211], v[64:67]
	v_mfma_f32_16x16x32_bf16 v[116:119], v[172:175], v[188:191], v[116:119]
	v_mfma_f32_16x16x32_bf16 v[112:115], v[180:183], v[188:191], v[112:115]
	v_mfma_f32_16x16x32_bf16 v[100:103], v[172:175], v[196:199], v[100:103]
	v_mfma_f32_16x16x32_bf16 v[96:99], v[180:183], v[196:199], v[96:99]
	v_mfma_f32_16x16x32_bf16 v[84:87], v[172:175], v[204:207], v[84:87]
	v_mfma_f32_16x16x32_bf16 v[80:83], v[180:183], v[204:207], v[80:83]
	v_mfma_f32_16x16x32_bf16 v[68:71], v[172:175], v[212:215], v[68:71]
	v_mfma_f32_16x16x32_bf16 v[64:67], v[180:183], v[212:215], v[64:67]
	s_setprio 0
	s_barrier
; #define PG8_STAGE(bufoff, gbase, voff) do { _Pragma("unroll") for (int _i = 0; _i < 2; ++_i) \
;         __builtin_amdgcn_global_load_lds((const unsigned*)((const char*)(gbase) + (voff)[_i]), (LAS unsigned*)(lds + (bufoff) + ldsw + _i * 8192), 16, 0, 0); } while (0)
; #define PG8_LDA(dst, b, h) do { _Pragma("unroll") for (int m = 0; m < 4; ++m) _Pragma("unroll") for (int k = 0; k < 2; ++k) dst[m][k] = *(const LAS bf16x8*)(lds + PG8_SA(b, h) + aoff + m * 2048 + k * 1024); } while (0)
; #define PG8_MMA(ai, bj, At, Bt) do { __builtin_amdgcn_s_setprio(1); _Pragma("unroll") for (int m = 0; m < 4; ++m) _Pragma("unroll") for (int n = 0; n < 2; ++n) _Pragma("unroll") for (int k = 0; k < 2; ++k) \
;         acc[ai][bj][m][n] = __builtin_amdgcn_mfma_f32_16x16x32_bf16(Bt[n][k], At[m][k], acc[ai][bj][m][n], 0, 0, 0); __builtin_amdgcn_s_setprio(0); } while (0)
; #define PG8_WAIT_V(n) asm volatile("s_waitcnt vmcnt(" #n ")" ::: "memory")
; #define PG8_WAIT_L(n) asm volatile("s_waitcnt lgkmcnt(" #n ")" ::: "memory")
; #define PG8_BAR __builtin_amdgcn_s_barrier()
; #define PG8_SCHED __builtin_amdgcn_sched_barrier(0)
; template <class Epi>
; __device__ __forceinline__ void gemm_phase(LAS unsigned char* lds, const Gemm g, const StaticOrder& S, const Epi& E) {
;     ...
;             PG8_LDA(At, 1, 1); PG8_STAGE(PG8_SB(1, 0), b3, voffB); PG8_STAGE(PG8_SB(1, 1), b3 + hsB, voffB); PG8_STAGE(PG8_SA(1, 0), a3, voffA);
;             PG8_WAIT_V(8); PG8_WAIT_L(0); PG8_BAR; PG8_MMA(1, 0, At, B0); PG8_MMA(1, 1, At, B1); PG8_BAR; PG8_SCHED;
;         }
	s_add_i32 s22, s55, s33
	v_lshl_add_u64 v[148:149], v[148:149], 0, s[8:9]
	s_mov_b32 m0, s22
	ds_read_b128 v[184:187], v155 offset:49152
	ds_read_b128 v[188:191], v155 offset:50176
	ds_read_b128 v[192:195], v155 offset:51200
	ds_read_b128 v[196:199], v155 offset:52224
	ds_read_b128 v[200:203], v155 offset:53248
	ds_read_b128 v[204:207], v155 offset:54272
	ds_read_b128 v[208:211], v155 offset:55296
	ds_read_b128 v[212:215], v155 offset:56320
	global_load_lds_dwordx4 v[148:149], off
	s_add_i32 m0, s22, 0x2000
	s_add_u32 s22, s26, 0xb0080
	v_lshl_add_u64 v[148:149], v[216:217], 0, s[8:9]
	s_addc_u32 s23, s27, 0
	s_add_i32 s26, s56, s33
	global_load_lds_dwordx4 v[148:149], off
	v_lshl_add_u64 v[148:149], s[22:23], 0, v[130:131]
	s_mov_b32 m0, s26
	s_nop 0
	global_load_lds_dwordx4 v[148:149], off
	v_lshl_add_u64 v[148:149], s[22:23], 0, v[134:135]
	s_add_i32 m0, s26, 0x2000
	s_nop 0
	global_load_lds_dwordx4 v[148:149], off
	v_lshl_add_u64 v[148:149], v[218:219], 0, s[8:9]
	s_mov_b32 m0, s39
	s_nop 0
	global_load_lds_dwordx4 v[148:149], off
	v_lshl_add_u64 v[148:149], v[220:221], 0, s[8:9]
	s_mov_b32 m0, s40
	s_nop 0
	global_load_lds_dwordx4 v[148:149], off
	s_waitcnt vmcnt(8)
	s_waitcnt lgkmcnt(0)
	s_barrier
	s_setprio 1
	s_waitcnt lgkmcnt(0)
	v_mfma_f32_16x16x32_bf16 v[60:63], v[144:147], v[184:187], v[60:63]
	v_mfma_f32_16x16x32_bf16 v[56:59], v[160:163], v[184:187], v[56:59]
	v_mfma_f32_16x16x32_bf16 v[44:47], v[144:147], v[192:195], v[44:47]
	v_mfma_f32_16x16x32_bf16 v[40:43], v[160:163], v[192:195], v[40:43]
	v_mfma_f32_16x16x32_bf16 v[28:31], v[144:147], v[200:203], v[28:31]
	v_mfma_f32_16x16x32_bf16 v[24:27], v[160:163], v[200:203], v[24:27]
	v_mfma_f32_16x16x32_bf16 v[12:15], v[144:147], v[208:211], v[12:15]
	v_mfma_f32_16x16x32_bf16 v[8:11], v[160:163], v[208:211], v[8:11]
	v_mfma_f32_16x16x32_bf16 v[60:63], v[156:159], v[188:191], v[60:63]
	v_mfma_f32_16x16x32_bf16 v[56:59], v[164:167], v[188:191], v[56:59]
	v_mfma_f32_16x16x32_bf16 v[44:47], v[156:159], v[196:199], v[44:47]
	v_mfma_f32_16x16x32_bf16 v[40:43], v[164:167], v[196:199], v[40:43]
	v_mfma_f32_16x16x32_bf16 v[28:31], v[156:159], v[204:207], v[28:31]
	v_mfma_f32_16x16x32_bf16 v[24:27], v[164:167], v[204:207], v[24:27]
	v_mfma_f32_16x16x32_bf16 v[12:15], v[156:159], v[212:215], v[12:15]
	v_mfma_f32_16x16x32_bf16 v[8:11], v[164:167], v[212:215], v[8:11]
	s_setprio 0
	s_setprio 1
	v_mfma_f32_16x16x32_bf16 v[52:55], v[168:171], v[184:187], v[52:55]
	v_mfma_f32_16x16x32_bf16 v[48:51], v[176:179], v[184:187], v[48:51]
	v_mfma_f32_16x16x32_bf16 v[36:39], v[168:171], v[192:195], v[36:39]
	v_mfma_f32_16x16x32_bf16 v[32:35], v[176:179], v[192:195], v[32:35]
	v_mfma_f32_16x16x32_bf16 v[20:23], v[168:171], v[200:203], v[20:23]
	v_mfma_f32_16x16x32_bf16 v[16:19], v[176:179], v[200:203], v[16:19]
	v_mfma_f32_16x16x32_bf16 v[4:7], v[168:171], v[208:211], v[4:7]
	v_mfma_f32_16x16x32_bf16 v[0:3], v[176:179], v[208:211], v[0:3]
	v_mfma_f32_16x16x32_bf16 v[52:55], v[172:175], v[188:191], v[52:55]
	v_mfma_f32_16x16x32_bf16 v[48:51], v[180:183], v[188:191], v[48:51]
	v_mfma_f32_16x16x32_bf16 v[36:39], v[172:175], v[196:199], v[36:39]
	v_mfma_f32_16x16x32_bf16 v[32:35], v[180:183], v[196:199], v[32:35]
	v_mfma_f32_16x16x32_bf16 v[20:23], v[172:175], v[204:207], v[20:23]
	v_mfma_f32_16x16x32_bf16 v[16:19], v[180:183], v[204:207], v[16:19]
	v_mfma_f32_16x16x32_bf16 v[4:7], v[172:175], v[212:215], v[4:7]
	v_mfma_f32_16x16x32_bf16 v[0:3], v[180:183], v[212:215], v[0:3]
	s_setprio 0
	s_barrier
	s_add_i32 s54, s54, 2
	s_add_u32 s52, s52, 0x100
	s_addc_u32 s53, s53, 0
	s_cmp_gt_u32 s54, 41
	s_mov_b64 s[22:23], s[24:25]
	s_cbranch_scc0 .LBB0_1638
	s_branch .Lpeel_exit8
